# GEMM K-loops: first four MFMAs of each 32-MFMA block issued before the block's opening barrier
# baseline (speedup 1.0000x reference)
.LBB0_246:
	s_add_u32 s3, s34, 0xfff80080
	s_addc_u32 s6, s35, -1
	s_add_i32 s7, 0, 0x10000
	s_cmp_eq_u32 s2, 28
	s_cselect_b32 s43, s15, s6
	s_cselect_b32 s42, s47, s3
	s_cselect_b32 s39, s13, s50
	s_cselect_b32 s38, s48, s49
	s_add_i32 s3, 0, 0x14000
	v_add_u32_e32 v156, s7, v145
	v_add_u32_e32 v172, s3, v145
	ds_read_b128 v[140:143], v156
	ds_read_b128 v[148:151], v156 offset:1024
	ds_read_b128 v[152:155], v156 offset:2048
	ds_read_b128 v[156:159], v156 offset:3072
	ds_read_b128 v[160:163], v172
	ds_read_b128 v[164:167], v172 offset:1024
	ds_read_b128 v[168:171], v172 offset:2048
	ds_read_b128 v[172:175], v172 offset:3072
	v_lshl_add_u64 v[176:177], s[34:35], 0, v[136:137]
	s_add_i32 m0, s18, 0xc000
	ds_read_b128 v[182:185], v147
	ds_read_b128 v[186:189], v147 offset:1024
	ds_read_b128 v[190:193], v147 offset:2048
	ds_read_b128 v[214:217], v147 offset:3072
	ds_read_b128 v[218:221], v147 offset:4096
	ds_read_b128 v[222:225], v147 offset:5120
	ds_read_b128 v[226:229], v147 offset:6144
	ds_read_b128 v[230:233], v147 offset:7168
	global_load_lds_dwordx4 v[176:177], off
	v_lshl_add_u64 v[176:177], s[34:35], 0, v[138:139]
	s_add_i32 m0, s18, 0xe000
	s_nop 0
	global_load_lds_dwordx4 v[176:177], off
	s_waitcnt vmcnt(8)
	s_waitcnt lgkmcnt(0)
	v_mfma_f32_16x16x32_bf16 v[126:129], v[140:143], v[182:185], v[126:129]
	v_mfma_f32_16x16x32_bf16 v[122:125], v[152:155], v[182:185], v[122:125]
	v_mfma_f32_16x16x32_bf16 v[118:121], v[140:143], v[190:193], v[118:121]
	v_mfma_f32_16x16x32_bf16 v[110:113], v[152:155], v[190:193], v[110:113]
	s_barrier
	s_setprio 1
	s_waitcnt lgkmcnt(0)
	v_mfma_f32_16x16x32_bf16 v[102:105], v[140:143], v[218:221], v[102:105]
	v_mfma_f32_16x16x32_bf16 v[92:95], v[152:155], v[218:221], v[92:95]
	v_mfma_f32_16x16x32_bf16 v[84:87], v[140:143], v[226:229], v[84:87]
	v_mfma_f32_16x16x32_bf16 v[76:79], v[152:155], v[226:229], v[76:79]
	v_mfma_f32_16x16x32_bf16 v[126:129], v[148:151], v[186:189], v[126:129]
	v_mfma_f32_16x16x32_bf16 v[122:125], v[156:159], v[186:189], v[122:125]
	v_mfma_f32_16x16x32_bf16 v[118:121], v[148:151], v[214:217], v[118:121]
	v_mfma_f32_16x16x32_bf16 v[110:113], v[156:159], v[214:217], v[110:113]
	v_mfma_f32_16x16x32_bf16 v[102:105], v[148:151], v[222:225], v[102:105]
	v_mfma_f32_16x16x32_bf16 v[92:95], v[156:159], v[222:225], v[92:95]
	v_mfma_f32_16x16x32_bf16 v[84:87], v[148:151], v[230:233], v[84:87]
	v_mfma_f32_16x16x32_bf16 v[76:79], v[156:159], v[230:233], v[76:79]
	s_setprio 0
	s_setprio 1
	v_mfma_f32_16x16x32_bf16 v[114:117], v[160:163], v[182:185], v[114:117]
	v_mfma_f32_16x16x32_bf16 v[106:109], v[168:171], v[182:185], v[106:109]
	v_mfma_f32_16x16x32_bf16 v[98:101], v[160:163], v[190:193], v[98:101]
	v_mfma_f32_16x16x32_bf16 v[88:91], v[168:171], v[190:193], v[88:91]
	v_mfma_f32_16x16x32_bf16 v[80:83], v[160:163], v[218:221], v[80:83]
	v_mfma_f32_16x16x32_bf16 v[72:75], v[168:171], v[218:221], v[72:75]
	v_mfma_f32_16x16x32_bf16 v[68:71], v[160:163], v[226:229], v[68:71]
	v_mfma_f32_16x16x32_bf16 v[64:67], v[168:171], v[226:229], v[64:67]
	v_mfma_f32_16x16x32_bf16 v[114:117], v[164:167], v[186:189], v[114:117]
	v_mfma_f32_16x16x32_bf16 v[106:109], v[172:175], v[186:189], v[106:109]
	v_mfma_f32_16x16x32_bf16 v[98:101], v[164:167], v[214:217], v[98:101]
	v_mfma_f32_16x16x32_bf16 v[88:91], v[172:175], v[214:217], v[88:91]
	v_mfma_f32_16x16x32_bf16 v[80:83], v[164:167], v[222:225], v[80:83]
	v_mfma_f32_16x16x32_bf16 v[72:75], v[172:175], v[222:225], v[72:75]
	v_mfma_f32_16x16x32_bf16 v[68:71], v[164:167], v[230:233], v[68:71]
	v_mfma_f32_16x16x32_bf16 v[64:67], v[172:175], v[230:233], v[64:67]
	s_setprio 0
	s_barrier
	s_add_i32 s6, s7, s17
	v_lshl_add_u64 v[176:177], s[38:39], 0, v[96:97]
	s_mov_b32 m0, s6
	ds_read_b128 v[182:185], v147 offset:16384
	ds_read_b128 v[186:189], v147 offset:17408
	ds_read_b128 v[190:193], v147 offset:18432
	ds_read_b128 v[214:217], v147 offset:19456
	ds_read_b128 v[218:221], v147 offset:20480
	ds_read_b128 v[222:225], v147 offset:21504
	ds_read_b128 v[226:229], v147 offset:22528
	ds_read_b128 v[230:233], v147 offset:23552
	global_load_lds_dwordx4 v[176:177], off
	s_add_i32 m0, s6, 0x2000
	s_add_u32 s6, s38, 0x80000
	v_lshl_add_u64 v[178:179], s[38:39], 0, v[130:131]
	s_addc_u32 s7, s39, 0
	s_add_i32 s3, s3, s17
	global_load_lds_dwordx4 v[178:179], off
	v_lshl_add_u64 v[180:181], s[6:7], 0, v[96:97]
	s_mov_b32 m0, s3
	v_lshl_add_u64 v[194:195], s[42:43], 0, v[132:133]
	global_load_lds_dwordx4 v[180:181], off
	v_lshl_add_u64 v[180:181], s[6:7], 0, v[130:131]
	s_add_i32 m0, s3, 0x2000
	s_nop 0
	global_load_lds_dwordx4 v[180:181], off
	v_lshl_add_u64 v[180:181], s[42:43], 0, v[134:135]
	s_mov_b32 m0, s18
	s_nop 0
	global_load_lds_dwordx4 v[180:181], off
	s_mov_b32 m0, s19
	s_nop 0
	global_load_lds_dwordx4 v[194:195], off
	s_waitcnt vmcnt(8)
	s_waitcnt lgkmcnt(0)
	v_mfma_f32_16x16x32_bf16 v[60:63], v[140:143], v[182:185], v[60:63]
	v_mfma_f32_16x16x32_bf16 v[56:59], v[152:155], v[182:185], v[56:59]
	v_mfma_f32_16x16x32_bf16 v[52:55], v[140:143], v[190:193], v[52:55]
	v_mfma_f32_16x16x32_bf16 v[44:47], v[152:155], v[190:193], v[44:47]
	s_barrier
	s_setprio 1
	s_waitcnt lgkmcnt(0)
	v_mfma_f32_16x16x32_bf16 v[36:39], v[140:143], v[218:221], v[36:39]
	v_mfma_f32_16x16x32_bf16 v[28:31], v[152:155], v[218:221], v[28:31]
	v_mfma_f32_16x16x32_bf16 v[20:23], v[140:143], v[226:229], v[20:23]
	v_mfma_f32_16x16x32_bf16 v[12:15], v[152:155], v[226:229], v[12:15]
	v_mfma_f32_16x16x32_bf16 v[60:63], v[148:151], v[186:189], v[60:63]
	v_mfma_f32_16x16x32_bf16 v[56:59], v[156:159], v[186:189], v[56:59]
	v_mfma_f32_16x16x32_bf16 v[52:55], v[148:151], v[214:217], v[52:55]
	v_mfma_f32_16x16x32_bf16 v[44:47], v[156:159], v[214:217], v[44:47]
	v_mfma_f32_16x16x32_bf16 v[36:39], v[148:151], v[222:225], v[36:39]
	v_mfma_f32_16x16x32_bf16 v[28:31], v[156:159], v[222:225], v[28:31]
	v_mfma_f32_16x16x32_bf16 v[20:23], v[148:151], v[230:233], v[20:23]
	v_mfma_f32_16x16x32_bf16 v[12:15], v[156:159], v[230:233], v[12:15]
	s_setprio 0
	s_setprio 1
	v_mfma_f32_16x16x32_bf16 v[48:51], v[160:163], v[182:185], v[48:51]
	v_mfma_f32_16x16x32_bf16 v[40:43], v[168:171], v[182:185], v[40:43]
	v_mfma_f32_16x16x32_bf16 v[32:35], v[160:163], v[190:193], v[32:35]
	v_mfma_f32_16x16x32_bf16 v[24:27], v[168:171], v[190:193], v[24:27]
	v_mfma_f32_16x16x32_bf16 v[16:19], v[160:163], v[218:221], v[16:19]
	v_mfma_f32_16x16x32_bf16 v[8:11], v[168:171], v[218:221], v[8:11]
	v_mfma_f32_16x16x32_bf16 v[4:7], v[160:163], v[226:229], v[4:7]
	v_mfma_f32_16x16x32_bf16 v[0:3], v[168:171], v[226:229], v[0:3]
	v_mfma_f32_16x16x32_bf16 v[48:51], v[164:167], v[186:189], v[48:51]
	v_mfma_f32_16x16x32_bf16 v[40:43], v[172:175], v[186:189], v[40:43]
	v_mfma_f32_16x16x32_bf16 v[32:35], v[164:167], v[214:217], v[32:35]
	v_mfma_f32_16x16x32_bf16 v[24:27], v[172:175], v[214:217], v[24:27]
	v_mfma_f32_16x16x32_bf16 v[16:19], v[164:167], v[222:225], v[16:19]
	v_mfma_f32_16x16x32_bf16 v[8:11], v[172:175], v[222:225], v[8:11]
	v_mfma_f32_16x16x32_bf16 v[4:7], v[164:167], v[230:233], v[4:7]
	v_mfma_f32_16x16x32_bf16 v[0:3], v[172:175], v[230:233], v[0:3]
	s_setprio 0
	s_barrier
	s_add_i32 s3, 0, 0x18000
	s_add_i32 s51, 0, 0x1c000
	v_add_u32_e32 v156, s3, v145
	v_add_u32_e32 v172, s51, v145
	ds_read_b128 v[140:143], v156
	ds_read_b128 v[148:151], v156 offset:1024
	ds_read_b128 v[152:155], v156 offset:2048
	ds_read_b128 v[156:159], v156 offset:3072
	ds_read_b128 v[160:163], v172
	ds_read_b128 v[164:167], v172 offset:1024
	ds_read_b128 v[168:171], v172 offset:2048
	ds_read_b128 v[172:175], v172 offset:3072
	s_add_u32 s6, s42, 0x80000
	s_addc_u32 s7, s43, 0
	s_mov_b32 m0, s20
	v_lshl_add_u64 v[202:203], s[6:7], 0, v[134:135]
	ds_read_b128 v[182:185], v147 offset:32768
	ds_read_b128 v[186:189], v147 offset:33792
	ds_read_b128 v[190:193], v147 offset:34816
	ds_read_b128 v[214:217], v147 offset:35840
	ds_read_b128 v[218:221], v147 offset:36864
	ds_read_b128 v[222:225], v147 offset:37888
	ds_read_b128 v[226:229], v147 offset:38912
	ds_read_b128 v[230:233], v147 offset:39936
	global_load_lds_dwordx4 v[202:203], off
	v_lshl_add_u64 v[202:203], s[6:7], 0, v[132:133]
	s_mov_b32 m0, s36
	s_nop 0
	global_load_lds_dwordx4 v[202:203], off
	s_waitcnt vmcnt(8)
	s_waitcnt lgkmcnt(0)
	v_mfma_f32_16x16x32_bf16 v[126:129], v[140:143], v[182:185], v[126:129]
	v_mfma_f32_16x16x32_bf16 v[122:125], v[152:155], v[182:185], v[122:125]
	v_mfma_f32_16x16x32_bf16 v[118:121], v[140:143], v[190:193], v[118:121]
	v_mfma_f32_16x16x32_bf16 v[110:113], v[152:155], v[190:193], v[110:113]
	s_barrier
	s_setprio 1
	s_waitcnt lgkmcnt(0)
	v_mfma_f32_16x16x32_bf16 v[102:105], v[140:143], v[218:221], v[102:105]
	v_mfma_f32_16x16x32_bf16 v[92:95], v[152:155], v[218:221], v[92:95]
	v_mfma_f32_16x16x32_bf16 v[84:87], v[140:143], v[226:229], v[84:87]
	v_mfma_f32_16x16x32_bf16 v[76:79], v[152:155], v[226:229], v[76:79]
	v_mfma_f32_16x16x32_bf16 v[126:129], v[148:151], v[186:189], v[126:129]
	v_mfma_f32_16x16x32_bf16 v[122:125], v[156:159], v[186:189], v[122:125]
	v_mfma_f32_16x16x32_bf16 v[118:121], v[148:151], v[214:217], v[118:121]
	v_mfma_f32_16x16x32_bf16 v[110:113], v[156:159], v[214:217], v[110:113]
	v_mfma_f32_16x16x32_bf16 v[102:105], v[148:151], v[222:225], v[102:105]
	v_mfma_f32_16x16x32_bf16 v[92:95], v[156:159], v[222:225], v[92:95]
	v_mfma_f32_16x16x32_bf16 v[84:87], v[148:151], v[230:233], v[84:87]
	v_mfma_f32_16x16x32_bf16 v[76:79], v[156:159], v[230:233], v[76:79]
	s_setprio 0
	s_setprio 1
	v_mfma_f32_16x16x32_bf16 v[114:117], v[160:163], v[182:185], v[114:117]
	v_mfma_f32_16x16x32_bf16 v[106:109], v[168:171], v[182:185], v[106:109]
	v_mfma_f32_16x16x32_bf16 v[98:101], v[160:163], v[190:193], v[98:101]
	v_mfma_f32_16x16x32_bf16 v[88:91], v[168:171], v[190:193], v[88:91]
	v_mfma_f32_16x16x32_bf16 v[80:83], v[160:163], v[218:221], v[80:83]
	v_mfma_f32_16x16x32_bf16 v[72:75], v[168:171], v[218:221], v[72:75]
	v_mfma_f32_16x16x32_bf16 v[68:71], v[160:163], v[226:229], v[68:71]
	v_mfma_f32_16x16x32_bf16 v[64:67], v[168:171], v[226:229], v[64:67]
	v_mfma_f32_16x16x32_bf16 v[114:117], v[164:167], v[186:189], v[114:117]
	v_mfma_f32_16x16x32_bf16 v[106:109], v[172:175], v[186:189], v[106:109]
	v_mfma_f32_16x16x32_bf16 v[98:101], v[164:167], v[214:217], v[98:101]
	v_mfma_f32_16x16x32_bf16 v[88:91], v[172:175], v[214:217], v[88:91]
	v_mfma_f32_16x16x32_bf16 v[80:83], v[164:167], v[222:225], v[80:83]
	v_mfma_f32_16x16x32_bf16 v[72:75], v[172:175], v[222:225], v[72:75]
	v_mfma_f32_16x16x32_bf16 v[68:71], v[164:167], v[230:233], v[68:71]
	v_mfma_f32_16x16x32_bf16 v[64:67], v[172:175], v[230:233], v[64:67]
	s_setprio 0
	s_barrier
	s_add_i32 s3, s3, s17
	v_lshl_add_u64 v[176:177], v[176:177], 0, s[30:31]
	s_mov_b32 m0, s3
	ds_read_b128 v[182:185], v147 offset:49152
	ds_read_b128 v[186:189], v147 offset:50176
	ds_read_b128 v[190:193], v147 offset:51200
	ds_read_b128 v[214:217], v147 offset:52224
	ds_read_b128 v[218:221], v147 offset:53248
	ds_read_b128 v[222:225], v147 offset:54272
	ds_read_b128 v[226:229], v147 offset:55296
	ds_read_b128 v[230:233], v147 offset:56320
	global_load_lds_dwordx4 v[176:177], off
	s_add_i32 m0, s3, 0x2000
	s_add_u32 s6, s38, 0x80080
	v_lshl_add_u64 v[176:177], v[178:179], 0, s[30:31]
	s_addc_u32 s7, s39, 0
	s_add_i32 s3, s51, s17
	global_load_lds_dwordx4 v[176:177], off
	v_lshl_add_u64 v[176:177], s[6:7], 0, v[96:97]
	s_mov_b32 m0, s3
	s_nop 0
	global_load_lds_dwordx4 v[176:177], off
	v_lshl_add_u64 v[176:177], s[6:7], 0, v[130:131]
	s_add_i32 m0, s3, 0x2000
	s_nop 0
	global_load_lds_dwordx4 v[176:177], off
	v_lshl_add_u64 v[176:177], v[180:181], 0, s[30:31]
	s_mov_b32 m0, s37
	s_nop 0
	global_load_lds_dwordx4 v[176:177], off
	v_lshl_add_u64 v[176:177], v[194:195], 0, s[30:31]
	s_mov_b32 m0, s40
	s_nop 0
	global_load_lds_dwordx4 v[176:177], off
	s_waitcnt vmcnt(8)
	s_waitcnt lgkmcnt(0)
	v_mfma_f32_16x16x32_bf16 v[60:63], v[140:143], v[182:185], v[60:63]
	v_mfma_f32_16x16x32_bf16 v[56:59], v[152:155], v[182:185], v[56:59]
	v_mfma_f32_16x16x32_bf16 v[52:55], v[140:143], v[190:193], v[52:55]
	v_mfma_f32_16x16x32_bf16 v[44:47], v[152:155], v[190:193], v[44:47]
	s_barrier
	s_setprio 1
	s_waitcnt lgkmcnt(0)
	v_mfma_f32_16x16x32_bf16 v[36:39], v[140:143], v[218:221], v[36:39]
	v_mfma_f32_16x16x32_bf16 v[28:31], v[152:155], v[218:221], v[28:31]
	v_mfma_f32_16x16x32_bf16 v[20:23], v[140:143], v[226:229], v[20:23]
	v_mfma_f32_16x16x32_bf16 v[12:15], v[152:155], v[226:229], v[12:15]
	v_mfma_f32_16x16x32_bf16 v[60:63], v[148:151], v[186:189], v[60:63]
	v_mfma_f32_16x16x32_bf16 v[56:59], v[156:159], v[186:189], v[56:59]
	v_mfma_f32_16x16x32_bf16 v[52:55], v[148:151], v[214:217], v[52:55]
	v_mfma_f32_16x16x32_bf16 v[44:47], v[156:159], v[214:217], v[44:47]
	v_mfma_f32_16x16x32_bf16 v[36:39], v[148:151], v[222:225], v[36:39]
	v_mfma_f32_16x16x32_bf16 v[28:31], v[156:159], v[222:225], v[28:31]
	v_mfma_f32_16x16x32_bf16 v[20:23], v[148:151], v[230:233], v[20:23]
	v_mfma_f32_16x16x32_bf16 v[12:15], v[156:159], v[230:233], v[12:15]
	s_setprio 0
	s_setprio 1
	v_mfma_f32_16x16x32_bf16 v[48:51], v[160:163], v[182:185], v[48:51]
	v_mfma_f32_16x16x32_bf16 v[40:43], v[168:171], v[182:185], v[40:43]
	v_mfma_f32_16x16x32_bf16 v[32:35], v[160:163], v[190:193], v[32:35]
	v_mfma_f32_16x16x32_bf16 v[24:27], v[168:171], v[190:193], v[24:27]
	v_mfma_f32_16x16x32_bf16 v[16:19], v[160:163], v[218:221], v[16:19]
	v_mfma_f32_16x16x32_bf16 v[8:11], v[168:171], v[218:221], v[8:11]
	v_mfma_f32_16x16x32_bf16 v[4:7], v[160:163], v[226:229], v[4:7]
	v_mfma_f32_16x16x32_bf16 v[0:3], v[168:171], v[226:229], v[0:3]
	v_mfma_f32_16x16x32_bf16 v[48:51], v[164:167], v[186:189], v[48:51]
	v_mfma_f32_16x16x32_bf16 v[40:43], v[172:175], v[186:189], v[40:43]
	v_mfma_f32_16x16x32_bf16 v[32:35], v[164:167], v[214:217], v[32:35]
	v_mfma_f32_16x16x32_bf16 v[24:27], v[172:175], v[214:217], v[24:27]
	v_mfma_f32_16x16x32_bf16 v[16:19], v[164:167], v[222:225], v[16:19]
	v_mfma_f32_16x16x32_bf16 v[8:11], v[172:175], v[222:225], v[8:11]
	v_mfma_f32_16x16x32_bf16 v[4:7], v[164:167], v[230:233], v[4:7]
	v_mfma_f32_16x16x32_bf16 v[0:3], v[172:175], v[230:233], v[0:3]
	s_setprio 0
	s_barrier
	s_add_i32 s2, s2, 2
	s_add_u32 s34, s34, 0x100
	s_addc_u32 s35, s35, 0
	s_add_u32 s49, s49, 0x100
	s_addc_u32 s50, s50, 0
	s_cmp_gt_u32 s2, 29
	s_cbranch_scc0 .LBB0_246
	s_and_b64 vcc, exec, s[10:11]
	s_cbranch_vccz .LBB0_249
	s_barrier

.LBB0_421:
	s_add_u32 s3, s22, 0xfffe0080
	s_addc_u32 s6, s23, -1
	s_add_i32 s7, 0, 0x10000
	s_cmp_eq_u32 s2, 4
	s_cselect_b32 s35, s4, s6
	s_cselect_b32 s34, s5, s3
	v_add_u32_e32 v96, s7, v176
	s_cselect_b32 s25, s9, s17
	s_cselect_b32 s24, s13, s15
	s_add_i32 s3, 0, 0x14000
	ds_read_b128 v[56:59], v96
	ds_read_b128 v[60:63], v96 offset:1024
	ds_read_b128 v[138:141], v96 offset:2048
	ds_read_b128 v[142:145], v96 offset:3072
	v_add_u32_e32 v96, s3, v176
	ds_read_b128 v[146:149], v96
	ds_read_b128 v[150:153], v96 offset:1024
	ds_read_b128 v[154:157], v96 offset:2048
	ds_read_b128 v[170:173], v96 offset:3072
	v_lshl_add_u64 v[174:175], s[22:23], 0, v[166:167]
	s_add_i32 m0, s75, 0xc000
	ds_read_b128 v[182:185], v177
	ds_read_b128 v[186:189], v177 offset:1024
	ds_read_b128 v[190:193], v177 offset:2048
	ds_read_b128 v[214:217], v177 offset:3072
	ds_read_b128 v[218:221], v177 offset:4096
	ds_read_b128 v[222:225], v177 offset:5120
	ds_read_b128 v[226:229], v177 offset:6144
	ds_read_b128 v[230:233], v177 offset:7168
	global_load_lds_dwordx4 v[174:175], off
	v_lshl_add_u64 v[174:175], s[22:23], 0, v[168:169]
	s_add_i32 m0, s75, 0xe000
	s_nop 0
	global_load_lds_dwordx4 v[174:175], off
	s_waitcnt vmcnt(8)
	s_waitcnt lgkmcnt(0)
	v_mfma_f32_16x16x32_bf16 v[134:137], v[56:59], v[182:185], v[134:137]
	v_mfma_f32_16x16x32_bf16 v[130:133], v[138:141], v[182:185], v[130:133]
	v_mfma_f32_16x16x32_bf16 v[118:121], v[56:59], v[190:193], v[118:121]
	v_mfma_f32_16x16x32_bf16 v[114:117], v[138:141], v[190:193], v[114:117]
	s_barrier
	s_setprio 1
	s_waitcnt lgkmcnt(0)
	v_mfma_f32_16x16x32_bf16 v[102:105], v[56:59], v[218:221], v[102:105]
	v_mfma_f32_16x16x32_bf16 v[98:101], v[138:141], v[218:221], v[98:101]
	v_mfma_f32_16x16x32_bf16 v[84:87], v[56:59], v[226:229], v[84:87]
	v_mfma_f32_16x16x32_bf16 v[80:83], v[138:141], v[226:229], v[80:83]
	v_mfma_f32_16x16x32_bf16 v[134:137], v[60:63], v[186:189], v[134:137]
	v_mfma_f32_16x16x32_bf16 v[130:133], v[142:145], v[186:189], v[130:133]
	v_mfma_f32_16x16x32_bf16 v[118:121], v[60:63], v[214:217], v[118:121]
	v_mfma_f32_16x16x32_bf16 v[114:117], v[142:145], v[214:217], v[114:117]
	v_mfma_f32_16x16x32_bf16 v[102:105], v[60:63], v[222:225], v[102:105]
	v_mfma_f32_16x16x32_bf16 v[98:101], v[142:145], v[222:225], v[98:101]
	v_mfma_f32_16x16x32_bf16 v[84:87], v[60:63], v[230:233], v[84:87]
	v_mfma_f32_16x16x32_bf16 v[80:83], v[142:145], v[230:233], v[80:83]
	s_setprio 0
	s_setprio 1
	v_mfma_f32_16x16x32_bf16 v[126:129], v[146:149], v[182:185], v[126:129]
	v_mfma_f32_16x16x32_bf16 v[122:125], v[154:157], v[182:185], v[122:125]
	v_mfma_f32_16x16x32_bf16 v[110:113], v[146:149], v[190:193], v[110:113]
	v_mfma_f32_16x16x32_bf16 v[106:109], v[154:157], v[190:193], v[106:109]
	v_mfma_f32_16x16x32_bf16 v[92:95], v[146:149], v[218:221], v[92:95]
	v_mfma_f32_16x16x32_bf16 v[88:91], v[154:157], v[218:221], v[88:91]
	v_mfma_f32_16x16x32_bf16 v[76:79], v[146:149], v[226:229], v[76:79]
	v_mfma_f32_16x16x32_bf16 v[72:75], v[154:157], v[226:229], v[72:75]
	v_mfma_f32_16x16x32_bf16 v[126:129], v[150:153], v[186:189], v[126:129]
	v_mfma_f32_16x16x32_bf16 v[122:125], v[170:173], v[186:189], v[122:125]
	v_mfma_f32_16x16x32_bf16 v[110:113], v[150:153], v[214:217], v[110:113]
	v_mfma_f32_16x16x32_bf16 v[106:109], v[170:173], v[214:217], v[106:109]
	v_mfma_f32_16x16x32_bf16 v[92:95], v[150:153], v[222:225], v[92:95]
	v_mfma_f32_16x16x32_bf16 v[88:91], v[170:173], v[222:225], v[88:91]
	v_mfma_f32_16x16x32_bf16 v[76:79], v[150:153], v[230:233], v[76:79]
	v_mfma_f32_16x16x32_bf16 v[72:75], v[170:173], v[230:233], v[72:75]
	s_setprio 0
	s_barrier
	s_add_i32 s6, s7, s74
	v_lshl_add_u64 v[174:175], s[24:25], 0, v[160:161]
	s_mov_b32 m0, s6
	ds_read_b128 v[182:185], v177 offset:16384
	ds_read_b128 v[186:189], v177 offset:17408
	ds_read_b128 v[190:193], v177 offset:18432
	ds_read_b128 v[214:217], v177 offset:19456
	ds_read_b128 v[218:221], v177 offset:20480
	ds_read_b128 v[222:225], v177 offset:21504
	ds_read_b128 v[226:229], v177 offset:22528
	ds_read_b128 v[230:233], v177 offset:23552
	global_load_lds_dwordx4 v[174:175], off
	s_add_i32 m0, s6, 0x2000
	s_add_u32 s6, s24, 0x20000
	v_lshl_add_u64 v[178:179], s[24:25], 0, v[164:165]
	s_addc_u32 s7, s25, 0
	s_add_i32 s3, s3, s74
	global_load_lds_dwordx4 v[178:179], off
	v_lshl_add_u64 v[180:181], s[6:7], 0, v[160:161]
	s_mov_b32 m0, s3
	v_lshl_add_u64 v[194:195], s[34:35], 0, v[162:163]
	global_load_lds_dwordx4 v[180:181], off
	v_lshl_add_u64 v[180:181], s[6:7], 0, v[164:165]
	s_add_i32 m0, s3, 0x2000
	s_nop 0
	global_load_lds_dwordx4 v[180:181], off
	v_lshl_add_u64 v[180:181], s[34:35], 0, v[158:159]
	s_mov_b32 m0, s75
	s_nop 0
	global_load_lds_dwordx4 v[180:181], off
	s_mov_b32 m0, s82
	s_nop 0
	global_load_lds_dwordx4 v[194:195], off
	s_waitcnt vmcnt(8)
	s_waitcnt lgkmcnt(0)
	v_mfma_f32_16x16x32_bf16 v[68:71], v[56:59], v[182:185], v[68:71]
	v_mfma_f32_16x16x32_bf16 v[64:67], v[138:141], v[182:185], v[64:67]
	v_mfma_f32_16x16x32_bf16 v[44:47], v[56:59], v[190:193], v[44:47]
	v_mfma_f32_16x16x32_bf16 v[40:43], v[138:141], v[190:193], v[40:43]
	s_barrier
	s_setprio 1
	s_waitcnt lgkmcnt(0)
	v_mfma_f32_16x16x32_bf16 v[28:31], v[56:59], v[218:221], v[28:31]
	v_mfma_f32_16x16x32_bf16 v[24:27], v[138:141], v[218:221], v[24:27]
	v_mfma_f32_16x16x32_bf16 v[12:15], v[56:59], v[226:229], v[12:15]
	v_mfma_f32_16x16x32_bf16 v[8:11], v[138:141], v[226:229], v[8:11]
	v_mfma_f32_16x16x32_bf16 v[68:71], v[60:63], v[186:189], v[68:71]
	v_mfma_f32_16x16x32_bf16 v[64:67], v[142:145], v[186:189], v[64:67]
	v_mfma_f32_16x16x32_bf16 v[44:47], v[60:63], v[214:217], v[44:47]
	v_mfma_f32_16x16x32_bf16 v[40:43], v[142:145], v[214:217], v[40:43]
	v_mfma_f32_16x16x32_bf16 v[28:31], v[60:63], v[222:225], v[28:31]
	v_mfma_f32_16x16x32_bf16 v[24:27], v[142:145], v[222:225], v[24:27]
	v_mfma_f32_16x16x32_bf16 v[12:15], v[60:63], v[230:233], v[12:15]
	v_mfma_f32_16x16x32_bf16 v[8:11], v[142:145], v[230:233], v[8:11]
	s_setprio 0
	s_setprio 1
	v_mfma_f32_16x16x32_bf16 v[52:55], v[146:149], v[182:185], v[52:55]
	v_mfma_f32_16x16x32_bf16 v[48:51], v[154:157], v[182:185], v[48:51]
	v_mfma_f32_16x16x32_bf16 v[36:39], v[146:149], v[190:193], v[36:39]
	v_mfma_f32_16x16x32_bf16 v[32:35], v[154:157], v[190:193], v[32:35]
	v_mfma_f32_16x16x32_bf16 v[20:23], v[146:149], v[218:221], v[20:23]
	v_mfma_f32_16x16x32_bf16 v[16:19], v[154:157], v[218:221], v[16:19]
	v_mfma_f32_16x16x32_bf16 v[4:7], v[146:149], v[226:229], v[4:7]
	v_mfma_f32_16x16x32_bf16 v[0:3], v[154:157], v[226:229], v[0:3]
	v_mfma_f32_16x16x32_bf16 v[52:55], v[150:153], v[186:189], v[52:55]
	v_mfma_f32_16x16x32_bf16 v[48:51], v[170:173], v[186:189], v[48:51]
	v_mfma_f32_16x16x32_bf16 v[36:39], v[150:153], v[214:217], v[36:39]
	v_mfma_f32_16x16x32_bf16 v[32:35], v[170:173], v[214:217], v[32:35]
	v_mfma_f32_16x16x32_bf16 v[20:23], v[150:153], v[222:225], v[20:23]
	v_mfma_f32_16x16x32_bf16 v[16:19], v[170:173], v[222:225], v[16:19]
	v_mfma_f32_16x16x32_bf16 v[4:7], v[150:153], v[230:233], v[4:7]
	v_mfma_f32_16x16x32_bf16 v[0:3], v[170:173], v[230:233], v[0:3]
	s_setprio 0
	s_barrier
	s_add_i32 s3, 0, 0x18000
	v_add_u32_e32 v96, s3, v176
	s_add_i32 s18, 0, 0x1c000
	ds_read_b128 v[56:59], v96
	ds_read_b128 v[60:63], v96 offset:1024
	ds_read_b128 v[138:141], v96 offset:2048
	ds_read_b128 v[142:145], v96 offset:3072
	v_add_u32_e32 v96, s18, v176
	ds_read_b128 v[146:149], v96
	ds_read_b128 v[150:153], v96 offset:1024
	ds_read_b128 v[154:157], v96 offset:2048
	ds_read_b128 v[170:173], v96 offset:3072
	s_add_u32 s6, s34, 0x20000
	s_addc_u32 s7, s35, 0
	s_mov_b32 m0, s83
	v_lshl_add_u64 v[202:203], s[6:7], 0, v[158:159]
	ds_read_b128 v[182:185], v177 offset:32768
	ds_read_b128 v[186:189], v177 offset:33792
	ds_read_b128 v[190:193], v177 offset:34816
	ds_read_b128 v[214:217], v177 offset:35840
	ds_read_b128 v[218:221], v177 offset:36864
	ds_read_b128 v[222:225], v177 offset:37888
	ds_read_b128 v[226:229], v177 offset:38912
	ds_read_b128 v[230:233], v177 offset:39936
	global_load_lds_dwordx4 v[202:203], off
	v_lshl_add_u64 v[202:203], s[6:7], 0, v[162:163]
	s_mov_b32 m0, s88
	s_nop 0
	global_load_lds_dwordx4 v[202:203], off
	s_waitcnt vmcnt(8)
	s_waitcnt lgkmcnt(0)
	v_mfma_f32_16x16x32_bf16 v[134:137], v[56:59], v[182:185], v[134:137]
	v_mfma_f32_16x16x32_bf16 v[130:133], v[138:141], v[182:185], v[130:133]
	v_mfma_f32_16x16x32_bf16 v[118:121], v[56:59], v[190:193], v[118:121]
	v_mfma_f32_16x16x32_bf16 v[114:117], v[138:141], v[190:193], v[114:117]
	s_barrier
	s_setprio 1
	s_waitcnt lgkmcnt(0)
	v_mfma_f32_16x16x32_bf16 v[102:105], v[56:59], v[218:221], v[102:105]
	v_mfma_f32_16x16x32_bf16 v[98:101], v[138:141], v[218:221], v[98:101]
	v_mfma_f32_16x16x32_bf16 v[84:87], v[56:59], v[226:229], v[84:87]
	v_mfma_f32_16x16x32_bf16 v[80:83], v[138:141], v[226:229], v[80:83]
	v_mfma_f32_16x16x32_bf16 v[134:137], v[60:63], v[186:189], v[134:137]
	v_mfma_f32_16x16x32_bf16 v[130:133], v[142:145], v[186:189], v[130:133]
	v_mfma_f32_16x16x32_bf16 v[118:121], v[60:63], v[214:217], v[118:121]
	v_mfma_f32_16x16x32_bf16 v[114:117], v[142:145], v[214:217], v[114:117]
	v_mfma_f32_16x16x32_bf16 v[102:105], v[60:63], v[222:225], v[102:105]
	v_mfma_f32_16x16x32_bf16 v[98:101], v[142:145], v[222:225], v[98:101]
	v_mfma_f32_16x16x32_bf16 v[84:87], v[60:63], v[230:233], v[84:87]
	v_mfma_f32_16x16x32_bf16 v[80:83], v[142:145], v[230:233], v[80:83]
	s_setprio 0
	s_setprio 1
	v_mfma_f32_16x16x32_bf16 v[126:129], v[146:149], v[182:185], v[126:129]
	v_mfma_f32_16x16x32_bf16 v[122:125], v[154:157], v[182:185], v[122:125]
	v_mfma_f32_16x16x32_bf16 v[110:113], v[146:149], v[190:193], v[110:113]
	v_mfma_f32_16x16x32_bf16 v[106:109], v[154:157], v[190:193], v[106:109]
	v_mfma_f32_16x16x32_bf16 v[92:95], v[146:149], v[218:221], v[92:95]
	v_mfma_f32_16x16x32_bf16 v[88:91], v[154:157], v[218:221], v[88:91]
	v_mfma_f32_16x16x32_bf16 v[76:79], v[146:149], v[226:229], v[76:79]
	v_mfma_f32_16x16x32_bf16 v[72:75], v[154:157], v[226:229], v[72:75]
	v_mfma_f32_16x16x32_bf16 v[126:129], v[150:153], v[186:189], v[126:129]
	v_mfma_f32_16x16x32_bf16 v[122:125], v[170:173], v[186:189], v[122:125]
	v_mfma_f32_16x16x32_bf16 v[110:113], v[150:153], v[214:217], v[110:113]
	v_mfma_f32_16x16x32_bf16 v[106:109], v[170:173], v[214:217], v[106:109]
	v_mfma_f32_16x16x32_bf16 v[92:95], v[150:153], v[222:225], v[92:95]
	v_mfma_f32_16x16x32_bf16 v[88:91], v[170:173], v[222:225], v[88:91]
	v_mfma_f32_16x16x32_bf16 v[76:79], v[150:153], v[230:233], v[76:79]
	v_mfma_f32_16x16x32_bf16 v[72:75], v[170:173], v[230:233], v[72:75]
	s_setprio 0
	s_barrier
	s_add_i32 s3, s3, s74
	v_lshl_add_u64 v[174:175], v[174:175], 0, s[30:31]
	s_mov_b32 m0, s3
	ds_read_b128 v[182:185], v177 offset:49152
	ds_read_b128 v[186:189], v177 offset:50176
	ds_read_b128 v[190:193], v177 offset:51200
	ds_read_b128 v[214:217], v177 offset:52224
	ds_read_b128 v[218:221], v177 offset:53248
	ds_read_b128 v[222:225], v177 offset:54272
	ds_read_b128 v[226:229], v177 offset:55296
	ds_read_b128 v[230:233], v177 offset:56320
	global_load_lds_dwordx4 v[174:175], off
	s_add_i32 m0, s3, 0x2000
	s_add_u32 s6, s24, 0x20080
	v_lshl_add_u64 v[174:175], v[178:179], 0, s[30:31]
	s_addc_u32 s7, s25, 0
	s_add_i32 s3, s18, s74
	global_load_lds_dwordx4 v[174:175], off
	v_lshl_add_u64 v[174:175], s[6:7], 0, v[160:161]
	s_mov_b32 m0, s3
	s_nop 0
	global_load_lds_dwordx4 v[174:175], off
	v_lshl_add_u64 v[174:175], s[6:7], 0, v[164:165]
	s_add_i32 m0, s3, 0x2000
	s_nop 0
	global_load_lds_dwordx4 v[174:175], off
	v_lshl_add_u64 v[174:175], v[180:181], 0, s[30:31]
	s_mov_b32 m0, s97
	s_nop 0
	global_load_lds_dwordx4 v[174:175], off
	v_lshl_add_u64 v[174:175], v[194:195], 0, s[30:31]
	s_mov_b32 m0, s50
	s_nop 0
	global_load_lds_dwordx4 v[174:175], off
	s_waitcnt vmcnt(8)
	s_waitcnt lgkmcnt(0)
	v_mfma_f32_16x16x32_bf16 v[68:71], v[56:59], v[182:185], v[68:71]
	v_mfma_f32_16x16x32_bf16 v[64:67], v[138:141], v[182:185], v[64:67]
	v_mfma_f32_16x16x32_bf16 v[44:47], v[56:59], v[190:193], v[44:47]
	v_mfma_f32_16x16x32_bf16 v[40:43], v[138:141], v[190:193], v[40:43]
	s_barrier
	s_setprio 1
	s_waitcnt lgkmcnt(0)
	v_mfma_f32_16x16x32_bf16 v[28:31], v[56:59], v[218:221], v[28:31]
	v_mfma_f32_16x16x32_bf16 v[24:27], v[138:141], v[218:221], v[24:27]
	v_mfma_f32_16x16x32_bf16 v[12:15], v[56:59], v[226:229], v[12:15]
	v_mfma_f32_16x16x32_bf16 v[8:11], v[138:141], v[226:229], v[8:11]
	v_mfma_f32_16x16x32_bf16 v[68:71], v[60:63], v[186:189], v[68:71]
	v_mfma_f32_16x16x32_bf16 v[64:67], v[142:145], v[186:189], v[64:67]
	v_mfma_f32_16x16x32_bf16 v[44:47], v[60:63], v[214:217], v[44:47]
	v_mfma_f32_16x16x32_bf16 v[40:43], v[142:145], v[214:217], v[40:43]
	v_mfma_f32_16x16x32_bf16 v[28:31], v[60:63], v[222:225], v[28:31]
	v_mfma_f32_16x16x32_bf16 v[24:27], v[142:145], v[222:225], v[24:27]
	v_mfma_f32_16x16x32_bf16 v[12:15], v[60:63], v[230:233], v[12:15]
	v_mfma_f32_16x16x32_bf16 v[8:11], v[142:145], v[230:233], v[8:11]
	s_setprio 0
	s_setprio 1
	v_mfma_f32_16x16x32_bf16 v[52:55], v[146:149], v[182:185], v[52:55]
	v_mfma_f32_16x16x32_bf16 v[48:51], v[154:157], v[182:185], v[48:51]
	v_mfma_f32_16x16x32_bf16 v[36:39], v[146:149], v[190:193], v[36:39]
	v_mfma_f32_16x16x32_bf16 v[32:35], v[154:157], v[190:193], v[32:35]
	v_mfma_f32_16x16x32_bf16 v[20:23], v[146:149], v[218:221], v[20:23]
	v_mfma_f32_16x16x32_bf16 v[16:19], v[154:157], v[218:221], v[16:19]
	v_mfma_f32_16x16x32_bf16 v[4:7], v[146:149], v[226:229], v[4:7]
	v_mfma_f32_16x16x32_bf16 v[0:3], v[154:157], v[226:229], v[0:3]
	v_mfma_f32_16x16x32_bf16 v[52:55], v[150:153], v[186:189], v[52:55]
	v_mfma_f32_16x16x32_bf16 v[48:51], v[170:173], v[186:189], v[48:51]
	v_mfma_f32_16x16x32_bf16 v[36:39], v[150:153], v[214:217], v[36:39]
	v_mfma_f32_16x16x32_bf16 v[32:35], v[170:173], v[214:217], v[32:35]
	v_mfma_f32_16x16x32_bf16 v[20:23], v[150:153], v[222:225], v[20:23]
	v_mfma_f32_16x16x32_bf16 v[16:19], v[170:173], v[222:225], v[16:19]
	v_mfma_f32_16x16x32_bf16 v[4:7], v[150:153], v[230:233], v[4:7]
	v_mfma_f32_16x16x32_bf16 v[0:3], v[170:173], v[230:233], v[0:3]
	s_setprio 0
	s_barrier
	s_add_i32 s2, s2, 2
	s_add_u32 s22, s22, 0x100
	s_addc_u32 s23, s23, 0
	s_add_u32 s15, s15, 0x100
	s_addc_u32 s17, s17, 0
	s_cmp_gt_u32 s2, 5
	s_cbranch_scc0 .LBB0_421
	s_and_b64 vcc, exec, s[58:59]
	s_cbranch_vccz .LBB0_424
	s_barrier

.LBB0_680:
	s_ashr_i32 s35, s34, 31
	s_lshl_b64 s[2:3], s[34:35], 17
	v_readlane_b32 s6, v251, 63
	s_add_u32 s38, s6, s2
	v_readlane_b32 s2, v252, 0
	s_addc_u32 s39, s2, s3
	s_and_b64 s[2:3], s[0:1], exec
	s_cselect_b32 s59, s39, s49
	s_cselect_b32 s58, s38, s48
	s_ashr_i32 s25, s24, 31
	s_lshl_b64 s[2:3], s[24:25], 17
	s_add_u32 s42, s5, s2
	s_addc_u32 s43, s17, s3
	s_and_b64 s[2:3], s[0:1], exec
	s_cselect_b32 s51, s43, s53
	s_cselect_b32 s50, s42, s52
	s_add_i32 s25, 0, 0x10000
	s_add_i32 s6, 0, 0x14000
	v_add_u32_e32 v96, s25, v148
	v_add_u32_e32 v198, s6, v148
	ds_read_b128 v[0:3], v96
	ds_read_b128 v[4:7], v96 offset:1024
	ds_read_b128 v[8:11], v96 offset:2048
	ds_read_b128 v[12:15], v96 offset:3072
	ds_read_b128 v[16:19], v198
	ds_read_b128 v[20:23], v198 offset:1024
	ds_read_b128 v[24:27], v198 offset:2048
	ds_read_b128 v[28:31], v198 offset:3072
	s_add_u32 s2, s48, 0x10080
	s_addc_u32 s3, s49, 0
	s_add_i32 s56, s18, 0xc000
	v_lshl_add_u64 v[64:65], s[2:3], 0, v[138:139]
	s_mov_b32 m0, s56
	ds_read_b128 v[32:35], v149
	ds_read_b128 v[36:39], v149 offset:1024
	ds_read_b128 v[40:43], v149 offset:2048
	ds_read_b128 v[44:47], v149 offset:3072
	ds_read_b128 v[48:51], v149 offset:4096
	ds_read_b128 v[52:55], v149 offset:5120
	ds_read_b128 v[56:59], v149 offset:6144
	ds_read_b128 v[60:63], v149 offset:7168
	global_load_lds_dwordx4 v[64:65], off
	v_lshl_add_u64 v[64:65], s[2:3], 0, v[142:143]
	s_add_i32 s2, s18, 0xe000
	s_mov_b32 m0, s2
	s_nop 0
	global_load_lds_dwordx4 v[64:65], off
	s_waitcnt vmcnt(8)
	s_waitcnt lgkmcnt(0)
	v_mfma_f32_16x16x32_bf16 v[64:67], v[0:3], v[32:35], 0
	v_mfma_f32_16x16x32_bf16 v[68:71], v[8:11], v[32:35], 0
	v_mfma_f32_16x16x32_bf16 v[72:75], v[0:3], v[40:43], 0
	v_mfma_f32_16x16x32_bf16 v[76:79], v[8:11], v[40:43], 0
	s_barrier
	s_setprio 1
	s_waitcnt lgkmcnt(0)
	v_mfma_f32_16x16x32_bf16 v[80:83], v[0:3], v[48:51], 0
	v_mfma_f32_16x16x32_bf16 v[84:87], v[8:11], v[48:51], 0
	v_mfma_f32_16x16x32_bf16 v[88:91], v[0:3], v[56:59], 0
	v_mfma_f32_16x16x32_bf16 v[92:95], v[8:11], v[56:59], 0
	v_mfma_f32_16x16x32_bf16 v[64:67], v[4:7], v[36:39], v[64:67]
	v_mfma_f32_16x16x32_bf16 v[68:71], v[12:15], v[36:39], v[68:71]
	v_mfma_f32_16x16x32_bf16 v[72:75], v[4:7], v[44:47], v[72:75]
	v_mfma_f32_16x16x32_bf16 v[76:79], v[12:15], v[44:47], v[76:79]
	v_mfma_f32_16x16x32_bf16 v[80:83], v[4:7], v[52:55], v[80:83]
	v_mfma_f32_16x16x32_bf16 v[84:87], v[12:15], v[52:55], v[84:87]
	v_mfma_f32_16x16x32_bf16 v[88:91], v[4:7], v[60:63], v[88:91]
	v_mfma_f32_16x16x32_bf16 v[92:95], v[12:15], v[60:63], v[92:95]
	s_setprio 0
	s_setprio 1
	v_mfma_f32_16x16x32_bf16 v[98:101], v[16:19], v[32:35], 0
	v_mfma_f32_16x16x32_bf16 v[32:35], v[24:27], v[32:35], 0
	v_mfma_f32_16x16x32_bf16 v[98:101], v[20:23], v[36:39], v[98:101]
	v_mfma_f32_16x16x32_bf16 v[32:35], v[28:31], v[36:39], v[32:35]
	v_mfma_f32_16x16x32_bf16 v[36:39], v[16:19], v[40:43], 0
	v_mfma_f32_16x16x32_bf16 v[40:43], v[24:27], v[40:43], 0
	v_mfma_f32_16x16x32_bf16 v[36:39], v[20:23], v[44:47], v[36:39]
	v_mfma_f32_16x16x32_bf16 v[40:43], v[28:31], v[44:47], v[40:43]
	v_mfma_f32_16x16x32_bf16 v[44:47], v[16:19], v[48:51], 0
	v_mfma_f32_16x16x32_bf16 v[48:51], v[24:27], v[48:51], 0
	v_mfma_f32_16x16x32_bf16 v[44:47], v[20:23], v[52:55], v[44:47]
	v_mfma_f32_16x16x32_bf16 v[48:51], v[28:31], v[52:55], v[48:51]
	v_mfma_f32_16x16x32_bf16 v[52:55], v[16:19], v[56:59], 0
	v_mfma_f32_16x16x32_bf16 v[56:59], v[24:27], v[56:59], 0
	v_mfma_f32_16x16x32_bf16 v[52:55], v[20:23], v[60:63], v[52:55]
	v_mfma_f32_16x16x32_bf16 v[56:59], v[28:31], v[60:63], v[56:59]
	s_setprio 0
	s_barrier
	s_add_i32 s25, s25, s4
	v_lshl_add_u64 v[146:147], s[52:53], 0, v[140:141]
	s_mov_b64 vcc, 0x100
	s_add_i32 s3, s25, 0x2000
	v_lshl_add_u64 v[130:131], v[146:147], 0, vcc
	s_mov_b32 m0, s25
	v_lshl_add_u64 v[178:179], s[52:53], 0, v[144:145]
	s_add_u32 s60, s52, 0x10100
	ds_read_b128 v[60:63], v149 offset:16384
	ds_read_b128 v[102:105], v149 offset:17408
	ds_read_b128 v[106:109], v149 offset:18432
	ds_read_b128 v[110:113], v149 offset:19456
	ds_read_b128 v[114:117], v149 offset:20480
	ds_read_b128 v[118:121], v149 offset:21504
	ds_read_b128 v[122:125], v149 offset:22528
	ds_read_b128 v[126:129], v149 offset:23552
	global_load_lds_dwordx4 v[130:131], off
	v_lshl_add_u64 v[130:131], v[178:179], 0, vcc
	s_mov_b32 m0, s3
	s_addc_u32 s61, s53, 0
	s_add_i32 s6, s6, s4
	global_load_lds_dwordx4 v[130:131], off
	v_lshl_add_u64 v[130:131], s[60:61], 0, v[140:141]
	s_mov_b32 m0, s6
	s_add_i32 s7, s6, 0x2000
	global_load_lds_dwordx4 v[130:131], off
	v_lshl_add_u64 v[130:131], s[60:61], 0, v[144:145]
	s_mov_b32 m0, s7
	v_lshl_add_u64 v[180:181], s[48:49], 0, v[138:139]
	global_load_lds_dwordx4 v[130:131], off
	v_lshl_add_u64 v[130:131], v[180:181], 0, vcc
	s_mov_b32 m0, s18
	v_lshl_add_u64 v[194:195], s[48:49], 0, v[142:143]
	global_load_lds_dwordx4 v[130:131], off
	v_lshl_add_u64 v[130:131], v[194:195], 0, vcc
	s_mov_b32 m0, s19
	s_nop 0
	global_load_lds_dwordx4 v[130:131], off
	s_waitcnt vmcnt(8)
	s_waitcnt lgkmcnt(0)
	v_mfma_f32_16x16x32_bf16 v[130:133], v[0:3], v[60:63], 0
	v_mfma_f32_16x16x32_bf16 v[150:153], v[0:3], v[106:109], 0
	v_mfma_f32_16x16x32_bf16 v[158:161], v[0:3], v[114:117], 0
	v_mfma_f32_16x16x32_bf16 v[0:3], v[0:3], v[122:125], 0
	s_barrier
	s_setprio 1
	s_waitcnt lgkmcnt(0)
	v_mfma_f32_16x16x32_bf16 v[130:133], v[4:7], v[102:105], v[130:133]
	v_mfma_f32_16x16x32_bf16 v[134:137], v[8:11], v[60:63], 0
	v_mfma_f32_16x16x32_bf16 v[150:153], v[4:7], v[110:113], v[150:153]
	v_mfma_f32_16x16x32_bf16 v[158:161], v[4:7], v[118:121], v[158:161]
	v_mfma_f32_16x16x32_bf16 v[0:3], v[4:7], v[126:129], v[0:3]
	v_mfma_f32_16x16x32_bf16 v[4:7], v[8:11], v[122:125], 0
	v_mfma_f32_16x16x32_bf16 v[134:137], v[12:15], v[102:105], v[134:137]
	v_mfma_f32_16x16x32_bf16 v[154:157], v[8:11], v[106:109], 0
	v_mfma_f32_16x16x32_bf16 v[162:165], v[8:11], v[114:117], 0
	v_mfma_f32_16x16x32_bf16 v[4:7], v[12:15], v[126:129], v[4:7]
	v_mfma_f32_16x16x32_bf16 v[154:157], v[12:15], v[110:113], v[154:157]
	v_mfma_f32_16x16x32_bf16 v[162:165], v[12:15], v[118:121], v[162:165]
	s_setprio 0
	s_setprio 1
	v_mfma_f32_16x16x32_bf16 v[8:11], v[16:19], v[60:63], 0
	v_mfma_f32_16x16x32_bf16 v[12:15], v[24:27], v[60:63], 0
	v_mfma_f32_16x16x32_bf16 v[8:11], v[20:23], v[102:105], v[8:11]
	v_mfma_f32_16x16x32_bf16 v[12:15], v[28:31], v[102:105], v[12:15]
	v_mfma_f32_16x16x32_bf16 v[60:63], v[16:19], v[106:109], 0
	v_mfma_f32_16x16x32_bf16 v[102:105], v[24:27], v[106:109], 0
	v_mfma_f32_16x16x32_bf16 v[106:109], v[16:19], v[114:117], 0
	v_mfma_f32_16x16x32_bf16 v[16:19], v[16:19], v[122:125], 0
	v_mfma_f32_16x16x32_bf16 v[60:63], v[20:23], v[110:113], v[60:63]
	v_mfma_f32_16x16x32_bf16 v[106:109], v[20:23], v[118:121], v[106:109]
	v_mfma_f32_16x16x32_bf16 v[16:19], v[20:23], v[126:129], v[16:19]
	v_mfma_f32_16x16x32_bf16 v[20:23], v[24:27], v[122:125], 0
	v_mfma_f32_16x16x32_bf16 v[102:105], v[28:31], v[110:113], v[102:105]
	v_mfma_f32_16x16x32_bf16 v[110:113], v[24:27], v[114:117], 0
	v_mfma_f32_16x16x32_bf16 v[20:23], v[28:31], v[126:129], v[20:23]
	v_mfma_f32_16x16x32_bf16 v[110:113], v[28:31], v[118:121], v[110:113]
	s_setprio 0
	s_barrier
	s_add_i32 s57, 0, 0x18000
	s_add_i32 s62, 0, 0x1c000
	v_add_u32_e32 v204, s57, v148
	v_add_u32_e32 v205, s62, v148
	ds_read_b128 v[24:27], v204
	ds_read_b128 v[28:31], v204 offset:1024
	ds_read_b128 v[114:117], v204 offset:2048
	ds_read_b128 v[118:121], v204 offset:3072
	ds_read_b128 v[122:125], v205
	ds_read_b128 v[126:129], v205 offset:1024
	ds_read_b128 v[166:169], v205 offset:2048
	ds_read_b128 v[170:173], v205 offset:3072
	s_add_u32 s60, s48, 0x10100
	s_addc_u32 s61, s49, 0
	s_mov_b32 m0, s20
	v_lshl_add_u64 v[202:203], s[60:61], 0, v[138:139]
	ds_read_b128 v[174:177], v149 offset:32768
	ds_read_b128 v[182:185], v149 offset:33792
	ds_read_b128 v[186:189], v149 offset:34816
	ds_read_b128 v[190:193], v149 offset:35840
	ds_read_b128 v[214:217], v149 offset:36864
	ds_read_b128 v[218:221], v149 offset:37888
	ds_read_b128 v[222:225], v149 offset:38912
	ds_read_b128 v[226:229], v149 offset:39936
	global_load_lds_dwordx4 v[202:203], off
	v_lshl_add_u64 v[202:203], s[60:61], 0, v[142:143]
	s_mov_b32 m0, s36
	s_nop 0
	global_load_lds_dwordx4 v[202:203], off
	s_waitcnt vmcnt(8)
	s_waitcnt lgkmcnt(0)
	v_mfma_f32_16x16x32_bf16 v[64:67], v[24:27], v[174:177], v[64:67]
	v_mfma_f32_16x16x32_bf16 v[68:71], v[114:117], v[174:177], v[68:71]
	v_mfma_f32_16x16x32_bf16 v[72:75], v[24:27], v[186:189], v[72:75]
	v_mfma_f32_16x16x32_bf16 v[76:79], v[114:117], v[186:189], v[76:79]
	s_barrier
	s_setprio 1
	s_waitcnt lgkmcnt(0)
	v_mfma_f32_16x16x32_bf16 v[80:83], v[24:27], v[214:217], v[80:83]
	v_mfma_f32_16x16x32_bf16 v[84:87], v[114:117], v[214:217], v[84:87]
	v_mfma_f32_16x16x32_bf16 v[88:91], v[24:27], v[222:225], v[88:91]
	v_mfma_f32_16x16x32_bf16 v[92:95], v[114:117], v[222:225], v[92:95]
	v_mfma_f32_16x16x32_bf16 v[64:67], v[28:31], v[182:185], v[64:67]
	v_mfma_f32_16x16x32_bf16 v[68:71], v[118:121], v[182:185], v[68:71]
	v_mfma_f32_16x16x32_bf16 v[72:75], v[28:31], v[190:193], v[72:75]
	v_mfma_f32_16x16x32_bf16 v[76:79], v[118:121], v[190:193], v[76:79]
	v_mfma_f32_16x16x32_bf16 v[80:83], v[28:31], v[218:221], v[80:83]
	v_mfma_f32_16x16x32_bf16 v[84:87], v[118:121], v[218:221], v[84:87]
	v_mfma_f32_16x16x32_bf16 v[88:91], v[28:31], v[226:229], v[88:91]
	v_mfma_f32_16x16x32_bf16 v[92:95], v[118:121], v[226:229], v[92:95]
	s_setprio 0
	s_setprio 1
	v_mfma_f32_16x16x32_bf16 v[98:101], v[122:125], v[174:177], v[98:101]
	v_mfma_f32_16x16x32_bf16 v[32:35], v[166:169], v[174:177], v[32:35]
	v_mfma_f32_16x16x32_bf16 v[36:39], v[122:125], v[186:189], v[36:39]
	v_mfma_f32_16x16x32_bf16 v[40:43], v[166:169], v[186:189], v[40:43]
	v_mfma_f32_16x16x32_bf16 v[44:47], v[122:125], v[214:217], v[44:47]
	v_mfma_f32_16x16x32_bf16 v[48:51], v[166:169], v[214:217], v[48:51]
	v_mfma_f32_16x16x32_bf16 v[52:55], v[122:125], v[222:225], v[52:55]
	v_mfma_f32_16x16x32_bf16 v[56:59], v[166:169], v[222:225], v[56:59]
	v_mfma_f32_16x16x32_bf16 v[98:101], v[126:129], v[182:185], v[98:101]
	v_mfma_f32_16x16x32_bf16 v[32:35], v[170:173], v[182:185], v[32:35]
	v_mfma_f32_16x16x32_bf16 v[36:39], v[126:129], v[190:193], v[36:39]
	v_mfma_f32_16x16x32_bf16 v[40:43], v[170:173], v[190:193], v[40:43]
	v_mfma_f32_16x16x32_bf16 v[44:47], v[126:129], v[218:221], v[44:47]
	v_mfma_f32_16x16x32_bf16 v[48:51], v[170:173], v[218:221], v[48:51]
	v_mfma_f32_16x16x32_bf16 v[52:55], v[126:129], v[226:229], v[52:55]
	v_mfma_f32_16x16x32_bf16 v[56:59], v[170:173], v[226:229], v[56:59]
	s_setprio 0
	s_barrier
	s_add_i32 s57, s57, s4
	s_mov_b64 vcc, 0x180
	s_add_i32 s35, s57, 0x2000
	v_lshl_add_u64 v[146:147], v[146:147], 0, vcc
	s_mov_b32 m0, s57
	s_add_u32 s60, s52, 0x10180
	ds_read_b128 v[174:177], v149 offset:49152
	ds_read_b128 v[182:185], v149 offset:50176
	ds_read_b128 v[186:189], v149 offset:51200
	ds_read_b128 v[190:193], v149 offset:52224
	ds_read_b128 v[214:217], v149 offset:53248
	ds_read_b128 v[218:221], v149 offset:54272
	ds_read_b128 v[222:225], v149 offset:55296
	ds_read_b128 v[226:229], v149 offset:56320
	global_load_lds_dwordx4 v[146:147], off
	v_lshl_add_u64 v[146:147], v[178:179], 0, vcc
	s_mov_b32 m0, s35
	s_addc_u32 s61, s53, 0
	s_add_i32 s52, s62, s4
	global_load_lds_dwordx4 v[146:147], off
	v_lshl_add_u64 v[146:147], s[60:61], 0, v[140:141]
	s_mov_b32 m0, s52
	s_add_i32 s53, s52, 0x2000
	global_load_lds_dwordx4 v[146:147], off
	v_lshl_add_u64 v[146:147], s[60:61], 0, v[144:145]
	s_mov_b32 m0, s53
	s_nop 0
	global_load_lds_dwordx4 v[146:147], off
	v_lshl_add_u64 v[146:147], v[180:181], 0, vcc
	s_mov_b32 m0, s45
	s_nop 0
	global_load_lds_dwordx4 v[146:147], off
	v_lshl_add_u64 v[146:147], v[194:195], 0, vcc
	s_mov_b32 m0, s47
	s_nop 0
	global_load_lds_dwordx4 v[146:147], off
	s_waitcnt vmcnt(8)
	s_waitcnt lgkmcnt(0)
	v_mfma_f32_16x16x32_bf16 v[130:133], v[24:27], v[174:177], v[130:133]
	v_mfma_f32_16x16x32_bf16 v[134:137], v[114:117], v[174:177], v[134:137]
	v_mfma_f32_16x16x32_bf16 v[0:3], v[24:27], v[222:225], v[0:3]
	v_mfma_f32_16x16x32_bf16 v[4:7], v[114:117], v[222:225], v[4:7]
	s_barrier
	s_setprio 1
	s_waitcnt lgkmcnt(0)
	v_mfma_f32_16x16x32_bf16 v[130:133], v[28:31], v[182:185], v[130:133]
	v_mfma_f32_16x16x32_bf16 v[134:137], v[118:121], v[182:185], v[134:137]
	v_mfma_f32_16x16x32_bf16 v[150:153], v[24:27], v[186:189], v[150:153]
	v_mfma_f32_16x16x32_bf16 v[154:157], v[114:117], v[186:189], v[154:157]
	v_mfma_f32_16x16x32_bf16 v[158:161], v[24:27], v[214:217], v[158:161]
	v_mfma_f32_16x16x32_bf16 v[162:165], v[114:117], v[214:217], v[162:165]
	v_mfma_f32_16x16x32_bf16 v[0:3], v[28:31], v[226:229], v[0:3]
	v_mfma_f32_16x16x32_bf16 v[4:7], v[118:121], v[226:229], v[4:7]
	v_mfma_f32_16x16x32_bf16 v[150:153], v[28:31], v[190:193], v[150:153]
	v_mfma_f32_16x16x32_bf16 v[154:157], v[118:121], v[190:193], v[154:157]
	v_mfma_f32_16x16x32_bf16 v[158:161], v[28:31], v[218:221], v[158:161]
	v_mfma_f32_16x16x32_bf16 v[162:165], v[118:121], v[218:221], v[162:165]
	s_setprio 0
	s_setprio 1
	v_mfma_f32_16x16x32_bf16 v[8:11], v[122:125], v[174:177], v[8:11]
	v_mfma_f32_16x16x32_bf16 v[12:15], v[166:169], v[174:177], v[12:15]
	v_mfma_f32_16x16x32_bf16 v[24:27], v[122:125], v[186:189], v[60:63]
	v_mfma_f32_16x16x32_bf16 v[28:31], v[166:169], v[186:189], v[102:105]
	v_mfma_f32_16x16x32_bf16 v[60:63], v[122:125], v[214:217], v[106:109]
	v_mfma_f32_16x16x32_bf16 v[102:105], v[166:169], v[214:217], v[110:113]
	v_mfma_f32_16x16x32_bf16 v[16:19], v[122:125], v[222:225], v[16:19]
	v_mfma_f32_16x16x32_bf16 v[20:23], v[166:169], v[222:225], v[20:23]
	v_mfma_f32_16x16x32_bf16 v[8:11], v[126:129], v[182:185], v[8:11]
	v_mfma_f32_16x16x32_bf16 v[12:15], v[170:173], v[182:185], v[12:15]
	v_mfma_f32_16x16x32_bf16 v[24:27], v[126:129], v[190:193], v[24:27]
	v_mfma_f32_16x16x32_bf16 v[28:31], v[170:173], v[190:193], v[28:31]
	v_mfma_f32_16x16x32_bf16 v[60:63], v[126:129], v[218:221], v[60:63]
	v_mfma_f32_16x16x32_bf16 v[102:105], v[170:173], v[218:221], v[102:105]
	v_mfma_f32_16x16x32_bf16 v[16:19], v[126:129], v[226:229], v[16:19]
	v_mfma_f32_16x16x32_bf16 v[20:23], v[170:173], v[226:229], v[20:23]
	s_setprio 0
	s_barrier
	ds_read_b128 v[106:109], v96
	ds_read_b128 v[110:113], v96 offset:1024
	ds_read_b128 v[114:117], v96 offset:2048
	ds_read_b128 v[118:121], v96 offset:3072
	ds_read_b128 v[122:125], v198
	ds_read_b128 v[126:129], v198 offset:1024
	ds_read_b128 v[166:169], v198 offset:2048
	ds_read_b128 v[170:173], v198 offset:3072
	s_add_u32 s48, s48, 0x10180
	s_addc_u32 s49, s49, 0
	s_mov_b32 m0, s56
	v_lshl_add_u64 v[146:147], s[48:49], 0, v[138:139]
	ds_read_b128 v[174:177], v149
	ds_read_b128 v[182:185], v149 offset:1024
	ds_read_b128 v[186:189], v149 offset:2048
	ds_read_b128 v[190:193], v149 offset:3072
	ds_read_b128 v[214:217], v149 offset:4096
	ds_read_b128 v[218:221], v149 offset:5120
	ds_read_b128 v[222:225], v149 offset:6144
	ds_read_b128 v[226:229], v149 offset:7168
	global_load_lds_dwordx4 v[146:147], off
	v_lshl_add_u64 v[146:147], s[48:49], 0, v[142:143]
	s_mov_b32 m0, s2
	s_nop 0
	global_load_lds_dwordx4 v[146:147], off
	s_waitcnt vmcnt(8)
	s_waitcnt lgkmcnt(0)
	v_mfma_f32_16x16x32_bf16 v[64:67], v[106:109], v[174:177], v[64:67]
	v_mfma_f32_16x16x32_bf16 v[68:71], v[114:117], v[174:177], v[68:71]
	v_mfma_f32_16x16x32_bf16 v[72:75], v[106:109], v[186:189], v[72:75]
	v_mfma_f32_16x16x32_bf16 v[76:79], v[114:117], v[186:189], v[76:79]
	s_barrier
	s_setprio 1
	s_waitcnt lgkmcnt(0)
	v_mfma_f32_16x16x32_bf16 v[80:83], v[106:109], v[214:217], v[80:83]
	v_mfma_f32_16x16x32_bf16 v[84:87], v[114:117], v[214:217], v[84:87]
	v_mfma_f32_16x16x32_bf16 v[88:91], v[106:109], v[222:225], v[88:91]
	v_mfma_f32_16x16x32_bf16 v[92:95], v[114:117], v[222:225], v[92:95]
	v_mfma_f32_16x16x32_bf16 v[64:67], v[110:113], v[182:185], v[64:67]
	v_mfma_f32_16x16x32_bf16 v[68:71], v[118:121], v[182:185], v[68:71]
	v_mfma_f32_16x16x32_bf16 v[72:75], v[110:113], v[190:193], v[72:75]
	v_mfma_f32_16x16x32_bf16 v[76:79], v[118:121], v[190:193], v[76:79]
	v_mfma_f32_16x16x32_bf16 v[80:83], v[110:113], v[218:221], v[80:83]
	v_mfma_f32_16x16x32_bf16 v[84:87], v[118:121], v[218:221], v[84:87]
	v_mfma_f32_16x16x32_bf16 v[88:91], v[110:113], v[226:229], v[88:91]
	v_mfma_f32_16x16x32_bf16 v[92:95], v[118:121], v[226:229], v[92:95]
	s_setprio 0
	s_setprio 1
	v_mfma_f32_16x16x32_bf16 v[32:35], v[166:169], v[174:177], v[32:35]
	v_mfma_f32_16x16x32_bf16 v[36:39], v[122:125], v[186:189], v[36:39]
	v_mfma_f32_16x16x32_bf16 v[40:43], v[166:169], v[186:189], v[40:43]
	v_mfma_f32_16x16x32_bf16 v[44:47], v[122:125], v[214:217], v[44:47]
	v_mfma_f32_16x16x32_bf16 v[48:51], v[166:169], v[214:217], v[48:51]
	v_mfma_f32_16x16x32_bf16 v[52:55], v[122:125], v[222:225], v[52:55]
	v_mfma_f32_16x16x32_bf16 v[56:59], v[166:169], v[222:225], v[56:59]
	v_mfma_f32_16x16x32_bf16 v[98:101], v[122:125], v[174:177], v[98:101]
	v_mfma_f32_16x16x32_bf16 v[32:35], v[170:173], v[182:185], v[32:35]
	v_mfma_f32_16x16x32_bf16 v[36:39], v[126:129], v[190:193], v[36:39]
	v_mfma_f32_16x16x32_bf16 v[40:43], v[170:173], v[190:193], v[40:43]
	v_mfma_f32_16x16x32_bf16 v[44:47], v[126:129], v[218:221], v[44:47]
	v_mfma_f32_16x16x32_bf16 v[48:51], v[170:173], v[218:221], v[48:51]
	v_mfma_f32_16x16x32_bf16 v[52:55], v[126:129], v[226:229], v[52:55]
	v_mfma_f32_16x16x32_bf16 v[56:59], v[170:173], v[226:229], v[56:59]
	v_mfma_f32_16x16x32_bf16 v[230:233], v[126:129], v[182:185], v[98:101]
	s_setprio 0
	s_barrier
	s_mov_b32 m0, s25
	v_lshl_add_u64 v[146:147], s[50:51], 0, v[140:141]
	s_add_u32 s2, s50, 0x10000
	ds_read_b128 v[98:101], v149 offset:16384
	ds_read_b128 v[174:177], v149 offset:17408
	ds_read_b128 v[182:185], v149 offset:18432
	ds_read_b128 v[186:189], v149 offset:19456
	ds_read_b128 v[190:193], v149 offset:20480
	ds_read_b128 v[214:217], v149 offset:21504
	ds_read_b128 v[218:221], v149 offset:22528
	ds_read_b128 v[222:225], v149 offset:23552
	global_load_lds_dwordx4 v[146:147], off
	v_lshl_add_u64 v[194:195], s[50:51], 0, v[144:145]
	s_mov_b32 m0, s3
	s_addc_u32 s3, s51, 0
	global_load_lds_dwordx4 v[194:195], off
	v_lshl_add_u64 v[178:179], s[2:3], 0, v[140:141]
	s_mov_b32 m0, s6
	v_lshl_add_u64 v[198:199], s[58:59], 0, v[138:139]
	global_load_lds_dwordx4 v[178:179], off
	v_lshl_add_u64 v[178:179], s[2:3], 0, v[144:145]
	s_mov_b32 m0, s7
	v_lshl_add_u64 v[200:201], s[58:59], 0, v[142:143]
	global_load_lds_dwordx4 v[178:179], off
	s_mov_b32 m0, s18
	s_nop 0
	global_load_lds_dwordx4 v[198:199], off
	s_mov_b32 m0, s19
	s_nop 0
	global_load_lds_dwordx4 v[200:201], off
	s_waitcnt vmcnt(8)
	s_waitcnt lgkmcnt(0)
	v_mfma_f32_16x16x32_bf16 v[130:133], v[106:109], v[98:101], v[130:133]
	v_mfma_f32_16x16x32_bf16 v[226:229], v[110:113], v[174:177], v[130:133]
	v_mfma_f32_16x16x32_bf16 v[130:133], v[114:117], v[98:101], v[134:137]
	v_mfma_f32_16x16x32_bf16 v[234:237], v[118:121], v[174:177], v[130:133]
	s_barrier
	s_setprio 1
	s_waitcnt lgkmcnt(0)
	v_mfma_f32_16x16x32_bf16 v[130:133], v[106:109], v[182:185], v[150:153]
	v_mfma_f32_16x16x32_bf16 v[150:153], v[110:113], v[186:189], v[130:133]
	v_mfma_f32_16x16x32_bf16 v[130:133], v[114:117], v[182:185], v[154:157]
	v_mfma_f32_16x16x32_bf16 v[154:157], v[118:121], v[186:189], v[130:133]
	v_mfma_f32_16x16x32_bf16 v[130:133], v[106:109], v[190:193], v[158:161]
	v_mfma_f32_16x16x32_bf16 v[0:3], v[106:109], v[218:221], v[0:3]
	v_mfma_f32_16x16x32_bf16 v[4:7], v[114:117], v[218:221], v[4:7]
	v_mfma_f32_16x16x32_bf16 v[158:161], v[110:113], v[214:217], v[130:133]
	v_mfma_f32_16x16x32_bf16 v[130:133], v[114:117], v[190:193], v[162:165]
	v_mfma_f32_16x16x32_bf16 v[0:3], v[110:113], v[222:225], v[0:3]
	v_mfma_f32_16x16x32_bf16 v[4:7], v[118:121], v[222:225], v[4:7]
	v_mfma_f32_16x16x32_bf16 v[162:165], v[118:121], v[214:217], v[130:133]
	s_setprio 0
	s_setprio 1
	v_mfma_f32_16x16x32_bf16 v[8:11], v[122:125], v[98:101], v[8:11]
	v_mfma_f32_16x16x32_bf16 v[12:15], v[166:169], v[98:101], v[12:15]
	v_mfma_f32_16x16x32_bf16 v[24:27], v[122:125], v[182:185], v[24:27]
	v_mfma_f32_16x16x32_bf16 v[28:31], v[166:169], v[182:185], v[28:31]
	v_mfma_f32_16x16x32_bf16 v[60:63], v[122:125], v[190:193], v[60:63]
	v_mfma_f32_16x16x32_bf16 v[16:19], v[122:125], v[218:221], v[16:19]
	v_mfma_f32_16x16x32_bf16 v[8:11], v[126:129], v[174:177], v[8:11]
	v_mfma_f32_16x16x32_bf16 v[12:15], v[170:173], v[174:177], v[12:15]
	v_mfma_f32_16x16x32_bf16 v[24:27], v[126:129], v[186:189], v[24:27]
	v_mfma_f32_16x16x32_bf16 v[28:31], v[170:173], v[186:189], v[28:31]
	v_mfma_f32_16x16x32_bf16 v[106:109], v[126:129], v[214:217], v[60:63]
	v_mfma_f32_16x16x32_bf16 v[60:63], v[166:169], v[190:193], v[102:105]
	v_mfma_f32_16x16x32_bf16 v[174:177], v[126:129], v[222:225], v[16:19]
	v_mfma_f32_16x16x32_bf16 v[16:19], v[166:169], v[218:221], v[20:23]
	v_mfma_f32_16x16x32_bf16 v[110:113], v[170:173], v[214:217], v[60:63]
	v_mfma_f32_16x16x32_bf16 v[166:169], v[170:173], v[222:225], v[16:19]
	s_setprio 0
	s_barrier
	s_nop 3
	ds_read_b128 v[16:19], v204
	ds_read_b128 v[20:23], v204 offset:1024
	ds_read_b128 v[170:173], v204 offset:2048
	ds_read_b128 v[182:185], v204 offset:3072
	ds_read_b128 v[186:189], v205
	ds_read_b128 v[190:193], v205 offset:1024
	ds_read_b128 v[214:217], v205 offset:2048
	ds_read_b128 v[218:221], v205 offset:3072
	s_add_u32 s2, s58, 0x10000
	s_addc_u32 s3, s59, 0
	s_mov_b32 m0, s20
	v_lshl_add_u64 v[98:99], s[2:3], 0, v[138:139]
	ds_read_b128 v[60:63], v149 offset:32768
	ds_read_b128 v[222:225], v149 offset:33792
	ds_read_b128 v[238:241], v149 offset:34816
	ds_read_b128 v[242:245], v149 offset:35840
	ds_read_b128 v[246:249], v149 offset:36864
	ds_read_b128 v[202:205], v149 offset:37888
	ds_read_b128 v[178:181], v149 offset:38912
	ds_read_b128 v[206:209], v149 offset:39936
	global_load_lds_dwordx4 v[98:99], off
	v_lshl_add_u64 v[98:99], s[2:3], 0, v[142:143]
	s_mov_b32 m0, s36
	s_nop 0
	global_load_lds_dwordx4 v[98:99], off
	s_waitcnt vmcnt(8)
	s_waitcnt lgkmcnt(0)
	v_mfma_f32_16x16x32_bf16 v[64:67], v[16:19], v[60:63], v[64:67]
	v_mfma_f32_16x16x32_bf16 v[134:137], v[20:23], v[222:225], v[64:67]
	v_mfma_f32_16x16x32_bf16 v[64:67], v[170:173], v[60:63], v[68:71]
	v_mfma_f32_16x16x32_bf16 v[130:133], v[182:185], v[222:225], v[64:67]
	s_barrier
	s_setprio 1
	s_waitcnt lgkmcnt(0)
	v_mfma_f32_16x16x32_bf16 v[64:67], v[16:19], v[238:241], v[72:75]
	v_mfma_f32_16x16x32_bf16 v[126:129], v[20:23], v[242:245], v[64:67]
	v_mfma_f32_16x16x32_bf16 v[64:67], v[170:173], v[238:241], v[76:79]
	v_mfma_f32_16x16x32_bf16 v[122:125], v[182:185], v[242:245], v[64:67]
	v_mfma_f32_16x16x32_bf16 v[64:67], v[16:19], v[246:249], v[80:83]
	v_mfma_f32_16x16x32_bf16 v[118:121], v[20:23], v[202:205], v[64:67]
	v_mfma_f32_16x16x32_bf16 v[64:67], v[170:173], v[246:249], v[84:87]
	v_mfma_f32_16x16x32_bf16 v[114:117], v[182:185], v[202:205], v[64:67]
	v_mfma_f32_16x16x32_bf16 v[64:67], v[16:19], v[178:181], v[88:91]
	v_mfma_f32_16x16x32_bf16 v[102:105], v[20:23], v[206:209], v[64:67]
	v_mfma_f32_16x16x32_bf16 v[64:67], v[170:173], v[178:181], v[92:95]
	v_mfma_f32_16x16x32_bf16 v[98:101], v[182:185], v[206:209], v[64:67]
	s_setprio 0
	s_setprio 1
	v_mfma_f32_16x16x32_bf16 v[64:67], v[186:189], v[60:63], v[230:233]
	v_mfma_f32_16x16x32_bf16 v[32:35], v[214:217], v[60:63], v[32:35]
	v_mfma_f32_16x16x32_bf16 v[68:71], v[190:193], v[222:225], v[64:67]
	v_mfma_f32_16x16x32_bf16 v[64:67], v[218:221], v[222:225], v[32:35]
	v_mfma_f32_16x16x32_bf16 v[32:35], v[186:189], v[238:241], v[36:39]
	v_mfma_f32_16x16x32_bf16 v[80:83], v[190:193], v[242:245], v[32:35]
	v_mfma_f32_16x16x32_bf16 v[32:35], v[214:217], v[238:241], v[40:43]
	v_mfma_f32_16x16x32_bf16 v[72:75], v[218:221], v[242:245], v[32:35]
	v_mfma_f32_16x16x32_bf16 v[32:35], v[186:189], v[246:249], v[44:47]
	v_mfma_f32_16x16x32_bf16 v[84:87], v[190:193], v[202:205], v[32:35]
	v_mfma_f32_16x16x32_bf16 v[32:35], v[214:217], v[246:249], v[48:51]
	v_mfma_f32_16x16x32_bf16 v[76:79], v[218:221], v[202:205], v[32:35]
	v_mfma_f32_16x16x32_bf16 v[32:35], v[186:189], v[178:181], v[52:55]
	v_mfma_f32_16x16x32_bf16 v[92:95], v[190:193], v[206:209], v[32:35]
	v_mfma_f32_16x16x32_bf16 v[32:35], v[214:217], v[178:181], v[56:59]
	v_mfma_f32_16x16x32_bf16 v[88:91], v[218:221], v[206:209], v[32:35]
	s_setprio 0
	s_barrier
	s_mov_b32 m0, s57
	s_nop 3
	v_lshl_add_u64 v[32:33], v[146:147], 0, s[30:31]
	s_add_u32 s2, s50, 0x10080
	ds_read_b128 v[178:181], v149 offset:49152
	ds_read_b128 v[202:205], v149 offset:50176
	ds_read_b128 v[206:209], v149 offset:51200
	ds_read_b128 v[222:225], v149 offset:52224
	ds_read_b128 v[230:233], v149 offset:53248
	ds_read_b128 v[238:241], v149 offset:54272
	ds_read_b128 v[242:245], v149 offset:55296
	ds_read_b128 v[246:249], v149 offset:56320
	global_load_lds_dwordx4 v[32:33], off
	v_lshl_add_u64 v[32:33], v[194:195], 0, s[30:31]
	s_mov_b32 m0, s35
	s_addc_u32 s3, s51, 0
	global_load_lds_dwordx4 v[32:33], off
	v_lshl_add_u64 v[32:33], s[2:3], 0, v[140:141]
	s_mov_b32 m0, s52
	s_nop 0
	global_load_lds_dwordx4 v[32:33], off
	v_lshl_add_u64 v[32:33], s[2:3], 0, v[144:145]
	s_mov_b32 m0, s53
	s_nop 0
	global_load_lds_dwordx4 v[32:33], off
	v_lshl_add_u64 v[32:33], v[198:199], 0, s[30:31]
	s_mov_b32 m0, s45
	s_nop 0
	global_load_lds_dwordx4 v[32:33], off
	v_lshl_add_u64 v[32:33], v[200:201], 0, s[30:31]
	s_mov_b32 m0, s47
	s_nop 0
	global_load_lds_dwordx4 v[32:33], off
	s_waitcnt vmcnt(8)
	s_waitcnt lgkmcnt(0)
	v_mfma_f32_16x16x32_bf16 v[32:35], v[16:19], v[178:181], v[226:229]
	v_mfma_f32_16x16x32_bf16 v[60:63], v[20:23], v[202:205], v[32:35]
	v_mfma_f32_16x16x32_bf16 v[32:35], v[170:173], v[178:181], v[234:237]
	v_mfma_f32_16x16x32_bf16 v[56:59], v[182:185], v[202:205], v[32:35]
	s_barrier
	s_setprio 1
	s_waitcnt lgkmcnt(0)
	v_mfma_f32_16x16x32_bf16 v[32:35], v[16:19], v[206:209], v[150:153]
	v_mfma_f32_16x16x32_bf16 v[52:55], v[20:23], v[222:225], v[32:35]
	v_mfma_f32_16x16x32_bf16 v[32:35], v[170:173], v[206:209], v[154:157]
	v_mfma_f32_16x16x32_bf16 v[48:51], v[182:185], v[222:225], v[32:35]
	v_mfma_f32_16x16x32_bf16 v[32:35], v[16:19], v[230:233], v[158:161]
	v_mfma_f32_16x16x32_bf16 v[0:3], v[16:19], v[242:245], v[0:3]
	v_mfma_f32_16x16x32_bf16 v[44:47], v[20:23], v[238:241], v[32:35]
	v_mfma_f32_16x16x32_bf16 v[32:35], v[170:173], v[230:233], v[162:165]
	v_mfma_f32_16x16x32_bf16 v[36:39], v[20:23], v[246:249], v[0:3]
	v_mfma_f32_16x16x32_bf16 v[0:3], v[170:173], v[242:245], v[4:7]
	v_mfma_f32_16x16x32_bf16 v[40:43], v[182:185], v[238:241], v[32:35]
	v_mfma_f32_16x16x32_bf16 v[32:35], v[182:185], v[246:249], v[0:3]
	s_setprio 0
	s_setprio 1
	v_mfma_f32_16x16x32_bf16 v[0:3], v[186:189], v[178:181], v[8:11]
	v_mfma_f32_16x16x32_bf16 v[4:7], v[190:193], v[202:205], v[0:3]
	v_mfma_f32_16x16x32_bf16 v[0:3], v[214:217], v[178:181], v[12:15]
	v_mfma_f32_16x16x32_bf16 v[8:11], v[186:189], v[206:209], v[24:27]
	v_mfma_f32_16x16x32_bf16 v[12:15], v[186:189], v[230:233], v[106:109]
	v_mfma_f32_16x16x32_bf16 v[24:27], v[186:189], v[242:245], v[174:177]
	v_mfma_f32_16x16x32_bf16 v[16:19], v[190:193], v[222:225], v[8:11]
	v_mfma_f32_16x16x32_bf16 v[8:11], v[214:217], v[206:209], v[28:31]
	v_mfma_f32_16x16x32_bf16 v[20:23], v[190:193], v[238:241], v[12:15]
	v_mfma_f32_16x16x32_bf16 v[12:15], v[214:217], v[230:233], v[110:113]
	v_mfma_f32_16x16x32_bf16 v[28:31], v[190:193], v[246:249], v[24:27]
	v_mfma_f32_16x16x32_bf16 v[24:27], v[214:217], v[242:245], v[166:169]
	v_mfma_f32_16x16x32_bf16 v[0:3], v[218:221], v[202:205], v[0:3]
	v_mfma_f32_16x16x32_bf16 v[8:11], v[218:221], v[222:225], v[8:11]
	v_mfma_f32_16x16x32_bf16 v[12:15], v[218:221], v[238:241], v[12:15]
	v_mfma_f32_16x16x32_bf16 v[24:27], v[218:221], v[246:249], v[24:27]
	s_setprio 0
	s_barrier
	s_andn2_b64 vcc, exec, s[14:15]
	s_cbranch_vccnz .LBB0_682
	s_barrier

.LBB0_717:
	s_add_u32 s3, s42, 0xfffe0080
	s_addc_u32 s6, s43, -1
	s_add_i32 s7, 0, 0x10000
	s_cmp_eq_u32 s2, 4
	s_cselect_b32 s47, s23, s6
	s_cselect_b32 s46, s51, s3
	v_add_u32_e32 v140, s7, v143
	s_cselect_b32 s45, s15, s54
	s_cselect_b32 s44, s52, s53
	s_add_i32 s3, 0, 0x14000
	ds_read_b128 v[146:149], v140
	ds_read_b128 v[150:153], v140 offset:1024
	ds_read_b128 v[154:157], v140 offset:2048
	ds_read_b128 v[158:161], v140 offset:3072
	v_add_u32_e32 v140, s3, v143
	ds_read_b128 v[162:165], v140
	ds_read_b128 v[166:169], v140 offset:1024
	ds_read_b128 v[170:173], v140 offset:2048
	ds_read_b128 v[174:177], v140 offset:3072
	v_lshl_add_u64 v[140:141], s[42:43], 0, v[136:137]
	s_add_i32 m0, s20, 0xc000
	ds_read_b128 v[178:181], v145
	ds_read_b128 v[182:185], v145 offset:1024
	ds_read_b128 v[186:189], v145 offset:2048
	ds_read_b128 v[190:193], v145 offset:3072
	ds_read_b128 v[202:205], v145 offset:4096
	ds_read_b128 v[206:209], v145 offset:5120
	ds_read_b128 v[214:217], v145 offset:6144
	ds_read_b128 v[218:221], v145 offset:7168
	global_load_lds_dwordx4 v[140:141], off
	v_lshl_add_u64 v[140:141], s[42:43], 0, v[138:139]
	s_add_i32 m0, s20, 0xe000
	s_nop 0
	global_load_lds_dwordx4 v[140:141], off
	s_waitcnt vmcnt(8)
	s_waitcnt lgkmcnt(0)
	v_mfma_f32_16x16x32_bf16 v[126:129], v[146:149], v[178:181], v[126:129]
	v_mfma_f32_16x16x32_bf16 v[122:125], v[154:157], v[178:181], v[122:125]
	v_mfma_f32_16x16x32_bf16 v[118:121], v[146:149], v[186:189], v[118:121]
	v_mfma_f32_16x16x32_bf16 v[110:113], v[154:157], v[186:189], v[110:113]
	s_barrier
	s_setprio 1
	s_waitcnt lgkmcnt(0)
	v_mfma_f32_16x16x32_bf16 v[102:105], v[146:149], v[202:205], v[102:105]
	v_mfma_f32_16x16x32_bf16 v[92:95], v[154:157], v[202:205], v[92:95]
	v_mfma_f32_16x16x32_bf16 v[84:87], v[146:149], v[214:217], v[84:87]
	v_mfma_f32_16x16x32_bf16 v[76:79], v[154:157], v[214:217], v[76:79]
	v_mfma_f32_16x16x32_bf16 v[126:129], v[150:153], v[182:185], v[126:129]
	v_mfma_f32_16x16x32_bf16 v[122:125], v[158:161], v[182:185], v[122:125]
	v_mfma_f32_16x16x32_bf16 v[118:121], v[150:153], v[190:193], v[118:121]
	v_mfma_f32_16x16x32_bf16 v[110:113], v[158:161], v[190:193], v[110:113]
	v_mfma_f32_16x16x32_bf16 v[102:105], v[150:153], v[206:209], v[102:105]
	v_mfma_f32_16x16x32_bf16 v[92:95], v[158:161], v[206:209], v[92:95]
	v_mfma_f32_16x16x32_bf16 v[84:87], v[150:153], v[218:221], v[84:87]
	v_mfma_f32_16x16x32_bf16 v[76:79], v[158:161], v[218:221], v[76:79]
	s_setprio 0
	s_setprio 1
	v_mfma_f32_16x16x32_bf16 v[114:117], v[162:165], v[178:181], v[114:117]
	v_mfma_f32_16x16x32_bf16 v[106:109], v[170:173], v[178:181], v[106:109]
	v_mfma_f32_16x16x32_bf16 v[98:101], v[162:165], v[186:189], v[98:101]
	v_mfma_f32_16x16x32_bf16 v[88:91], v[170:173], v[186:189], v[88:91]
	v_mfma_f32_16x16x32_bf16 v[80:83], v[162:165], v[202:205], v[80:83]
	v_mfma_f32_16x16x32_bf16 v[72:75], v[170:173], v[202:205], v[72:75]
	v_mfma_f32_16x16x32_bf16 v[68:71], v[162:165], v[214:217], v[68:71]
	v_mfma_f32_16x16x32_bf16 v[64:67], v[170:173], v[214:217], v[64:67]
	v_mfma_f32_16x16x32_bf16 v[114:117], v[166:169], v[182:185], v[114:117]
	v_mfma_f32_16x16x32_bf16 v[106:109], v[174:177], v[182:185], v[106:109]
	v_mfma_f32_16x16x32_bf16 v[98:101], v[166:169], v[190:193], v[98:101]
	v_mfma_f32_16x16x32_bf16 v[88:91], v[174:177], v[190:193], v[88:91]
	v_mfma_f32_16x16x32_bf16 v[80:83], v[166:169], v[206:209], v[80:83]
	v_mfma_f32_16x16x32_bf16 v[72:75], v[174:177], v[206:209], v[72:75]
	v_mfma_f32_16x16x32_bf16 v[68:71], v[166:169], v[218:221], v[68:71]
	v_mfma_f32_16x16x32_bf16 v[64:67], v[174:177], v[218:221], v[64:67]
	s_setprio 0
	s_barrier
	s_add_i32 s6, s7, s4
	v_lshl_add_u64 v[140:141], s[44:45], 0, v[96:97]
	s_mov_b32 m0, s6
	ds_read_b128 v[178:181], v145 offset:16384
	ds_read_b128 v[182:185], v145 offset:17408
	ds_read_b128 v[186:189], v145 offset:18432
	ds_read_b128 v[190:193], v145 offset:19456
	ds_read_b128 v[202:205], v145 offset:20480
	ds_read_b128 v[206:209], v145 offset:21504
	ds_read_b128 v[214:217], v145 offset:22528
	ds_read_b128 v[218:221], v145 offset:23552
	global_load_lds_dwordx4 v[140:141], off
	s_add_i32 m0, s6, 0x2000
	s_add_u32 s6, s44, 0x20000
	v_lshl_add_u64 v[194:195], s[44:45], 0, v[134:135]
	s_addc_u32 s7, s45, 0
	s_add_i32 s3, s3, s4
	global_load_lds_dwordx4 v[194:195], off
	v_lshl_add_u64 v[198:199], s[6:7], 0, v[96:97]
	s_mov_b32 m0, s3
	v_lshl_add_u64 v[200:201], s[46:47], 0, v[132:133]
	global_load_lds_dwordx4 v[198:199], off
	v_lshl_add_u64 v[198:199], s[6:7], 0, v[134:135]
	s_add_i32 m0, s3, 0x2000
	s_nop 0
	global_load_lds_dwordx4 v[198:199], off
	v_lshl_add_u64 v[198:199], s[46:47], 0, v[130:131]
	s_mov_b32 m0, s20
	s_nop 0
	global_load_lds_dwordx4 v[198:199], off
	s_mov_b32 m0, s25
	s_nop 0
	global_load_lds_dwordx4 v[200:201], off
	s_waitcnt vmcnt(8)
	s_waitcnt lgkmcnt(0)
	v_mfma_f32_16x16x32_bf16 v[60:63], v[146:149], v[178:181], v[60:63]
	v_mfma_f32_16x16x32_bf16 v[56:59], v[154:157], v[178:181], v[56:59]
	v_mfma_f32_16x16x32_bf16 v[52:55], v[146:149], v[186:189], v[52:55]
	v_mfma_f32_16x16x32_bf16 v[44:47], v[154:157], v[186:189], v[44:47]
	s_barrier
	s_setprio 1
	s_waitcnt lgkmcnt(0)
	v_mfma_f32_16x16x32_bf16 v[36:39], v[146:149], v[202:205], v[36:39]
	v_mfma_f32_16x16x32_bf16 v[28:31], v[154:157], v[202:205], v[28:31]
	v_mfma_f32_16x16x32_bf16 v[20:23], v[146:149], v[214:217], v[20:23]
	v_mfma_f32_16x16x32_bf16 v[12:15], v[154:157], v[214:217], v[12:15]
	v_mfma_f32_16x16x32_bf16 v[60:63], v[150:153], v[182:185], v[60:63]
	v_mfma_f32_16x16x32_bf16 v[56:59], v[158:161], v[182:185], v[56:59]
	v_mfma_f32_16x16x32_bf16 v[52:55], v[150:153], v[190:193], v[52:55]
	v_mfma_f32_16x16x32_bf16 v[44:47], v[158:161], v[190:193], v[44:47]
	v_mfma_f32_16x16x32_bf16 v[36:39], v[150:153], v[206:209], v[36:39]
	v_mfma_f32_16x16x32_bf16 v[28:31], v[158:161], v[206:209], v[28:31]
	v_mfma_f32_16x16x32_bf16 v[20:23], v[150:153], v[218:221], v[20:23]
	v_mfma_f32_16x16x32_bf16 v[12:15], v[158:161], v[218:221], v[12:15]
	s_setprio 0
	s_setprio 1
	v_mfma_f32_16x16x32_bf16 v[48:51], v[162:165], v[178:181], v[48:51]
	v_mfma_f32_16x16x32_bf16 v[40:43], v[170:173], v[178:181], v[40:43]
	v_mfma_f32_16x16x32_bf16 v[32:35], v[162:165], v[186:189], v[32:35]
	v_mfma_f32_16x16x32_bf16 v[24:27], v[170:173], v[186:189], v[24:27]
	v_mfma_f32_16x16x32_bf16 v[16:19], v[162:165], v[202:205], v[16:19]
	v_mfma_f32_16x16x32_bf16 v[8:11], v[170:173], v[202:205], v[8:11]
	v_mfma_f32_16x16x32_bf16 v[4:7], v[162:165], v[214:217], v[4:7]
	v_mfma_f32_16x16x32_bf16 v[0:3], v[170:173], v[214:217], v[0:3]
	v_mfma_f32_16x16x32_bf16 v[48:51], v[166:169], v[182:185], v[48:51]
	v_mfma_f32_16x16x32_bf16 v[40:43], v[174:177], v[182:185], v[40:43]
	v_mfma_f32_16x16x32_bf16 v[32:35], v[166:169], v[190:193], v[32:35]
	v_mfma_f32_16x16x32_bf16 v[24:27], v[174:177], v[190:193], v[24:27]
	v_mfma_f32_16x16x32_bf16 v[16:19], v[166:169], v[206:209], v[16:19]
	v_mfma_f32_16x16x32_bf16 v[8:11], v[174:177], v[206:209], v[8:11]
	v_mfma_f32_16x16x32_bf16 v[4:7], v[166:169], v[218:221], v[4:7]
	v_mfma_f32_16x16x32_bf16 v[0:3], v[174:177], v[218:221], v[0:3]
	s_setprio 0
	s_barrier
	s_add_i32 s3, 0, 0x18000
	s_add_i32 s55, 0, 0x1c000
	v_add_u32_e32 v158, s3, v143
	v_add_u32_e32 v174, s55, v143
	ds_read_b128 v[146:149], v158
	ds_read_b128 v[150:153], v158 offset:1024
	ds_read_b128 v[154:157], v158 offset:2048
	ds_read_b128 v[158:161], v158 offset:3072
	ds_read_b128 v[162:165], v174
	ds_read_b128 v[166:169], v174 offset:1024
	ds_read_b128 v[170:173], v174 offset:2048
	ds_read_b128 v[174:177], v174 offset:3072
	s_add_u32 s6, s46, 0x20000
	s_addc_u32 s7, s47, 0
	s_mov_b32 m0, s36
	v_lshl_add_u64 v[222:223], s[6:7], 0, v[130:131]
	ds_read_b128 v[178:181], v145 offset:32768
	ds_read_b128 v[182:185], v145 offset:33792
	ds_read_b128 v[186:189], v145 offset:34816
	ds_read_b128 v[190:193], v145 offset:35840
	ds_read_b128 v[202:205], v145 offset:36864
	ds_read_b128 v[206:209], v145 offset:37888
	ds_read_b128 v[214:217], v145 offset:38912
	ds_read_b128 v[218:221], v145 offset:39936
	global_load_lds_dwordx4 v[222:223], off
	v_lshl_add_u64 v[222:223], s[6:7], 0, v[132:133]
	s_mov_b32 m0, s37
	s_nop 0
	global_load_lds_dwordx4 v[222:223], off
	s_waitcnt vmcnt(8)
	s_waitcnt lgkmcnt(0)
	v_mfma_f32_16x16x32_bf16 v[126:129], v[146:149], v[178:181], v[126:129]
	v_mfma_f32_16x16x32_bf16 v[122:125], v[154:157], v[178:181], v[122:125]
	v_mfma_f32_16x16x32_bf16 v[118:121], v[146:149], v[186:189], v[118:121]
	v_mfma_f32_16x16x32_bf16 v[110:113], v[154:157], v[186:189], v[110:113]
	s_barrier
	s_setprio 1
	s_waitcnt lgkmcnt(0)
	v_mfma_f32_16x16x32_bf16 v[102:105], v[146:149], v[202:205], v[102:105]
	v_mfma_f32_16x16x32_bf16 v[92:95], v[154:157], v[202:205], v[92:95]
	v_mfma_f32_16x16x32_bf16 v[84:87], v[146:149], v[214:217], v[84:87]
	v_mfma_f32_16x16x32_bf16 v[76:79], v[154:157], v[214:217], v[76:79]
	v_mfma_f32_16x16x32_bf16 v[126:129], v[150:153], v[182:185], v[126:129]
	v_mfma_f32_16x16x32_bf16 v[122:125], v[158:161], v[182:185], v[122:125]
	v_mfma_f32_16x16x32_bf16 v[118:121], v[150:153], v[190:193], v[118:121]
	v_mfma_f32_16x16x32_bf16 v[110:113], v[158:161], v[190:193], v[110:113]
	v_mfma_f32_16x16x32_bf16 v[102:105], v[150:153], v[206:209], v[102:105]
	v_mfma_f32_16x16x32_bf16 v[92:95], v[158:161], v[206:209], v[92:95]
	v_mfma_f32_16x16x32_bf16 v[84:87], v[150:153], v[218:221], v[84:87]
	v_mfma_f32_16x16x32_bf16 v[76:79], v[158:161], v[218:221], v[76:79]
	s_setprio 0
	s_setprio 1
	v_mfma_f32_16x16x32_bf16 v[114:117], v[162:165], v[178:181], v[114:117]
	v_mfma_f32_16x16x32_bf16 v[106:109], v[170:173], v[178:181], v[106:109]
	v_mfma_f32_16x16x32_bf16 v[98:101], v[162:165], v[186:189], v[98:101]
	v_mfma_f32_16x16x32_bf16 v[88:91], v[170:173], v[186:189], v[88:91]
	v_mfma_f32_16x16x32_bf16 v[80:83], v[162:165], v[202:205], v[80:83]
	v_mfma_f32_16x16x32_bf16 v[72:75], v[170:173], v[202:205], v[72:75]
	v_mfma_f32_16x16x32_bf16 v[68:71], v[162:165], v[214:217], v[68:71]
	v_mfma_f32_16x16x32_bf16 v[64:67], v[170:173], v[214:217], v[64:67]
	v_mfma_f32_16x16x32_bf16 v[114:117], v[166:169], v[182:185], v[114:117]
	v_mfma_f32_16x16x32_bf16 v[106:109], v[174:177], v[182:185], v[106:109]
	v_mfma_f32_16x16x32_bf16 v[98:101], v[166:169], v[190:193], v[98:101]
	v_mfma_f32_16x16x32_bf16 v[88:91], v[174:177], v[190:193], v[88:91]
	v_mfma_f32_16x16x32_bf16 v[80:83], v[166:169], v[206:209], v[80:83]
	v_mfma_f32_16x16x32_bf16 v[72:75], v[174:177], v[206:209], v[72:75]
	v_mfma_f32_16x16x32_bf16 v[68:71], v[166:169], v[218:221], v[68:71]
	v_mfma_f32_16x16x32_bf16 v[64:67], v[174:177], v[218:221], v[64:67]
	s_setprio 0
	s_barrier
	s_add_i32 s3, s3, s4
	v_lshl_add_u64 v[140:141], v[140:141], 0, s[30:31]
	s_mov_b32 m0, s3
	ds_read_b128 v[178:181], v145 offset:49152
	ds_read_b128 v[182:185], v145 offset:50176
	ds_read_b128 v[186:189], v145 offset:51200
	ds_read_b128 v[190:193], v145 offset:52224
	ds_read_b128 v[202:205], v145 offset:53248
	ds_read_b128 v[206:209], v145 offset:54272
	ds_read_b128 v[214:217], v145 offset:55296
	ds_read_b128 v[218:221], v145 offset:56320
	global_load_lds_dwordx4 v[140:141], off
	s_add_i32 m0, s3, 0x2000
	s_add_u32 s6, s44, 0x20080
	v_lshl_add_u64 v[140:141], v[194:195], 0, s[30:31]
	s_addc_u32 s7, s45, 0
	s_add_i32 s3, s55, s4
	global_load_lds_dwordx4 v[140:141], off
	v_lshl_add_u64 v[140:141], s[6:7], 0, v[96:97]
	s_mov_b32 m0, s3
	s_nop 0
	global_load_lds_dwordx4 v[140:141], off
	v_lshl_add_u64 v[140:141], s[6:7], 0, v[134:135]
	s_add_i32 m0, s3, 0x2000
	s_nop 0
	global_load_lds_dwordx4 v[140:141], off
	v_lshl_add_u64 v[140:141], v[198:199], 0, s[30:31]
	s_mov_b32 m0, s40
	s_nop 0
	global_load_lds_dwordx4 v[140:141], off
	v_lshl_add_u64 v[140:141], v[200:201], 0, s[30:31]
	s_mov_b32 m0, s48
	s_nop 0
	global_load_lds_dwordx4 v[140:141], off
	s_waitcnt vmcnt(8)
	s_waitcnt lgkmcnt(0)
	v_mfma_f32_16x16x32_bf16 v[60:63], v[146:149], v[178:181], v[60:63]
	v_mfma_f32_16x16x32_bf16 v[56:59], v[154:157], v[178:181], v[56:59]
	v_mfma_f32_16x16x32_bf16 v[52:55], v[146:149], v[186:189], v[52:55]
	v_mfma_f32_16x16x32_bf16 v[44:47], v[154:157], v[186:189], v[44:47]
	s_barrier
	s_setprio 1
	s_waitcnt lgkmcnt(0)
	v_mfma_f32_16x16x32_bf16 v[36:39], v[146:149], v[202:205], v[36:39]
	v_mfma_f32_16x16x32_bf16 v[28:31], v[154:157], v[202:205], v[28:31]
	v_mfma_f32_16x16x32_bf16 v[20:23], v[146:149], v[214:217], v[20:23]
	v_mfma_f32_16x16x32_bf16 v[12:15], v[154:157], v[214:217], v[12:15]
	v_mfma_f32_16x16x32_bf16 v[60:63], v[150:153], v[182:185], v[60:63]
	v_mfma_f32_16x16x32_bf16 v[56:59], v[158:161], v[182:185], v[56:59]
	v_mfma_f32_16x16x32_bf16 v[52:55], v[150:153], v[190:193], v[52:55]
	v_mfma_f32_16x16x32_bf16 v[44:47], v[158:161], v[190:193], v[44:47]
	v_mfma_f32_16x16x32_bf16 v[36:39], v[150:153], v[206:209], v[36:39]
	v_mfma_f32_16x16x32_bf16 v[28:31], v[158:161], v[206:209], v[28:31]
	v_mfma_f32_16x16x32_bf16 v[20:23], v[150:153], v[218:221], v[20:23]
	v_mfma_f32_16x16x32_bf16 v[12:15], v[158:161], v[218:221], v[12:15]
	s_setprio 0
	s_setprio 1
	v_mfma_f32_16x16x32_bf16 v[48:51], v[162:165], v[178:181], v[48:51]
	v_mfma_f32_16x16x32_bf16 v[40:43], v[170:173], v[178:181], v[40:43]
	v_mfma_f32_16x16x32_bf16 v[32:35], v[162:165], v[186:189], v[32:35]
	v_mfma_f32_16x16x32_bf16 v[24:27], v[170:173], v[186:189], v[24:27]
	v_mfma_f32_16x16x32_bf16 v[16:19], v[162:165], v[202:205], v[16:19]
	v_mfma_f32_16x16x32_bf16 v[8:11], v[170:173], v[202:205], v[8:11]
	v_mfma_f32_16x16x32_bf16 v[4:7], v[162:165], v[214:217], v[4:7]
	v_mfma_f32_16x16x32_bf16 v[0:3], v[170:173], v[214:217], v[0:3]
	v_mfma_f32_16x16x32_bf16 v[48:51], v[166:169], v[182:185], v[48:51]
	v_mfma_f32_16x16x32_bf16 v[40:43], v[174:177], v[182:185], v[40:43]
	v_mfma_f32_16x16x32_bf16 v[32:35], v[166:169], v[190:193], v[32:35]
	v_mfma_f32_16x16x32_bf16 v[24:27], v[174:177], v[190:193], v[24:27]
	v_mfma_f32_16x16x32_bf16 v[16:19], v[166:169], v[206:209], v[16:19]
	v_mfma_f32_16x16x32_bf16 v[8:11], v[174:177], v[206:209], v[8:11]
	v_mfma_f32_16x16x32_bf16 v[4:7], v[166:169], v[218:221], v[4:7]
	v_mfma_f32_16x16x32_bf16 v[0:3], v[174:177], v[218:221], v[0:3]
	s_setprio 0
	s_barrier
	s_add_i32 s2, s2, 2
	s_add_u32 s42, s42, 0x100
	s_addc_u32 s43, s43, 0
	s_add_u32 s53, s53, 0x100
	s_addc_u32 s54, s54, 0
	s_cmp_gt_u32 s2, 5
	s_cbranch_scc0 .LBB0_717
	v_readlane_b32 s54, v254, 56
	s_and_b64 vcc, exec, s[10:11]
	v_readlane_b32 s55, v254, 57
	s_cbranch_vccz .LBB0_720
	s_barrier

.LBB0_973:
	s_add_u32 s6, s34, s2
	s_addc_u32 s13, s35, 0
	s_add_u32 s3, s6, 0x100
	s_addc_u32 s23, s13, 0
	s_and_b64 s[36:37], s[60:61], exec
	s_cselect_b32 s73, s43, s23
	s_cselect_b32 s72, s42, s3
	s_add_u32 s2, s24, s2
	s_addc_u32 s3, s25, 0
	s_add_u32 s23, s2, 0x100
	s_addc_u32 s36, s3, 0
	s_add_i32 s47, 0, 0x10000
	s_and_b64 s[2:3], s[60:61], exec
	s_cselect_b32 s75, s53, s36
	s_cselect_b32 s74, s52, s23
	s_add_i32 s49, 0, 0x14000
	s_add_u32 s86, s6, 0x80080
	s_addc_u32 s87, s13, 0
	s_add_i32 s40, s47, s4
	s_add_i32 m0, s5, 0xc000
	s_add_i32 s51, s5, 0xe000
	s_add_i32 s23, s40, 0x2000
	s_add_u32 s82, s74, 0x80000
	v_add_u32_e32 v148, s47, v132
	v_add_u32_e32 v164, s49, v132
	s_addc_u32 s83, s75, 0
	s_add_i32 s37, s49, s4
	ds_read_b128 v[136:139], v148
	ds_read_b128 v[140:143], v148 offset:1024
	ds_read_b128 v[144:147], v148 offset:2048
	ds_read_b128 v[148:151], v148 offset:3072
	ds_read_b128 v[152:155], v164
	ds_read_b128 v[156:159], v164 offset:1024
	ds_read_b128 v[160:163], v164 offset:2048
	ds_read_b128 v[164:167], v164 offset:3072
	s_add_i32 s36, s37, 0x2000
	s_add_i32 s13, 0, 0x18000
	s_add_i32 s6, 0, 0x1c000
	s_add_u32 s62, s72, 0x80000
	s_addc_u32 s63, s73, 0
	s_add_i32 s3, s13, s4
	s_add_i32 s2, s3, 0x2000
	s_add_u32 s60, s74, 0x80080
	s_addc_u32 s61, s75, 0
	s_add_i32 s49, s6, s4
	s_add_i32 s47, s49, 0x2000
	v_lshl_add_u64 v[198:199], s[86:87], 0, v[96:97]
	ds_read_b128 v[168:171], v135
	ds_read_b128 v[172:175], v135 offset:1024
	ds_read_b128 v[176:179], v135 offset:2048
	ds_read_b128 v[180:183], v135 offset:3072
	ds_read_b128 v[184:187], v135 offset:4096
	ds_read_b128 v[188:191], v135 offset:5120
	ds_read_b128 v[192:195], v135 offset:6144
	ds_read_b128 v[202:205], v135 offset:7168
	global_load_lds_dwordx4 v[198:199], off
	v_lshl_add_u64 v[198:199], s[86:87], 0, v[130:131]
	s_mov_b32 m0, s51
	s_nop 0
	global_load_lds_dwordx4 v[198:199], off
	s_waitcnt vmcnt(8)
	s_waitcnt lgkmcnt(0)
	v_mfma_f32_16x16x32_bf16 v[126:129], v[136:139], v[168:171], v[126:129]
	v_mfma_f32_16x16x32_bf16 v[122:125], v[144:147], v[168:171], v[122:125]
	v_mfma_f32_16x16x32_bf16 v[118:121], v[136:139], v[176:179], v[118:121]
	v_mfma_f32_16x16x32_bf16 v[114:117], v[144:147], v[176:179], v[114:117]
	s_barrier
	s_setprio 1
	s_waitcnt lgkmcnt(0)
	v_mfma_f32_16x16x32_bf16 v[106:109], v[136:139], v[184:187], v[106:109]
	v_mfma_f32_16x16x32_bf16 v[98:101], v[144:147], v[184:187], v[98:101]
	v_mfma_f32_16x16x32_bf16 v[88:91], v[136:139], v[192:195], v[88:91]
	v_mfma_f32_16x16x32_bf16 v[80:83], v[144:147], v[192:195], v[80:83]
	v_mfma_f32_16x16x32_bf16 v[126:129], v[140:143], v[172:175], v[126:129]
	v_mfma_f32_16x16x32_bf16 v[122:125], v[148:151], v[172:175], v[122:125]
	v_mfma_f32_16x16x32_bf16 v[118:121], v[140:143], v[180:183], v[118:121]
	v_mfma_f32_16x16x32_bf16 v[114:117], v[148:151], v[180:183], v[114:117]
	v_mfma_f32_16x16x32_bf16 v[106:109], v[140:143], v[188:191], v[106:109]
	v_mfma_f32_16x16x32_bf16 v[98:101], v[148:151], v[188:191], v[98:101]
	v_mfma_f32_16x16x32_bf16 v[88:91], v[140:143], v[202:205], v[88:91]
	v_mfma_f32_16x16x32_bf16 v[80:83], v[148:151], v[202:205], v[80:83]
	s_setprio 0
	s_setprio 1
	v_mfma_f32_16x16x32_bf16 v[110:113], v[152:155], v[168:171], v[110:113]
	v_mfma_f32_16x16x32_bf16 v[102:105], v[160:163], v[168:171], v[102:105]
	v_mfma_f32_16x16x32_bf16 v[92:95], v[152:155], v[176:179], v[92:95]
	v_mfma_f32_16x16x32_bf16 v[84:87], v[160:163], v[176:179], v[84:87]
	v_mfma_f32_16x16x32_bf16 v[76:79], v[152:155], v[184:187], v[76:79]
	v_mfma_f32_16x16x32_bf16 v[72:75], v[160:163], v[184:187], v[72:75]
	v_mfma_f32_16x16x32_bf16 v[68:71], v[152:155], v[192:195], v[68:71]
	v_mfma_f32_16x16x32_bf16 v[64:67], v[160:163], v[192:195], v[64:67]
	v_mfma_f32_16x16x32_bf16 v[110:113], v[156:159], v[172:175], v[110:113]
	v_mfma_f32_16x16x32_bf16 v[102:105], v[164:167], v[172:175], v[102:105]
	v_mfma_f32_16x16x32_bf16 v[92:95], v[156:159], v[180:183], v[92:95]
	v_mfma_f32_16x16x32_bf16 v[84:87], v[164:167], v[180:183], v[84:87]
	v_mfma_f32_16x16x32_bf16 v[76:79], v[156:159], v[188:191], v[76:79]
	v_mfma_f32_16x16x32_bf16 v[72:75], v[164:167], v[188:191], v[72:75]
	v_mfma_f32_16x16x32_bf16 v[68:71], v[156:159], v[202:205], v[68:71]
	v_mfma_f32_16x16x32_bf16 v[64:67], v[164:167], v[202:205], v[64:67]
	s_setprio 0
	s_barrier
	s_mov_b32 m0, s40
	v_lshl_add_u64 v[198:199], s[74:75], 0, v[96:97]
	ds_read_b128 v[168:171], v135 offset:16384
	ds_read_b128 v[172:175], v135 offset:17408
	ds_read_b128 v[176:179], v135 offset:18432
	ds_read_b128 v[180:183], v135 offset:19456
	ds_read_b128 v[184:187], v135 offset:20480
	ds_read_b128 v[188:191], v135 offset:21504
	ds_read_b128 v[192:195], v135 offset:22528
	ds_read_b128 v[202:205], v135 offset:23552
	global_load_lds_dwordx4 v[198:199], off
	v_lshl_add_u64 v[200:201], s[74:75], 0, v[130:131]
	s_mov_b32 m0, s23
	v_lshl_add_u64 v[206:207], s[82:83], 0, v[96:97]
	global_load_lds_dwordx4 v[200:201], off
	s_mov_b32 m0, s37
	v_lshl_add_u64 v[208:209], s[72:73], 0, v[130:131]
	global_load_lds_dwordx4 v[206:207], off
	v_lshl_add_u64 v[206:207], s[82:83], 0, v[130:131]
	s_mov_b32 m0, s36
	s_nop 0
	global_load_lds_dwordx4 v[206:207], off
	v_lshl_add_u64 v[206:207], s[72:73], 0, v[96:97]
	s_mov_b32 m0, s5
	s_nop 0
	global_load_lds_dwordx4 v[206:207], off
	s_mov_b32 m0, s7
	s_nop 0
	global_load_lds_dwordx4 v[208:209], off
	s_waitcnt vmcnt(8)
	s_waitcnt lgkmcnt(0)
	v_mfma_f32_16x16x32_bf16 v[60:63], v[136:139], v[168:171], v[60:63]
	v_mfma_f32_16x16x32_bf16 v[56:59], v[144:147], v[168:171], v[56:59]
	v_mfma_f32_16x16x32_bf16 v[52:55], v[136:139], v[176:179], v[52:55]
	v_mfma_f32_16x16x32_bf16 v[48:51], v[144:147], v[176:179], v[48:51]
	s_barrier
	s_setprio 1
	s_waitcnt lgkmcnt(0)
	v_mfma_f32_16x16x32_bf16 v[36:39], v[136:139], v[184:187], v[36:39]
	v_mfma_f32_16x16x32_bf16 v[32:35], v[144:147], v[184:187], v[32:35]
	v_mfma_f32_16x16x32_bf16 v[20:23], v[136:139], v[192:195], v[20:23]
	v_mfma_f32_16x16x32_bf16 v[16:19], v[144:147], v[192:195], v[16:19]
	v_mfma_f32_16x16x32_bf16 v[60:63], v[140:143], v[172:175], v[60:63]
	v_mfma_f32_16x16x32_bf16 v[56:59], v[148:151], v[172:175], v[56:59]
	v_mfma_f32_16x16x32_bf16 v[52:55], v[140:143], v[180:183], v[52:55]
	v_mfma_f32_16x16x32_bf16 v[48:51], v[148:151], v[180:183], v[48:51]
	v_mfma_f32_16x16x32_bf16 v[36:39], v[140:143], v[188:191], v[36:39]
	v_mfma_f32_16x16x32_bf16 v[32:35], v[148:151], v[188:191], v[32:35]
	v_mfma_f32_16x16x32_bf16 v[20:23], v[140:143], v[202:205], v[20:23]
	v_mfma_f32_16x16x32_bf16 v[16:19], v[148:151], v[202:205], v[16:19]
	s_setprio 0
	s_setprio 1
	v_mfma_f32_16x16x32_bf16 v[44:47], v[152:155], v[168:171], v[44:47]
	v_mfma_f32_16x16x32_bf16 v[40:43], v[160:163], v[168:171], v[40:43]
	v_mfma_f32_16x16x32_bf16 v[28:31], v[152:155], v[176:179], v[28:31]
	v_mfma_f32_16x16x32_bf16 v[24:27], v[160:163], v[176:179], v[24:27]
	v_mfma_f32_16x16x32_bf16 v[12:15], v[152:155], v[184:187], v[12:15]
	v_mfma_f32_16x16x32_bf16 v[8:11], v[160:163], v[184:187], v[8:11]
	v_mfma_f32_16x16x32_bf16 v[4:7], v[152:155], v[192:195], v[4:7]
	v_mfma_f32_16x16x32_bf16 v[0:3], v[160:163], v[192:195], v[0:3]
	v_mfma_f32_16x16x32_bf16 v[44:47], v[156:159], v[172:175], v[44:47]
	v_mfma_f32_16x16x32_bf16 v[40:43], v[164:167], v[172:175], v[40:43]
	v_mfma_f32_16x16x32_bf16 v[28:31], v[156:159], v[180:183], v[28:31]
	v_mfma_f32_16x16x32_bf16 v[24:27], v[164:167], v[180:183], v[24:27]
	v_mfma_f32_16x16x32_bf16 v[12:15], v[156:159], v[188:191], v[12:15]
	v_mfma_f32_16x16x32_bf16 v[8:11], v[164:167], v[188:191], v[8:11]
	v_mfma_f32_16x16x32_bf16 v[4:7], v[156:159], v[202:205], v[4:7]
	v_mfma_f32_16x16x32_bf16 v[0:3], v[164:167], v[202:205], v[0:3]
	s_setprio 0
	s_barrier
	v_add_u32_e32 v148, s13, v132
	v_add_u32_e32 v164, s6, v132
	ds_read_b128 v[136:139], v148
	ds_read_b128 v[140:143], v148 offset:1024
	ds_read_b128 v[144:147], v148 offset:2048
	ds_read_b128 v[148:151], v148 offset:3072
	ds_read_b128 v[152:155], v164
	ds_read_b128 v[156:159], v164 offset:1024
	ds_read_b128 v[160:163], v164 offset:2048
	ds_read_b128 v[164:167], v164 offset:3072
	s_mov_b32 m0, s15
	v_lshl_add_u64 v[214:215], s[62:63], 0, v[96:97]
	ds_read_b128 v[168:171], v135 offset:32768
	ds_read_b128 v[172:175], v135 offset:33792
	ds_read_b128 v[176:179], v135 offset:34816
	ds_read_b128 v[180:183], v135 offset:35840
	ds_read_b128 v[184:187], v135 offset:36864
	ds_read_b128 v[188:191], v135 offset:37888
	ds_read_b128 v[192:195], v135 offset:38912
	ds_read_b128 v[202:205], v135 offset:39936
	global_load_lds_dwordx4 v[214:215], off
	v_lshl_add_u64 v[214:215], s[62:63], 0, v[130:131]
	s_mov_b32 m0, s17
	s_nop 0
	global_load_lds_dwordx4 v[214:215], off
	s_waitcnt vmcnt(8)
	s_waitcnt lgkmcnt(0)
	v_mfma_f32_16x16x32_bf16 v[126:129], v[136:139], v[168:171], v[126:129]
	v_mfma_f32_16x16x32_bf16 v[122:125], v[144:147], v[168:171], v[122:125]
	v_mfma_f32_16x16x32_bf16 v[118:121], v[136:139], v[176:179], v[118:121]
	v_mfma_f32_16x16x32_bf16 v[114:117], v[144:147], v[176:179], v[114:117]
	s_barrier
	s_setprio 1
	s_waitcnt lgkmcnt(0)
	v_mfma_f32_16x16x32_bf16 v[106:109], v[136:139], v[184:187], v[106:109]
	v_mfma_f32_16x16x32_bf16 v[98:101], v[144:147], v[184:187], v[98:101]
	v_mfma_f32_16x16x32_bf16 v[88:91], v[136:139], v[192:195], v[88:91]
	v_mfma_f32_16x16x32_bf16 v[80:83], v[144:147], v[192:195], v[80:83]
	v_mfma_f32_16x16x32_bf16 v[126:129], v[140:143], v[172:175], v[126:129]
	v_mfma_f32_16x16x32_bf16 v[122:125], v[148:151], v[172:175], v[122:125]
	v_mfma_f32_16x16x32_bf16 v[118:121], v[140:143], v[180:183], v[118:121]
	v_mfma_f32_16x16x32_bf16 v[114:117], v[148:151], v[180:183], v[114:117]
	v_mfma_f32_16x16x32_bf16 v[106:109], v[140:143], v[188:191], v[106:109]
	v_mfma_f32_16x16x32_bf16 v[98:101], v[148:151], v[188:191], v[98:101]
	v_mfma_f32_16x16x32_bf16 v[88:91], v[140:143], v[202:205], v[88:91]
	v_mfma_f32_16x16x32_bf16 v[80:83], v[148:151], v[202:205], v[80:83]
	s_setprio 0
	s_setprio 1
	v_mfma_f32_16x16x32_bf16 v[110:113], v[152:155], v[168:171], v[110:113]
	v_mfma_f32_16x16x32_bf16 v[102:105], v[160:163], v[168:171], v[102:105]
	v_mfma_f32_16x16x32_bf16 v[92:95], v[152:155], v[176:179], v[92:95]
	v_mfma_f32_16x16x32_bf16 v[84:87], v[160:163], v[176:179], v[84:87]
	v_mfma_f32_16x16x32_bf16 v[76:79], v[152:155], v[184:187], v[76:79]
	v_mfma_f32_16x16x32_bf16 v[72:75], v[160:163], v[184:187], v[72:75]
	v_mfma_f32_16x16x32_bf16 v[68:71], v[152:155], v[192:195], v[68:71]
	v_mfma_f32_16x16x32_bf16 v[64:67], v[160:163], v[192:195], v[64:67]
	v_mfma_f32_16x16x32_bf16 v[110:113], v[156:159], v[172:175], v[110:113]
	v_mfma_f32_16x16x32_bf16 v[102:105], v[164:167], v[172:175], v[102:105]
	v_mfma_f32_16x16x32_bf16 v[92:95], v[156:159], v[180:183], v[92:95]
	v_mfma_f32_16x16x32_bf16 v[84:87], v[164:167], v[180:183], v[84:87]
	v_mfma_f32_16x16x32_bf16 v[76:79], v[156:159], v[188:191], v[76:79]
	v_mfma_f32_16x16x32_bf16 v[72:75], v[164:167], v[188:191], v[72:75]
	v_mfma_f32_16x16x32_bf16 v[68:71], v[156:159], v[202:205], v[68:71]
	v_mfma_f32_16x16x32_bf16 v[64:67], v[164:167], v[202:205], v[64:67]
	s_setprio 0
	s_barrier
	s_mov_b32 m0, s3
	v_lshl_add_u64 v[198:199], v[198:199], 0, s[30:31]
	ds_read_b128 v[168:171], v135 offset:49152
	ds_read_b128 v[172:175], v135 offset:50176
	ds_read_b128 v[176:179], v135 offset:51200
	ds_read_b128 v[180:183], v135 offset:52224
	ds_read_b128 v[184:187], v135 offset:53248
	ds_read_b128 v[188:191], v135 offset:54272
	ds_read_b128 v[192:195], v135 offset:55296
	ds_read_b128 v[202:205], v135 offset:56320
	global_load_lds_dwordx4 v[198:199], off
	v_lshl_add_u64 v[198:199], v[200:201], 0, s[30:31]
	s_mov_b32 m0, s2
	s_nop 0
	global_load_lds_dwordx4 v[198:199], off
	v_lshl_add_u64 v[198:199], s[60:61], 0, v[96:97]
	s_mov_b32 m0, s49
	s_nop 0
	global_load_lds_dwordx4 v[198:199], off
	v_lshl_add_u64 v[198:199], s[60:61], 0, v[130:131]
	s_mov_b32 m0, s47
	s_nop 0
	global_load_lds_dwordx4 v[198:199], off
	v_lshl_add_u64 v[198:199], v[206:207], 0, s[30:31]
	s_mov_b32 m0, s18
	s_nop 0
	global_load_lds_dwordx4 v[198:199], off
	v_lshl_add_u64 v[198:199], v[208:209], 0, s[30:31]
	s_mov_b32 m0, s19
	s_nop 0
	global_load_lds_dwordx4 v[198:199], off
	s_waitcnt vmcnt(8)
	s_waitcnt lgkmcnt(0)
	v_mfma_f32_16x16x32_bf16 v[60:63], v[136:139], v[168:171], v[60:63]
	v_mfma_f32_16x16x32_bf16 v[56:59], v[144:147], v[168:171], v[56:59]
	v_mfma_f32_16x16x32_bf16 v[52:55], v[136:139], v[176:179], v[52:55]
	v_mfma_f32_16x16x32_bf16 v[48:51], v[144:147], v[176:179], v[48:51]
	s_barrier
	s_setprio 1
	s_waitcnt lgkmcnt(0)
	v_mfma_f32_16x16x32_bf16 v[36:39], v[136:139], v[184:187], v[36:39]
	v_mfma_f32_16x16x32_bf16 v[32:35], v[144:147], v[184:187], v[32:35]
	v_mfma_f32_16x16x32_bf16 v[20:23], v[136:139], v[192:195], v[20:23]
	v_mfma_f32_16x16x32_bf16 v[16:19], v[144:147], v[192:195], v[16:19]
	v_mfma_f32_16x16x32_bf16 v[60:63], v[140:143], v[172:175], v[60:63]
	v_mfma_f32_16x16x32_bf16 v[56:59], v[148:151], v[172:175], v[56:59]
	v_mfma_f32_16x16x32_bf16 v[52:55], v[140:143], v[180:183], v[52:55]
	v_mfma_f32_16x16x32_bf16 v[48:51], v[148:151], v[180:183], v[48:51]
	v_mfma_f32_16x16x32_bf16 v[36:39], v[140:143], v[188:191], v[36:39]
	v_mfma_f32_16x16x32_bf16 v[32:35], v[148:151], v[188:191], v[32:35]
	v_mfma_f32_16x16x32_bf16 v[20:23], v[140:143], v[202:205], v[20:23]
	v_mfma_f32_16x16x32_bf16 v[16:19], v[148:151], v[202:205], v[16:19]
	s_setprio 0
	s_setprio 1
	v_mfma_f32_16x16x32_bf16 v[44:47], v[152:155], v[168:171], v[44:47]
	v_mfma_f32_16x16x32_bf16 v[40:43], v[160:163], v[168:171], v[40:43]
	v_mfma_f32_16x16x32_bf16 v[28:31], v[152:155], v[176:179], v[28:31]
	v_mfma_f32_16x16x32_bf16 v[24:27], v[160:163], v[176:179], v[24:27]
	v_mfma_f32_16x16x32_bf16 v[12:15], v[152:155], v[184:187], v[12:15]
	v_mfma_f32_16x16x32_bf16 v[8:11], v[160:163], v[184:187], v[8:11]
	v_mfma_f32_16x16x32_bf16 v[4:7], v[152:155], v[192:195], v[4:7]
	v_mfma_f32_16x16x32_bf16 v[0:3], v[160:163], v[192:195], v[0:3]
	v_mfma_f32_16x16x32_bf16 v[44:47], v[156:159], v[172:175], v[44:47]
	v_mfma_f32_16x16x32_bf16 v[40:43], v[164:167], v[172:175], v[40:43]
	v_mfma_f32_16x16x32_bf16 v[28:31], v[156:159], v[180:183], v[28:31]
	v_mfma_f32_16x16x32_bf16 v[24:27], v[164:167], v[180:183], v[24:27]
	v_mfma_f32_16x16x32_bf16 v[12:15], v[156:159], v[188:191], v[12:15]
	v_mfma_f32_16x16x32_bf16 v[8:11], v[164:167], v[188:191], v[8:11]
	v_mfma_f32_16x16x32_bf16 v[4:7], v[156:159], v[202:205], v[4:7]
	v_mfma_f32_16x16x32_bf16 v[0:3], v[164:167], v[202:205], v[0:3]
	s_setprio 0
	s_barrier
	s_movk_i32 s2, 0x100
	s_andn2_b64 vcc, exec, s[58:59]
	s_mov_b64 s[60:61], -1
	s_mov_b64 s[58:59], 0
	s_cbranch_vccz .LBB0_973
	s_and_b64 vcc, exec, s[38:39]
	s_cbranch_vccz .LBB0_976
	s_barrier

.LBB0_993:
	s_add_u32 s3, s24, s46
	s_addc_u32 s6, s25, s47
	s_add_u32 s3, s3, 0x100
	s_addc_u32 s6, s6, 0
	s_add_u32 s48, s59, s46
	s_addc_u32 s49, s60, s47
	s_add_i32 s63, 0, 0x10000
	s_cmpk_eq_i32 s46, 0xf00
	s_cselect_b32 s51, s23, s6
	s_cselect_b32 s50, s61, s3
	v_add_u32_e32 v146, s63, v144
	s_cselect_b32 s49, s15, s49
	s_cselect_b32 s48, s62, s48
	s_add_i32 s3, 0, 0x14000
	ds_read_b128 v[154:157], v146
	ds_read_b128 v[158:161], v146 offset:1024
	ds_read_b128 v[162:165], v146 offset:2048
	ds_read_b128 v[166:169], v146 offset:3072
	v_add_u32_e32 v146, s3, v144
	ds_read_b128 v[174:177], v146
	ds_read_b128 v[178:181], v146 offset:1024
	ds_read_b128 v[182:185], v146 offset:2048
	ds_read_b128 v[186:189], v146 offset:3072
	v_lshl_add_u64 v[146:147], v[140:141], 0, s[46:47]
	s_add_i32 m0, s17, 0xc000
	ds_read_b128 v[190:193], v145
	ds_read_b128 v[202:205], v145 offset:1024
	ds_read_b128 v[206:209], v145 offset:2048
	ds_read_b128 v[214:217], v145 offset:3072
	ds_read_b128 v[218:221], v145 offset:4096
	ds_read_b128 v[222:225], v145 offset:5120
	ds_read_b128 v[226:229], v145 offset:6144
	ds_read_b128 v[230:233], v145 offset:7168
	global_load_lds_dwordx4 v[146:147], off
	v_lshl_add_u64 v[146:147], v[142:143], 0, s[46:47]
	s_add_i32 m0, s17, 0xe000
	s_nop 0
	global_load_lds_dwordx4 v[146:147], off
	s_waitcnt vmcnt(8)
	s_waitcnt lgkmcnt(0)
	v_mfma_f32_16x16x32_bf16 v[110:113], v[154:157], v[190:193], v[110:113]
	v_mfma_f32_16x16x32_bf16 v[106:109], v[162:165], v[190:193], v[106:109]
	v_mfma_f32_16x16x32_bf16 v[118:121], v[154:157], v[206:209], v[118:121]
	v_mfma_f32_16x16x32_bf16 v[114:117], v[162:165], v[206:209], v[114:117]
	s_barrier
	s_setprio 1
	s_waitcnt lgkmcnt(0)
	v_mfma_f32_16x16x32_bf16 v[126:129], v[154:157], v[218:221], v[126:129]
	v_mfma_f32_16x16x32_bf16 v[122:125], v[162:165], v[218:221], v[122:125]
	v_mfma_f32_16x16x32_bf16 v[92:95], v[154:157], v[226:229], v[92:95]
	v_mfma_f32_16x16x32_bf16 v[88:91], v[162:165], v[226:229], v[88:91]
	v_mfma_f32_16x16x32_bf16 v[110:113], v[158:161], v[202:205], v[110:113]
	v_mfma_f32_16x16x32_bf16 v[106:109], v[166:169], v[202:205], v[106:109]
	v_mfma_f32_16x16x32_bf16 v[118:121], v[158:161], v[214:217], v[118:121]
	v_mfma_f32_16x16x32_bf16 v[114:117], v[166:169], v[214:217], v[114:117]
	v_mfma_f32_16x16x32_bf16 v[126:129], v[158:161], v[222:225], v[126:129]
	v_mfma_f32_16x16x32_bf16 v[122:125], v[166:169], v[222:225], v[122:125]
	v_mfma_f32_16x16x32_bf16 v[92:95], v[158:161], v[230:233], v[92:95]
	v_mfma_f32_16x16x32_bf16 v[88:91], v[166:169], v[230:233], v[88:91]
	s_setprio 0
	s_setprio 1
	v_mfma_f32_16x16x32_bf16 v[4:7], v[174:177], v[190:193], v[4:7]
	v_mfma_f32_16x16x32_bf16 v[0:3], v[182:185], v[190:193], v[0:3]
	v_mfma_f32_16x16x32_bf16 v[12:15], v[174:177], v[206:209], v[12:15]
	v_mfma_f32_16x16x32_bf16 v[8:11], v[182:185], v[206:209], v[8:11]
	v_mfma_f32_16x16x32_bf16 v[24:27], v[174:177], v[218:221], v[24:27]
	v_mfma_f32_16x16x32_bf16 v[20:23], v[182:185], v[218:221], v[20:23]
	v_mfma_f32_16x16x32_bf16 v[40:43], v[174:177], v[226:229], v[40:43]
	v_mfma_f32_16x16x32_bf16 v[32:35], v[182:185], v[226:229], v[32:35]
	v_mfma_f32_16x16x32_bf16 v[4:7], v[178:181], v[202:205], v[4:7]
	v_mfma_f32_16x16x32_bf16 v[0:3], v[186:189], v[202:205], v[0:3]
	v_mfma_f32_16x16x32_bf16 v[12:15], v[178:181], v[214:217], v[12:15]
	v_mfma_f32_16x16x32_bf16 v[8:11], v[186:189], v[214:217], v[8:11]
	v_mfma_f32_16x16x32_bf16 v[24:27], v[178:181], v[222:225], v[24:27]
	v_mfma_f32_16x16x32_bf16 v[20:23], v[186:189], v[222:225], v[20:23]
	v_mfma_f32_16x16x32_bf16 v[40:43], v[178:181], v[230:233], v[40:43]
	v_mfma_f32_16x16x32_bf16 v[32:35], v[186:189], v[230:233], v[32:35]
	s_setprio 0
	s_barrier
	s_add_i32 s6, s63, s5
	v_lshl_add_u64 v[146:147], s[48:49], 0, v[96:97]
	s_mov_b32 m0, s6
	ds_read_b128 v[190:193], v145 offset:16384
	ds_read_b128 v[202:205], v145 offset:17408
	ds_read_b128 v[206:209], v145 offset:18432
	ds_read_b128 v[214:217], v145 offset:19456
	ds_read_b128 v[218:221], v145 offset:20480
	ds_read_b128 v[222:225], v145 offset:21504
	ds_read_b128 v[226:229], v145 offset:22528
	ds_read_b128 v[230:233], v145 offset:23552
	global_load_lds_dwordx4 v[146:147], off
	s_add_i32 m0, s6, 0x2000
	s_add_u32 s72, s48, 0x80000
	v_lshl_add_u64 v[150:151], s[48:49], 0, v[130:131]
	s_addc_u32 s73, s49, 0
	s_add_i32 s3, s3, s5
	global_load_lds_dwordx4 v[150:151], off
	v_lshl_add_u64 v[170:171], s[72:73], 0, v[96:97]
	s_mov_b32 m0, s3
	v_lshl_add_u64 v[194:195], s[50:51], 0, v[132:133]
	global_load_lds_dwordx4 v[170:171], off
	v_lshl_add_u64 v[170:171], s[72:73], 0, v[130:131]
	s_add_i32 m0, s3, 0x2000
	s_nop 0
	global_load_lds_dwordx4 v[170:171], off
	v_lshl_add_u64 v[170:171], s[50:51], 0, v[134:135]
	s_mov_b32 m0, s17
	s_nop 0
	global_load_lds_dwordx4 v[170:171], off
	s_mov_b32 m0, s18
	s_nop 0
	global_load_lds_dwordx4 v[194:195], off
	s_waitcnt vmcnt(8)
	s_waitcnt lgkmcnt(0)
	v_mfma_f32_16x16x32_bf16 v[102:105], v[154:157], v[190:193], v[102:105]
	v_mfma_f32_16x16x32_bf16 v[98:101], v[162:165], v[190:193], v[98:101]
	v_mfma_f32_16x16x32_bf16 v[84:87], v[154:157], v[206:209], v[84:87]
	v_mfma_f32_16x16x32_bf16 v[80:83], v[162:165], v[206:209], v[80:83]
	s_barrier
	s_setprio 1
	s_waitcnt lgkmcnt(0)
	v_mfma_f32_16x16x32_bf16 v[68:71], v[154:157], v[218:221], v[68:71]
	v_mfma_f32_16x16x32_bf16 v[64:67], v[162:165], v[218:221], v[64:67]
	v_mfma_f32_16x16x32_bf16 v[44:47], v[154:157], v[226:229], v[44:47]
	v_mfma_f32_16x16x32_bf16 v[36:39], v[162:165], v[226:229], v[36:39]
	v_mfma_f32_16x16x32_bf16 v[102:105], v[158:161], v[202:205], v[102:105]
	v_mfma_f32_16x16x32_bf16 v[98:101], v[166:169], v[202:205], v[98:101]
	v_mfma_f32_16x16x32_bf16 v[84:87], v[158:161], v[214:217], v[84:87]
	v_mfma_f32_16x16x32_bf16 v[80:83], v[166:169], v[214:217], v[80:83]
	v_mfma_f32_16x16x32_bf16 v[68:71], v[158:161], v[222:225], v[68:71]
	v_mfma_f32_16x16x32_bf16 v[64:67], v[166:169], v[222:225], v[64:67]
	v_mfma_f32_16x16x32_bf16 v[44:47], v[158:161], v[230:233], v[44:47]
	v_mfma_f32_16x16x32_bf16 v[36:39], v[166:169], v[230:233], v[36:39]
	s_setprio 0
	s_setprio 1
	v_mfma_f32_16x16x32_bf16 v[60:63], v[174:177], v[190:193], v[60:63]
	v_mfma_f32_16x16x32_bf16 v[56:59], v[182:185], v[190:193], v[56:59]
	v_mfma_f32_16x16x32_bf16 v[76:79], v[174:177], v[206:209], v[76:79]
	v_mfma_f32_16x16x32_bf16 v[72:75], v[182:185], v[206:209], v[72:75]
	v_mfma_f32_16x16x32_bf16 v[52:55], v[174:177], v[218:221], v[52:55]
	v_mfma_f32_16x16x32_bf16 v[48:51], v[182:185], v[218:221], v[48:51]
	v_mfma_f32_16x16x32_bf16 v[28:31], v[174:177], v[226:229], v[28:31]
	v_mfma_f32_16x16x32_bf16 v[16:19], v[182:185], v[226:229], v[16:19]
	v_mfma_f32_16x16x32_bf16 v[60:63], v[178:181], v[202:205], v[60:63]
	v_mfma_f32_16x16x32_bf16 v[56:59], v[186:189], v[202:205], v[56:59]
	v_mfma_f32_16x16x32_bf16 v[76:79], v[178:181], v[214:217], v[76:79]
	v_mfma_f32_16x16x32_bf16 v[72:75], v[186:189], v[214:217], v[72:75]
	v_mfma_f32_16x16x32_bf16 v[52:55], v[178:181], v[222:225], v[52:55]
	v_mfma_f32_16x16x32_bf16 v[48:51], v[186:189], v[222:225], v[48:51]
	v_mfma_f32_16x16x32_bf16 v[28:31], v[178:181], v[230:233], v[28:31]
	v_mfma_f32_16x16x32_bf16 v[16:19], v[186:189], v[230:233], v[16:19]
	s_setprio 0
	s_barrier
	s_add_i32 s3, 0, 0x18000
	v_add_u32_e32 v149, s3, v144
	s_add_i32 s6, 0, 0x1c000
	ds_read_b128 v[154:157], v149
	ds_read_b128 v[158:161], v149 offset:1024
	ds_read_b128 v[162:165], v149 offset:2048
	ds_read_b128 v[166:169], v149 offset:3072
	v_add_u32_e32 v149, s6, v144
	ds_read_b128 v[174:177], v149
	ds_read_b128 v[178:181], v149 offset:1024
	ds_read_b128 v[182:185], v149 offset:2048
	ds_read_b128 v[186:189], v149 offset:3072
	s_add_u32 s50, s50, 0x80000
	s_addc_u32 s51, s51, 0
	s_mov_b32 m0, s19
	v_lshl_add_u64 v[198:199], s[50:51], 0, v[134:135]
	ds_read_b128 v[190:193], v145 offset:32768
	ds_read_b128 v[202:205], v145 offset:33792
	ds_read_b128 v[206:209], v145 offset:34816
	ds_read_b128 v[214:217], v145 offset:35840
	ds_read_b128 v[218:221], v145 offset:36864
	ds_read_b128 v[222:225], v145 offset:37888
	ds_read_b128 v[226:229], v145 offset:38912
	ds_read_b128 v[230:233], v145 offset:39936
	global_load_lds_dwordx4 v[198:199], off
	v_lshl_add_u64 v[198:199], s[50:51], 0, v[132:133]
	s_mov_b32 m0, s20
	s_nop 0
	global_load_lds_dwordx4 v[198:199], off
	s_waitcnt vmcnt(8)
	s_waitcnt lgkmcnt(0)
	v_mfma_f32_16x16x32_bf16 v[110:113], v[154:157], v[190:193], v[110:113]
	v_mfma_f32_16x16x32_bf16 v[106:109], v[162:165], v[190:193], v[106:109]
	v_mfma_f32_16x16x32_bf16 v[118:121], v[154:157], v[206:209], v[118:121]
	v_mfma_f32_16x16x32_bf16 v[114:117], v[162:165], v[206:209], v[114:117]
	s_barrier
	s_setprio 1
	s_waitcnt lgkmcnt(0)
	v_mfma_f32_16x16x32_bf16 v[126:129], v[154:157], v[218:221], v[126:129]
	v_mfma_f32_16x16x32_bf16 v[122:125], v[162:165], v[218:221], v[122:125]
	v_mfma_f32_16x16x32_bf16 v[92:95], v[154:157], v[226:229], v[92:95]
	v_mfma_f32_16x16x32_bf16 v[88:91], v[162:165], v[226:229], v[88:91]
	v_mfma_f32_16x16x32_bf16 v[110:113], v[158:161], v[202:205], v[110:113]
	v_mfma_f32_16x16x32_bf16 v[106:109], v[166:169], v[202:205], v[106:109]
	v_mfma_f32_16x16x32_bf16 v[118:121], v[158:161], v[214:217], v[118:121]
	v_mfma_f32_16x16x32_bf16 v[114:117], v[166:169], v[214:217], v[114:117]
	v_mfma_f32_16x16x32_bf16 v[126:129], v[158:161], v[222:225], v[126:129]
	v_mfma_f32_16x16x32_bf16 v[122:125], v[166:169], v[222:225], v[122:125]
	v_mfma_f32_16x16x32_bf16 v[92:95], v[158:161], v[230:233], v[92:95]
	v_mfma_f32_16x16x32_bf16 v[88:91], v[166:169], v[230:233], v[88:91]
	s_setprio 0
	s_setprio 1
	v_mfma_f32_16x16x32_bf16 v[4:7], v[174:177], v[190:193], v[4:7]
	v_mfma_f32_16x16x32_bf16 v[0:3], v[182:185], v[190:193], v[0:3]
	v_mfma_f32_16x16x32_bf16 v[12:15], v[174:177], v[206:209], v[12:15]
	v_mfma_f32_16x16x32_bf16 v[8:11], v[182:185], v[206:209], v[8:11]
	v_mfma_f32_16x16x32_bf16 v[24:27], v[174:177], v[218:221], v[24:27]
	v_mfma_f32_16x16x32_bf16 v[20:23], v[182:185], v[218:221], v[20:23]
	v_mfma_f32_16x16x32_bf16 v[40:43], v[174:177], v[226:229], v[40:43]
	v_mfma_f32_16x16x32_bf16 v[32:35], v[182:185], v[226:229], v[32:35]
	v_mfma_f32_16x16x32_bf16 v[4:7], v[178:181], v[202:205], v[4:7]
	v_mfma_f32_16x16x32_bf16 v[0:3], v[186:189], v[202:205], v[0:3]
	v_mfma_f32_16x16x32_bf16 v[12:15], v[178:181], v[214:217], v[12:15]
	v_mfma_f32_16x16x32_bf16 v[8:11], v[186:189], v[214:217], v[8:11]
	v_mfma_f32_16x16x32_bf16 v[24:27], v[178:181], v[222:225], v[24:27]
	v_mfma_f32_16x16x32_bf16 v[20:23], v[186:189], v[222:225], v[20:23]
	v_mfma_f32_16x16x32_bf16 v[40:43], v[178:181], v[230:233], v[40:43]
	v_mfma_f32_16x16x32_bf16 v[32:35], v[186:189], v[230:233], v[32:35]
	s_setprio 0
	s_barrier
	s_add_i32 s3, s3, s5
	v_lshl_add_u64 v[146:147], v[146:147], 0, s[30:31]
	s_mov_b32 m0, s3
	ds_read_b128 v[190:193], v145 offset:49152
	ds_read_b128 v[202:205], v145 offset:50176
	ds_read_b128 v[206:209], v145 offset:51200
	ds_read_b128 v[214:217], v145 offset:52224
	ds_read_b128 v[218:221], v145 offset:53248
	ds_read_b128 v[222:225], v145 offset:54272
	ds_read_b128 v[226:229], v145 offset:55296
	ds_read_b128 v[230:233], v145 offset:56320
	global_load_lds_dwordx4 v[146:147], off
	s_add_i32 m0, s3, 0x2000
	s_add_u32 s48, s48, 0x80080
	v_lshl_add_u64 v[146:147], v[150:151], 0, s[30:31]
	s_addc_u32 s49, s49, 0
	s_add_i32 s3, s6, s5
	global_load_lds_dwordx4 v[146:147], off
	v_lshl_add_u64 v[146:147], s[48:49], 0, v[96:97]
	s_mov_b32 m0, s3
	s_nop 0
	global_load_lds_dwordx4 v[146:147], off
	v_lshl_add_u64 v[146:147], s[48:49], 0, v[130:131]
	s_add_i32 m0, s3, 0x2000
	s_nop 0
	global_load_lds_dwordx4 v[146:147], off
	v_lshl_add_u64 v[146:147], v[170:171], 0, s[30:31]
	s_mov_b32 m0, s37
	s_nop 0
	global_load_lds_dwordx4 v[146:147], off
	v_lshl_add_u64 v[146:147], v[194:195], 0, s[30:31]
	s_mov_b32 m0, s56
	s_nop 0
	global_load_lds_dwordx4 v[146:147], off
	s_waitcnt vmcnt(8)
	s_waitcnt lgkmcnt(0)
	v_mfma_f32_16x16x32_bf16 v[102:105], v[154:157], v[190:193], v[102:105]
	v_mfma_f32_16x16x32_bf16 v[98:101], v[162:165], v[190:193], v[98:101]
	v_mfma_f32_16x16x32_bf16 v[84:87], v[154:157], v[206:209], v[84:87]
	v_mfma_f32_16x16x32_bf16 v[80:83], v[162:165], v[206:209], v[80:83]
	s_barrier
	s_setprio 1
	s_waitcnt lgkmcnt(0)
	v_mfma_f32_16x16x32_bf16 v[68:71], v[154:157], v[218:221], v[68:71]
	v_mfma_f32_16x16x32_bf16 v[64:67], v[162:165], v[218:221], v[64:67]
	v_mfma_f32_16x16x32_bf16 v[44:47], v[154:157], v[226:229], v[44:47]
	v_mfma_f32_16x16x32_bf16 v[36:39], v[162:165], v[226:229], v[36:39]
	v_mfma_f32_16x16x32_bf16 v[102:105], v[158:161], v[202:205], v[102:105]
	v_mfma_f32_16x16x32_bf16 v[98:101], v[166:169], v[202:205], v[98:101]
	v_mfma_f32_16x16x32_bf16 v[84:87], v[158:161], v[214:217], v[84:87]
	v_mfma_f32_16x16x32_bf16 v[80:83], v[166:169], v[214:217], v[80:83]
	v_mfma_f32_16x16x32_bf16 v[68:71], v[158:161], v[222:225], v[68:71]
	v_mfma_f32_16x16x32_bf16 v[64:67], v[166:169], v[222:225], v[64:67]
	v_mfma_f32_16x16x32_bf16 v[44:47], v[158:161], v[230:233], v[44:47]
	v_mfma_f32_16x16x32_bf16 v[36:39], v[166:169], v[230:233], v[36:39]
	s_setprio 0
	s_setprio 1
	v_mfma_f32_16x16x32_bf16 v[60:63], v[174:177], v[190:193], v[60:63]
	v_mfma_f32_16x16x32_bf16 v[56:59], v[182:185], v[190:193], v[56:59]
	v_mfma_f32_16x16x32_bf16 v[76:79], v[174:177], v[206:209], v[76:79]
	v_mfma_f32_16x16x32_bf16 v[72:75], v[182:185], v[206:209], v[72:75]
	v_mfma_f32_16x16x32_bf16 v[52:55], v[174:177], v[218:221], v[52:55]
	v_mfma_f32_16x16x32_bf16 v[48:51], v[182:185], v[218:221], v[48:51]
	v_mfma_f32_16x16x32_bf16 v[28:31], v[174:177], v[226:229], v[28:31]
	v_mfma_f32_16x16x32_bf16 v[16:19], v[182:185], v[226:229], v[16:19]
	v_mfma_f32_16x16x32_bf16 v[60:63], v[178:181], v[202:205], v[60:63]
	v_mfma_f32_16x16x32_bf16 v[56:59], v[186:189], v[202:205], v[56:59]
	v_mfma_f32_16x16x32_bf16 v[76:79], v[178:181], v[214:217], v[76:79]
	v_mfma_f32_16x16x32_bf16 v[72:75], v[186:189], v[214:217], v[72:75]
	v_mfma_f32_16x16x32_bf16 v[52:55], v[178:181], v[222:225], v[52:55]
	v_mfma_f32_16x16x32_bf16 v[48:51], v[186:189], v[222:225], v[48:51]
	v_mfma_f32_16x16x32_bf16 v[28:31], v[178:181], v[230:233], v[28:31]
	v_mfma_f32_16x16x32_bf16 v[16:19], v[186:189], v[230:233], v[16:19]
	s_setprio 0
	s_barrier
	s_add_i32 s2, s2, 2
	s_add_u32 s46, s46, 0x100
	s_addc_u32 s47, s47, 0
	s_cmp_gt_u32 s2, 29
	s_cbranch_scc0 .LBB0_993
	s_and_b64 vcc, exec, s[12:13]
	s_cbranch_vccz .LBB0_996
	s_barrier

.LBB0_1158:
	s_add_u32 s34, s62, 0x100
	s_addc_u32 s35, s63, 0
	s_add_i32 s67, 0, 0x10000
	s_cmp_eq_u32 s6, 28
	s_cselect_b32 s89, s23, s35
	s_cselect_b32 s88, s61, s34
	s_cselect_b32 vcc_hi, s91, s3
	s_cselect_b32 vcc_lo, s93, s2
	s_add_i32 s76, 0, 0x14000
	v_add_u32_e32 v142, s67, v191
	v_add_u32_e32 v158, s76, v191
	ds_read_b128 v[130:133], v142
	ds_read_b128 v[134:137], v142 offset:1024
	ds_read_b128 v[138:141], v142 offset:2048
	ds_read_b128 v[142:145], v142 offset:3072
	ds_read_b128 v[146:149], v158
	ds_read_b128 v[150:153], v158 offset:1024
	ds_read_b128 v[154:157], v158 offset:2048
	ds_read_b128 v[158:161], v158 offset:3072
	v_lshl_add_u64 v[188:189], s[62:63], 0, v[184:185]
	s_add_i32 m0, s17, 0xc000
	ds_read_b128 v[162:165], v224
	ds_read_b128 v[166:169], v224 offset:1024
	ds_read_b128 v[170:173], v224 offset:2048
	ds_read_b128 v[178:181], v224 offset:3072
	ds_read_b128 v[202:205], v224 offset:4096
	ds_read_b128 v[206:209], v224 offset:5120
	ds_read_b128 v[226:229], v224 offset:6144
	ds_read_b128 v[230:233], v224 offset:7168
	global_load_lds_dwordx4 v[188:189], off
	v_lshl_add_u64 v[188:189], s[62:63], 0, v[186:187]
	s_add_i32 m0, s17, 0xe000
	s_nop 0
	global_load_lds_dwordx4 v[188:189], off
	s_waitcnt vmcnt(8)
	s_waitcnt lgkmcnt(0)
	v_mfma_f32_16x16x32_bf16 v[126:129], v[130:133], v[162:165], v[126:129]
	v_mfma_f32_16x16x32_bf16 v[56:59], v[138:141], v[162:165], v[56:59]
	v_mfma_f32_16x16x32_bf16 v[122:125], v[130:133], v[170:173], v[122:125]
	v_mfma_f32_16x16x32_bf16 v[52:55], v[138:141], v[170:173], v[52:55]
	s_barrier
	s_setprio 1
	s_waitcnt lgkmcnt(0)
	v_mfma_f32_16x16x32_bf16 v[118:121], v[130:133], v[202:205], v[118:121]
	v_mfma_f32_16x16x32_bf16 v[60:63], v[138:141], v[202:205], v[60:63]
	v_mfma_f32_16x16x32_bf16 v[114:117], v[130:133], v[226:229], v[114:117]
	v_mfma_f32_16x16x32_bf16 v[44:47], v[138:141], v[226:229], v[44:47]
	v_mfma_f32_16x16x32_bf16 v[126:129], v[134:137], v[166:169], v[126:129]
	v_mfma_f32_16x16x32_bf16 v[56:59], v[142:145], v[166:169], v[56:59]
	v_mfma_f32_16x16x32_bf16 v[122:125], v[134:137], v[178:181], v[122:125]
	v_mfma_f32_16x16x32_bf16 v[52:55], v[142:145], v[178:181], v[52:55]
	v_mfma_f32_16x16x32_bf16 v[118:121], v[134:137], v[206:209], v[118:121]
	v_mfma_f32_16x16x32_bf16 v[60:63], v[142:145], v[206:209], v[60:63]
	v_mfma_f32_16x16x32_bf16 v[114:117], v[134:137], v[230:233], v[114:117]
	v_mfma_f32_16x16x32_bf16 v[44:47], v[142:145], v[230:233], v[44:47]
	s_setprio 0
	s_setprio 1
	v_mfma_f32_16x16x32_bf16 v[110:113], v[146:149], v[162:165], v[110:113]
	v_mfma_f32_16x16x32_bf16 v[40:43], v[154:157], v[162:165], v[40:43]
	v_mfma_f32_16x16x32_bf16 v[106:109], v[146:149], v[170:173], v[106:109]
	v_mfma_f32_16x16x32_bf16 v[36:39], v[154:157], v[170:173], v[36:39]
	v_mfma_f32_16x16x32_bf16 v[102:105], v[146:149], v[202:205], v[102:105]
	v_mfma_f32_16x16x32_bf16 v[48:51], v[154:157], v[202:205], v[48:51]
	v_mfma_f32_16x16x32_bf16 v[98:101], v[146:149], v[226:229], v[98:101]
	v_mfma_f32_16x16x32_bf16 v[32:35], v[154:157], v[226:229], v[32:35]
	v_mfma_f32_16x16x32_bf16 v[110:113], v[150:153], v[166:169], v[110:113]
	v_mfma_f32_16x16x32_bf16 v[40:43], v[158:161], v[166:169], v[40:43]
	v_mfma_f32_16x16x32_bf16 v[106:109], v[150:153], v[178:181], v[106:109]
	v_mfma_f32_16x16x32_bf16 v[36:39], v[158:161], v[178:181], v[36:39]
	v_mfma_f32_16x16x32_bf16 v[102:105], v[150:153], v[206:209], v[102:105]
	v_mfma_f32_16x16x32_bf16 v[48:51], v[158:161], v[206:209], v[48:51]
	v_mfma_f32_16x16x32_bf16 v[98:101], v[150:153], v[230:233], v[98:101]
	v_mfma_f32_16x16x32_bf16 v[32:35], v[158:161], v[230:233], v[32:35]
	s_setprio 0
	s_barrier
	s_add_i32 s62, s67, s5
	v_lshl_add_u64 v[188:189], vcc, 0, v[96:97]
	s_mov_b32 m0, s62
	ds_read_b128 v[162:165], v224 offset:16384
	ds_read_b128 v[166:169], v224 offset:17408
	ds_read_b128 v[170:173], v224 offset:18432
	ds_read_b128 v[178:181], v224 offset:19456
	ds_read_b128 v[202:205], v224 offset:20480
	ds_read_b128 v[206:209], v224 offset:21504
	ds_read_b128 v[226:229], v224 offset:22528
	ds_read_b128 v[230:233], v224 offset:23552
	global_load_lds_dwordx4 v[188:189], off
	s_add_i32 m0, s62, 0x2000
	s_add_u32 s62, vcc_lo, 0x80000
	v_lshl_add_u64 v[198:199], vcc, 0, v[182:183]
	s_addc_u32 s63, vcc_hi, 0
	s_add_i32 s67, s76, s5
	global_load_lds_dwordx4 v[198:199], off
	v_lshl_add_u64 v[200:201], s[62:63], 0, v[96:97]
	s_mov_b32 m0, s67
	v_lshl_add_u64 v[234:235], s[88:89], 0, v[176:177]
	global_load_lds_dwordx4 v[200:201], off
	v_lshl_add_u64 v[200:201], s[62:63], 0, v[182:183]
	s_add_i32 m0, s67, 0x2000
	s_nop 0
	global_load_lds_dwordx4 v[200:201], off
	v_lshl_add_u64 v[200:201], s[88:89], 0, v[174:175]
	s_mov_b32 m0, s17
	s_nop 0
	global_load_lds_dwordx4 v[200:201], off
	s_mov_b32 m0, s18
	s_nop 0
	global_load_lds_dwordx4 v[234:235], off
	s_waitcnt vmcnt(8)
	s_waitcnt lgkmcnt(0)
	v_mfma_f32_16x16x32_bf16 v[92:95], v[130:133], v[162:165], v[92:95]
	v_mfma_f32_16x16x32_bf16 v[24:27], v[138:141], v[162:165], v[24:27]
	v_mfma_f32_16x16x32_bf16 v[88:91], v[130:133], v[170:173], v[88:91]
	v_mfma_f32_16x16x32_bf16 v[28:31], v[138:141], v[170:173], v[28:31]
	s_barrier
	s_setprio 1
	s_waitcnt lgkmcnt(0)
	v_mfma_f32_16x16x32_bf16 v[84:87], v[130:133], v[202:205], v[84:87]
	v_mfma_f32_16x16x32_bf16 v[16:19], v[138:141], v[202:205], v[16:19]
	v_mfma_f32_16x16x32_bf16 v[80:83], v[130:133], v[226:229], v[80:83]
	v_mfma_f32_16x16x32_bf16 v[20:23], v[138:141], v[226:229], v[20:23]
	v_mfma_f32_16x16x32_bf16 v[92:95], v[134:137], v[166:169], v[92:95]
	v_mfma_f32_16x16x32_bf16 v[24:27], v[142:145], v[166:169], v[24:27]
	v_mfma_f32_16x16x32_bf16 v[88:91], v[134:137], v[178:181], v[88:91]
	v_mfma_f32_16x16x32_bf16 v[28:31], v[142:145], v[178:181], v[28:31]
	v_mfma_f32_16x16x32_bf16 v[84:87], v[134:137], v[206:209], v[84:87]
	v_mfma_f32_16x16x32_bf16 v[16:19], v[142:145], v[206:209], v[16:19]
	v_mfma_f32_16x16x32_bf16 v[80:83], v[134:137], v[230:233], v[80:83]
	v_mfma_f32_16x16x32_bf16 v[20:23], v[142:145], v[230:233], v[20:23]
	s_setprio 0
	s_setprio 1
	v_mfma_f32_16x16x32_bf16 v[76:79], v[146:149], v[162:165], v[76:79]
	v_mfma_f32_16x16x32_bf16 v[12:15], v[154:157], v[162:165], v[12:15]
	v_mfma_f32_16x16x32_bf16 v[72:75], v[146:149], v[170:173], v[72:75]
	v_mfma_f32_16x16x32_bf16 v[8:11], v[154:157], v[170:173], v[8:11]
	v_mfma_f32_16x16x32_bf16 v[68:71], v[146:149], v[202:205], v[68:71]
	v_mfma_f32_16x16x32_bf16 v[0:3], v[154:157], v[202:205], v[0:3]
	v_mfma_f32_16x16x32_bf16 v[64:67], v[146:149], v[226:229], v[64:67]
	v_mfma_f32_16x16x32_bf16 v[4:7], v[154:157], v[226:229], v[4:7]
	v_mfma_f32_16x16x32_bf16 v[76:79], v[150:153], v[166:169], v[76:79]
	v_mfma_f32_16x16x32_bf16 v[12:15], v[158:161], v[166:169], v[12:15]
	v_mfma_f32_16x16x32_bf16 v[72:75], v[150:153], v[178:181], v[72:75]
	v_mfma_f32_16x16x32_bf16 v[8:11], v[158:161], v[178:181], v[8:11]
	v_mfma_f32_16x16x32_bf16 v[68:71], v[150:153], v[206:209], v[68:71]
	v_mfma_f32_16x16x32_bf16 v[0:3], v[158:161], v[206:209], v[0:3]
	v_mfma_f32_16x16x32_bf16 v[64:67], v[150:153], v[230:233], v[64:67]
	v_mfma_f32_16x16x32_bf16 v[4:7], v[158:161], v[230:233], v[4:7]
	s_setprio 0
	s_barrier
	s_add_i32 s67, 0, 0x18000
	s_add_i32 s76, 0, 0x1c000
	v_add_u32_e32 v142, s67, v191
	v_add_u32_e32 v158, s76, v191
	ds_read_b128 v[130:133], v142
	ds_read_b128 v[134:137], v142 offset:1024
	ds_read_b128 v[138:141], v142 offset:2048
	ds_read_b128 v[142:145], v142 offset:3072
	ds_read_b128 v[146:149], v158
	ds_read_b128 v[150:153], v158 offset:1024
	ds_read_b128 v[154:157], v158 offset:2048
	ds_read_b128 v[158:161], v158 offset:3072
	s_add_u32 s62, s88, 0x80000
	s_addc_u32 s63, s89, 0
	s_mov_b32 m0, s19
	v_lshl_add_u64 v[236:237], s[62:63], 0, v[174:175]
	ds_read_b128 v[162:165], v224 offset:32768
	ds_read_b128 v[166:169], v224 offset:33792
	ds_read_b128 v[170:173], v224 offset:34816
	ds_read_b128 v[178:181], v224 offset:35840
	ds_read_b128 v[202:205], v224 offset:36864
	ds_read_b128 v[206:209], v224 offset:37888
	ds_read_b128 v[226:229], v224 offset:38912
	ds_read_b128 v[230:233], v224 offset:39936
	global_load_lds_dwordx4 v[236:237], off
	v_lshl_add_u64 v[236:237], s[62:63], 0, v[176:177]
	s_mov_b32 m0, s20
	s_nop 0
	global_load_lds_dwordx4 v[236:237], off
	s_waitcnt vmcnt(8)
	s_waitcnt lgkmcnt(0)
	v_mfma_f32_16x16x32_bf16 v[126:129], v[130:133], v[162:165], v[126:129]
	v_mfma_f32_16x16x32_bf16 v[56:59], v[138:141], v[162:165], v[56:59]
	v_mfma_f32_16x16x32_bf16 v[122:125], v[130:133], v[170:173], v[122:125]
	v_mfma_f32_16x16x32_bf16 v[52:55], v[138:141], v[170:173], v[52:55]
	s_barrier
	s_setprio 1
	s_waitcnt lgkmcnt(0)
	v_mfma_f32_16x16x32_bf16 v[118:121], v[130:133], v[202:205], v[118:121]
	v_mfma_f32_16x16x32_bf16 v[60:63], v[138:141], v[202:205], v[60:63]
	v_mfma_f32_16x16x32_bf16 v[114:117], v[130:133], v[226:229], v[114:117]
	v_mfma_f32_16x16x32_bf16 v[44:47], v[138:141], v[226:229], v[44:47]
	v_mfma_f32_16x16x32_bf16 v[126:129], v[134:137], v[166:169], v[126:129]
	v_mfma_f32_16x16x32_bf16 v[56:59], v[142:145], v[166:169], v[56:59]
	v_mfma_f32_16x16x32_bf16 v[122:125], v[134:137], v[178:181], v[122:125]
	v_mfma_f32_16x16x32_bf16 v[52:55], v[142:145], v[178:181], v[52:55]
	v_mfma_f32_16x16x32_bf16 v[118:121], v[134:137], v[206:209], v[118:121]
	v_mfma_f32_16x16x32_bf16 v[60:63], v[142:145], v[206:209], v[60:63]
	v_mfma_f32_16x16x32_bf16 v[114:117], v[134:137], v[230:233], v[114:117]
	v_mfma_f32_16x16x32_bf16 v[44:47], v[142:145], v[230:233], v[44:47]
	s_setprio 0
	s_setprio 1
	v_mfma_f32_16x16x32_bf16 v[110:113], v[146:149], v[162:165], v[110:113]
	v_mfma_f32_16x16x32_bf16 v[40:43], v[154:157], v[162:165], v[40:43]
	v_mfma_f32_16x16x32_bf16 v[106:109], v[146:149], v[170:173], v[106:109]
	v_mfma_f32_16x16x32_bf16 v[36:39], v[154:157], v[170:173], v[36:39]
	v_mfma_f32_16x16x32_bf16 v[102:105], v[146:149], v[202:205], v[102:105]
	v_mfma_f32_16x16x32_bf16 v[48:51], v[154:157], v[202:205], v[48:51]
	v_mfma_f32_16x16x32_bf16 v[98:101], v[146:149], v[226:229], v[98:101]
	v_mfma_f32_16x16x32_bf16 v[32:35], v[154:157], v[226:229], v[32:35]
	v_mfma_f32_16x16x32_bf16 v[110:113], v[150:153], v[166:169], v[110:113]
	v_mfma_f32_16x16x32_bf16 v[40:43], v[158:161], v[166:169], v[40:43]
	v_mfma_f32_16x16x32_bf16 v[106:109], v[150:153], v[178:181], v[106:109]
	v_mfma_f32_16x16x32_bf16 v[36:39], v[158:161], v[178:181], v[36:39]
	v_mfma_f32_16x16x32_bf16 v[102:105], v[150:153], v[206:209], v[102:105]
	v_mfma_f32_16x16x32_bf16 v[48:51], v[158:161], v[206:209], v[48:51]
	v_mfma_f32_16x16x32_bf16 v[98:101], v[150:153], v[230:233], v[98:101]
	v_mfma_f32_16x16x32_bf16 v[32:35], v[158:161], v[230:233], v[32:35]
	s_setprio 0
	s_barrier
	s_add_i32 s62, s67, s5
	v_lshl_add_u64 v[188:189], v[188:189], 0, s[30:31]
	s_mov_b32 m0, s62
	ds_read_b128 v[162:165], v224 offset:49152
	ds_read_b128 v[166:169], v224 offset:50176
	ds_read_b128 v[170:173], v224 offset:51200
	ds_read_b128 v[178:181], v224 offset:52224
	ds_read_b128 v[202:205], v224 offset:53248
	ds_read_b128 v[206:209], v224 offset:54272
	ds_read_b128 v[226:229], v224 offset:55296
	ds_read_b128 v[230:233], v224 offset:56320
	global_load_lds_dwordx4 v[188:189], off
	s_add_i32 m0, s62, 0x2000
	s_add_u32 s62, vcc_lo, 0x80080
	v_lshl_add_u64 v[188:189], v[198:199], 0, s[30:31]
	s_addc_u32 s63, vcc_hi, 0
	s_add_i32 s67, s76, s5
	global_load_lds_dwordx4 v[188:189], off
	v_lshl_add_u64 v[188:189], s[62:63], 0, v[96:97]
	s_mov_b32 m0, s67
	s_nop 0
	global_load_lds_dwordx4 v[188:189], off
	v_lshl_add_u64 v[188:189], s[62:63], 0, v[182:183]
	s_add_i32 m0, s67, 0x2000
	s_nop 0
	global_load_lds_dwordx4 v[188:189], off
	v_lshl_add_u64 v[188:189], v[200:201], 0, s[30:31]
	s_mov_b32 m0, s36
	s_nop 0
	global_load_lds_dwordx4 v[188:189], off
	v_lshl_add_u64 v[188:189], v[234:235], 0, s[30:31]
	s_mov_b32 m0, s37
	s_nop 0
	global_load_lds_dwordx4 v[188:189], off
	s_waitcnt vmcnt(8)
	s_waitcnt lgkmcnt(0)
	v_mfma_f32_16x16x32_bf16 v[92:95], v[130:133], v[162:165], v[92:95]
	v_mfma_f32_16x16x32_bf16 v[24:27], v[138:141], v[162:165], v[24:27]
	v_mfma_f32_16x16x32_bf16 v[88:91], v[130:133], v[170:173], v[88:91]
	v_mfma_f32_16x16x32_bf16 v[28:31], v[138:141], v[170:173], v[28:31]
	s_barrier
	s_setprio 1
	s_waitcnt lgkmcnt(0)
	v_mfma_f32_16x16x32_bf16 v[84:87], v[130:133], v[202:205], v[84:87]
	v_mfma_f32_16x16x32_bf16 v[16:19], v[138:141], v[202:205], v[16:19]
	v_mfma_f32_16x16x32_bf16 v[80:83], v[130:133], v[226:229], v[80:83]
	v_mfma_f32_16x16x32_bf16 v[20:23], v[138:141], v[226:229], v[20:23]
	v_mfma_f32_16x16x32_bf16 v[92:95], v[134:137], v[166:169], v[92:95]
	v_mfma_f32_16x16x32_bf16 v[24:27], v[142:145], v[166:169], v[24:27]
	v_mfma_f32_16x16x32_bf16 v[88:91], v[134:137], v[178:181], v[88:91]
	v_mfma_f32_16x16x32_bf16 v[28:31], v[142:145], v[178:181], v[28:31]
	v_mfma_f32_16x16x32_bf16 v[84:87], v[134:137], v[206:209], v[84:87]
	v_mfma_f32_16x16x32_bf16 v[16:19], v[142:145], v[206:209], v[16:19]
	v_mfma_f32_16x16x32_bf16 v[80:83], v[134:137], v[230:233], v[80:83]
	v_mfma_f32_16x16x32_bf16 v[20:23], v[142:145], v[230:233], v[20:23]
	s_setprio 0
	s_setprio 1
	v_mfma_f32_16x16x32_bf16 v[76:79], v[146:149], v[162:165], v[76:79]
	v_mfma_f32_16x16x32_bf16 v[12:15], v[154:157], v[162:165], v[12:15]
	v_mfma_f32_16x16x32_bf16 v[72:75], v[146:149], v[170:173], v[72:75]
	v_mfma_f32_16x16x32_bf16 v[8:11], v[154:157], v[170:173], v[8:11]
	v_mfma_f32_16x16x32_bf16 v[68:71], v[146:149], v[202:205], v[68:71]
	v_mfma_f32_16x16x32_bf16 v[0:3], v[154:157], v[202:205], v[0:3]
	v_mfma_f32_16x16x32_bf16 v[64:67], v[146:149], v[226:229], v[64:67]
	v_mfma_f32_16x16x32_bf16 v[4:7], v[154:157], v[226:229], v[4:7]
	v_mfma_f32_16x16x32_bf16 v[76:79], v[150:153], v[166:169], v[76:79]
	v_mfma_f32_16x16x32_bf16 v[12:15], v[158:161], v[166:169], v[12:15]
	v_mfma_f32_16x16x32_bf16 v[72:75], v[150:153], v[178:181], v[72:75]
	v_mfma_f32_16x16x32_bf16 v[8:11], v[158:161], v[178:181], v[8:11]
	v_mfma_f32_16x16x32_bf16 v[68:71], v[150:153], v[206:209], v[68:71]
	v_mfma_f32_16x16x32_bf16 v[0:3], v[158:161], v[206:209], v[0:3]
	v_mfma_f32_16x16x32_bf16 v[64:67], v[150:153], v[230:233], v[64:67]
	v_mfma_f32_16x16x32_bf16 v[4:7], v[158:161], v[230:233], v[4:7]
	s_setprio 0
	s_barrier
	s_add_i32 s6, s6, 2
	s_add_u32 s2, s2, 0x100
	s_addc_u32 s3, s3, 0
	s_cmp_gt_u32 s6, 29
	s_mov_b64 s[62:63], s[34:35]
	s_cbranch_scc0 .LBB0_1158
	s_and_b64 vcc, exec, s[24:25]
	s_cbranch_vccz .LBB0_1161
	s_barrier

.LBB0_1333:
	s_add_u32 s38, s42, 0x100
	s_addc_u32 s39, s43, 0
	s_add_i32 s13, 0, 0x10000
	s_cmp_eq_u32 s6, 4
	s_cselect_b32 s47, s25, s39
	s_cselect_b32 s46, s24, s38
	s_cselect_b32 s45, s35, s3
	s_cselect_b32 s44, s34, s2
	s_add_i32 s23, 0, 0x14000
	v_add_u32_e32 v152, s13, v136
	v_add_u32_e32 v168, s23, v136
	ds_read_b128 v[140:143], v152
	ds_read_b128 v[144:147], v152 offset:1024
	ds_read_b128 v[148:151], v152 offset:2048
	ds_read_b128 v[152:155], v152 offset:3072
	ds_read_b128 v[156:159], v168
	ds_read_b128 v[160:163], v168 offset:1024
	ds_read_b128 v[164:167], v168 offset:2048
	ds_read_b128 v[168:171], v168 offset:3072
	v_lshl_add_u64 v[198:199], s[42:43], 0, v[132:133]
	s_add_i32 m0, s5, 0xc000
	ds_read_b128 v[172:175], v139
	ds_read_b128 v[176:179], v139 offset:1024
	ds_read_b128 v[180:183], v139 offset:2048
	ds_read_b128 v[184:187], v139 offset:3072
	ds_read_b128 v[188:191], v139 offset:4096
	ds_read_b128 v[192:195], v139 offset:5120
	ds_read_b128 v[202:205], v139 offset:6144
	ds_read_b128 v[206:209], v139 offset:7168
	global_load_lds_dwordx4 v[198:199], off
	v_lshl_add_u64 v[198:199], s[42:43], 0, v[134:135]
	s_add_i32 m0, s5, 0xe000
	s_nop 0
	global_load_lds_dwordx4 v[198:199], off
	s_waitcnt vmcnt(8)
	s_waitcnt lgkmcnt(0)
	v_mfma_f32_16x16x32_bf16 v[126:129], v[140:143], v[172:175], v[126:129]
	v_mfma_f32_16x16x32_bf16 v[122:125], v[148:151], v[172:175], v[122:125]
	v_mfma_f32_16x16x32_bf16 v[118:121], v[140:143], v[180:183], v[118:121]
	v_mfma_f32_16x16x32_bf16 v[114:117], v[148:151], v[180:183], v[114:117]
	s_barrier
	s_setprio 1
	s_waitcnt lgkmcnt(0)
	v_mfma_f32_16x16x32_bf16 v[106:109], v[140:143], v[188:191], v[106:109]
	v_mfma_f32_16x16x32_bf16 v[98:101], v[148:151], v[188:191], v[98:101]
	v_mfma_f32_16x16x32_bf16 v[88:91], v[140:143], v[202:205], v[88:91]
	v_mfma_f32_16x16x32_bf16 v[80:83], v[148:151], v[202:205], v[80:83]
	v_mfma_f32_16x16x32_bf16 v[126:129], v[144:147], v[176:179], v[126:129]
	v_mfma_f32_16x16x32_bf16 v[122:125], v[152:155], v[176:179], v[122:125]
	v_mfma_f32_16x16x32_bf16 v[118:121], v[144:147], v[184:187], v[118:121]
	v_mfma_f32_16x16x32_bf16 v[114:117], v[152:155], v[184:187], v[114:117]
	v_mfma_f32_16x16x32_bf16 v[106:109], v[144:147], v[192:195], v[106:109]
	v_mfma_f32_16x16x32_bf16 v[98:101], v[152:155], v[192:195], v[98:101]
	v_mfma_f32_16x16x32_bf16 v[88:91], v[144:147], v[206:209], v[88:91]
	v_mfma_f32_16x16x32_bf16 v[80:83], v[152:155], v[206:209], v[80:83]
	s_setprio 0
	s_setprio 1
	v_mfma_f32_16x16x32_bf16 v[110:113], v[156:159], v[172:175], v[110:113]
	v_mfma_f32_16x16x32_bf16 v[102:105], v[164:167], v[172:175], v[102:105]
	v_mfma_f32_16x16x32_bf16 v[92:95], v[156:159], v[180:183], v[92:95]
	v_mfma_f32_16x16x32_bf16 v[84:87], v[164:167], v[180:183], v[84:87]
	v_mfma_f32_16x16x32_bf16 v[76:79], v[156:159], v[188:191], v[76:79]
	v_mfma_f32_16x16x32_bf16 v[72:75], v[164:167], v[188:191], v[72:75]
	v_mfma_f32_16x16x32_bf16 v[68:71], v[156:159], v[202:205], v[68:71]
	v_mfma_f32_16x16x32_bf16 v[64:67], v[164:167], v[202:205], v[64:67]
	v_mfma_f32_16x16x32_bf16 v[110:113], v[160:163], v[176:179], v[110:113]
	v_mfma_f32_16x16x32_bf16 v[102:105], v[168:171], v[176:179], v[102:105]
	v_mfma_f32_16x16x32_bf16 v[92:95], v[160:163], v[184:187], v[92:95]
	v_mfma_f32_16x16x32_bf16 v[84:87], v[168:171], v[184:187], v[84:87]
	v_mfma_f32_16x16x32_bf16 v[76:79], v[160:163], v[192:195], v[76:79]
	v_mfma_f32_16x16x32_bf16 v[72:75], v[168:171], v[192:195], v[72:75]
	v_mfma_f32_16x16x32_bf16 v[68:71], v[160:163], v[206:209], v[68:71]
	v_mfma_f32_16x16x32_bf16 v[64:67], v[168:171], v[206:209], v[64:67]
	s_setprio 0
	s_barrier
	s_add_i32 s13, s13, s4
	v_lshl_add_u64 v[198:199], s[44:45], 0, v[96:97]
	s_mov_b32 m0, s13
	ds_read_b128 v[172:175], v139 offset:16384
	ds_read_b128 v[176:179], v139 offset:17408
	ds_read_b128 v[180:183], v139 offset:18432
	ds_read_b128 v[184:187], v139 offset:19456
	ds_read_b128 v[188:191], v139 offset:20480
	ds_read_b128 v[192:195], v139 offset:21504
	ds_read_b128 v[202:205], v139 offset:22528
	ds_read_b128 v[206:209], v139 offset:23552
	global_load_lds_dwordx4 v[198:199], off
	s_add_i32 m0, s13, 0x2000
	s_add_u32 s42, s44, 0x160000
	v_lshl_add_u64 v[200:201], s[44:45], 0, v[130:131]
	s_addc_u32 s43, s45, 0
	s_add_i32 s13, s23, s4
	global_load_lds_dwordx4 v[200:201], off
	v_lshl_add_u64 v[214:215], s[42:43], 0, v[96:97]
	s_mov_b32 m0, s13
	v_lshl_add_u64 v[216:217], s[46:47], 0, v[130:131]
	global_load_lds_dwordx4 v[214:215], off
	v_lshl_add_u64 v[214:215], s[42:43], 0, v[130:131]
	s_add_i32 m0, s13, 0x2000
	s_nop 0
	global_load_lds_dwordx4 v[214:215], off
	v_lshl_add_u64 v[214:215], s[46:47], 0, v[96:97]
	s_mov_b32 m0, s5
	s_nop 0
	global_load_lds_dwordx4 v[214:215], off
	s_mov_b32 m0, s17
	s_nop 0
	global_load_lds_dwordx4 v[216:217], off
	s_waitcnt vmcnt(8)
	s_waitcnt lgkmcnt(0)
	v_mfma_f32_16x16x32_bf16 v[60:63], v[140:143], v[172:175], v[60:63]
	v_mfma_f32_16x16x32_bf16 v[56:59], v[148:151], v[172:175], v[56:59]
	v_mfma_f32_16x16x32_bf16 v[52:55], v[140:143], v[180:183], v[52:55]
	v_mfma_f32_16x16x32_bf16 v[48:51], v[148:151], v[180:183], v[48:51]
	s_barrier
	s_setprio 1
	s_waitcnt lgkmcnt(0)
	v_mfma_f32_16x16x32_bf16 v[36:39], v[140:143], v[188:191], v[36:39]
	v_mfma_f32_16x16x32_bf16 v[32:35], v[148:151], v[188:191], v[32:35]
	v_mfma_f32_16x16x32_bf16 v[20:23], v[140:143], v[202:205], v[20:23]
	v_mfma_f32_16x16x32_bf16 v[16:19], v[148:151], v[202:205], v[16:19]
	v_mfma_f32_16x16x32_bf16 v[60:63], v[144:147], v[176:179], v[60:63]
	v_mfma_f32_16x16x32_bf16 v[56:59], v[152:155], v[176:179], v[56:59]
	v_mfma_f32_16x16x32_bf16 v[52:55], v[144:147], v[184:187], v[52:55]
	v_mfma_f32_16x16x32_bf16 v[48:51], v[152:155], v[184:187], v[48:51]
	v_mfma_f32_16x16x32_bf16 v[36:39], v[144:147], v[192:195], v[36:39]
	v_mfma_f32_16x16x32_bf16 v[32:35], v[152:155], v[192:195], v[32:35]
	v_mfma_f32_16x16x32_bf16 v[20:23], v[144:147], v[206:209], v[20:23]
	v_mfma_f32_16x16x32_bf16 v[16:19], v[152:155], v[206:209], v[16:19]
	s_setprio 0
	s_setprio 1
	v_mfma_f32_16x16x32_bf16 v[44:47], v[156:159], v[172:175], v[44:47]
	v_mfma_f32_16x16x32_bf16 v[40:43], v[164:167], v[172:175], v[40:43]
	v_mfma_f32_16x16x32_bf16 v[28:31], v[156:159], v[180:183], v[28:31]
	v_mfma_f32_16x16x32_bf16 v[24:27], v[164:167], v[180:183], v[24:27]
	v_mfma_f32_16x16x32_bf16 v[12:15], v[156:159], v[188:191], v[12:15]
	v_mfma_f32_16x16x32_bf16 v[8:11], v[164:167], v[188:191], v[8:11]
	v_mfma_f32_16x16x32_bf16 v[4:7], v[156:159], v[202:205], v[4:7]
	v_mfma_f32_16x16x32_bf16 v[0:3], v[164:167], v[202:205], v[0:3]
	v_mfma_f32_16x16x32_bf16 v[44:47], v[160:163], v[176:179], v[44:47]
	v_mfma_f32_16x16x32_bf16 v[40:43], v[168:171], v[176:179], v[40:43]
	v_mfma_f32_16x16x32_bf16 v[28:31], v[160:163], v[184:187], v[28:31]
	v_mfma_f32_16x16x32_bf16 v[24:27], v[168:171], v[184:187], v[24:27]
	v_mfma_f32_16x16x32_bf16 v[12:15], v[160:163], v[192:195], v[12:15]
	v_mfma_f32_16x16x32_bf16 v[8:11], v[168:171], v[192:195], v[8:11]
	v_mfma_f32_16x16x32_bf16 v[4:7], v[160:163], v[206:209], v[4:7]
	v_mfma_f32_16x16x32_bf16 v[0:3], v[168:171], v[206:209], v[0:3]
	s_setprio 0
	s_barrier
	s_add_i32 s13, 0, 0x18000
	s_add_i32 s23, 0, 0x1c000
	v_add_u32_e32 v152, s13, v136
	v_add_u32_e32 v168, s23, v136
	ds_read_b128 v[140:143], v152
	ds_read_b128 v[144:147], v152 offset:1024
	ds_read_b128 v[148:151], v152 offset:2048
	ds_read_b128 v[152:155], v152 offset:3072
	ds_read_b128 v[156:159], v168
	ds_read_b128 v[160:163], v168 offset:1024
	ds_read_b128 v[164:167], v168 offset:2048
	ds_read_b128 v[168:171], v168 offset:3072
	s_add_u32 s42, s46, 0x160000
	s_addc_u32 s43, s47, 0
	s_mov_b32 m0, s18
	v_lshl_add_u64 v[218:219], s[42:43], 0, v[96:97]
	ds_read_b128 v[172:175], v139 offset:32768
	ds_read_b128 v[176:179], v139 offset:33792
	ds_read_b128 v[180:183], v139 offset:34816
	ds_read_b128 v[184:187], v139 offset:35840
	ds_read_b128 v[188:191], v139 offset:36864
	ds_read_b128 v[192:195], v139 offset:37888
	ds_read_b128 v[202:205], v139 offset:38912
	ds_read_b128 v[206:209], v139 offset:39936
	global_load_lds_dwordx4 v[218:219], off
	v_lshl_add_u64 v[218:219], s[42:43], 0, v[130:131]
	s_mov_b32 m0, s19
	s_nop 0
	global_load_lds_dwordx4 v[218:219], off
	s_waitcnt vmcnt(8)
	s_waitcnt lgkmcnt(0)
	v_mfma_f32_16x16x32_bf16 v[126:129], v[140:143], v[172:175], v[126:129]
	v_mfma_f32_16x16x32_bf16 v[122:125], v[148:151], v[172:175], v[122:125]
	v_mfma_f32_16x16x32_bf16 v[118:121], v[140:143], v[180:183], v[118:121]
	v_mfma_f32_16x16x32_bf16 v[114:117], v[148:151], v[180:183], v[114:117]
	s_barrier
	s_setprio 1
	s_waitcnt lgkmcnt(0)
	v_mfma_f32_16x16x32_bf16 v[106:109], v[140:143], v[188:191], v[106:109]
	v_mfma_f32_16x16x32_bf16 v[98:101], v[148:151], v[188:191], v[98:101]
	v_mfma_f32_16x16x32_bf16 v[88:91], v[140:143], v[202:205], v[88:91]
	v_mfma_f32_16x16x32_bf16 v[80:83], v[148:151], v[202:205], v[80:83]
	v_mfma_f32_16x16x32_bf16 v[126:129], v[144:147], v[176:179], v[126:129]
	v_mfma_f32_16x16x32_bf16 v[122:125], v[152:155], v[176:179], v[122:125]
	v_mfma_f32_16x16x32_bf16 v[118:121], v[144:147], v[184:187], v[118:121]
	v_mfma_f32_16x16x32_bf16 v[114:117], v[152:155], v[184:187], v[114:117]
	v_mfma_f32_16x16x32_bf16 v[106:109], v[144:147], v[192:195], v[106:109]
	v_mfma_f32_16x16x32_bf16 v[98:101], v[152:155], v[192:195], v[98:101]
	v_mfma_f32_16x16x32_bf16 v[88:91], v[144:147], v[206:209], v[88:91]
	v_mfma_f32_16x16x32_bf16 v[80:83], v[152:155], v[206:209], v[80:83]
	s_setprio 0
	s_setprio 1
	v_mfma_f32_16x16x32_bf16 v[110:113], v[156:159], v[172:175], v[110:113]
	v_mfma_f32_16x16x32_bf16 v[102:105], v[164:167], v[172:175], v[102:105]
	v_mfma_f32_16x16x32_bf16 v[92:95], v[156:159], v[180:183], v[92:95]
	v_mfma_f32_16x16x32_bf16 v[84:87], v[164:167], v[180:183], v[84:87]
	v_mfma_f32_16x16x32_bf16 v[76:79], v[156:159], v[188:191], v[76:79]
	v_mfma_f32_16x16x32_bf16 v[72:75], v[164:167], v[188:191], v[72:75]
	v_mfma_f32_16x16x32_bf16 v[68:71], v[156:159], v[202:205], v[68:71]
	v_mfma_f32_16x16x32_bf16 v[64:67], v[164:167], v[202:205], v[64:67]
	v_mfma_f32_16x16x32_bf16 v[110:113], v[160:163], v[176:179], v[110:113]
	v_mfma_f32_16x16x32_bf16 v[102:105], v[168:171], v[176:179], v[102:105]
	v_mfma_f32_16x16x32_bf16 v[92:95], v[160:163], v[184:187], v[92:95]
	v_mfma_f32_16x16x32_bf16 v[84:87], v[168:171], v[184:187], v[84:87]
	v_mfma_f32_16x16x32_bf16 v[76:79], v[160:163], v[192:195], v[76:79]
	v_mfma_f32_16x16x32_bf16 v[72:75], v[168:171], v[192:195], v[72:75]
	v_mfma_f32_16x16x32_bf16 v[68:71], v[160:163], v[206:209], v[68:71]
	v_mfma_f32_16x16x32_bf16 v[64:67], v[168:171], v[206:209], v[64:67]
	s_setprio 0
	s_barrier
	s_add_i32 s13, s13, s4
	v_lshl_add_u64 v[198:199], v[198:199], 0, s[30:31]
	s_mov_b32 m0, s13
	ds_read_b128 v[172:175], v139 offset:49152
	ds_read_b128 v[176:179], v139 offset:50176
	ds_read_b128 v[180:183], v139 offset:51200
	ds_read_b128 v[184:187], v139 offset:52224
	ds_read_b128 v[188:191], v139 offset:53248
	ds_read_b128 v[192:195], v139 offset:54272
	ds_read_b128 v[202:205], v139 offset:55296
	ds_read_b128 v[206:209], v139 offset:56320
	global_load_lds_dwordx4 v[198:199], off
	s_add_i32 m0, s13, 0x2000
	s_add_u32 s42, s44, 0x160080
	v_lshl_add_u64 v[198:199], v[200:201], 0, s[30:31]
	s_addc_u32 s43, s45, 0
	s_add_i32 s13, s23, s4
	global_load_lds_dwordx4 v[198:199], off
	v_lshl_add_u64 v[198:199], s[42:43], 0, v[96:97]
	s_mov_b32 m0, s13
	s_nop 0
	global_load_lds_dwordx4 v[198:199], off
	v_lshl_add_u64 v[198:199], s[42:43], 0, v[130:131]
	s_add_i32 m0, s13, 0x2000
	s_nop 0
	global_load_lds_dwordx4 v[198:199], off
	v_lshl_add_u64 v[198:199], v[214:215], 0, s[30:31]
	s_mov_b32 m0, s37
	s_nop 0
	global_load_lds_dwordx4 v[198:199], off
	v_lshl_add_u64 v[198:199], v[216:217], 0, s[30:31]
	s_mov_b32 m0, s40
	s_nop 0
	global_load_lds_dwordx4 v[198:199], off
	s_waitcnt vmcnt(8)
	s_waitcnt lgkmcnt(0)
	v_mfma_f32_16x16x32_bf16 v[60:63], v[140:143], v[172:175], v[60:63]
	v_mfma_f32_16x16x32_bf16 v[56:59], v[148:151], v[172:175], v[56:59]
	v_mfma_f32_16x16x32_bf16 v[52:55], v[140:143], v[180:183], v[52:55]
	v_mfma_f32_16x16x32_bf16 v[48:51], v[148:151], v[180:183], v[48:51]
	s_barrier
	s_setprio 1
	s_waitcnt lgkmcnt(0)
	v_mfma_f32_16x16x32_bf16 v[36:39], v[140:143], v[188:191], v[36:39]
	v_mfma_f32_16x16x32_bf16 v[32:35], v[148:151], v[188:191], v[32:35]
	v_mfma_f32_16x16x32_bf16 v[20:23], v[140:143], v[202:205], v[20:23]
	v_mfma_f32_16x16x32_bf16 v[16:19], v[148:151], v[202:205], v[16:19]
	v_mfma_f32_16x16x32_bf16 v[60:63], v[144:147], v[176:179], v[60:63]
	v_mfma_f32_16x16x32_bf16 v[56:59], v[152:155], v[176:179], v[56:59]
	v_mfma_f32_16x16x32_bf16 v[52:55], v[144:147], v[184:187], v[52:55]
	v_mfma_f32_16x16x32_bf16 v[48:51], v[152:155], v[184:187], v[48:51]
	v_mfma_f32_16x16x32_bf16 v[36:39], v[144:147], v[192:195], v[36:39]
	v_mfma_f32_16x16x32_bf16 v[32:35], v[152:155], v[192:195], v[32:35]
	v_mfma_f32_16x16x32_bf16 v[20:23], v[144:147], v[206:209], v[20:23]
	v_mfma_f32_16x16x32_bf16 v[16:19], v[152:155], v[206:209], v[16:19]
	s_setprio 0
	s_setprio 1
	v_mfma_f32_16x16x32_bf16 v[44:47], v[156:159], v[172:175], v[44:47]
	v_mfma_f32_16x16x32_bf16 v[40:43], v[164:167], v[172:175], v[40:43]
	v_mfma_f32_16x16x32_bf16 v[28:31], v[156:159], v[180:183], v[28:31]
	v_mfma_f32_16x16x32_bf16 v[24:27], v[164:167], v[180:183], v[24:27]
	v_mfma_f32_16x16x32_bf16 v[12:15], v[156:159], v[188:191], v[12:15]
	v_mfma_f32_16x16x32_bf16 v[8:11], v[164:167], v[188:191], v[8:11]
	v_mfma_f32_16x16x32_bf16 v[4:7], v[156:159], v[202:205], v[4:7]
	v_mfma_f32_16x16x32_bf16 v[0:3], v[164:167], v[202:205], v[0:3]
	v_mfma_f32_16x16x32_bf16 v[44:47], v[160:163], v[176:179], v[44:47]
	v_mfma_f32_16x16x32_bf16 v[40:43], v[168:171], v[176:179], v[40:43]
	v_mfma_f32_16x16x32_bf16 v[28:31], v[160:163], v[184:187], v[28:31]
	v_mfma_f32_16x16x32_bf16 v[24:27], v[168:171], v[184:187], v[24:27]
	v_mfma_f32_16x16x32_bf16 v[12:15], v[160:163], v[192:195], v[12:15]
	v_mfma_f32_16x16x32_bf16 v[8:11], v[168:171], v[192:195], v[8:11]
	v_mfma_f32_16x16x32_bf16 v[4:7], v[160:163], v[206:209], v[4:7]
	v_mfma_f32_16x16x32_bf16 v[0:3], v[168:171], v[206:209], v[0:3]
	s_setprio 0
	s_barrier
	s_add_i32 s6, s6, 2
	s_add_u32 s2, s2, 0x100
	s_addc_u32 s3, s3, 0
	s_cmp_gt_u32 s6, 5
	s_mov_b64 s[42:43], s[38:39]
	s_cbranch_scc0 .LBB0_1333
	s_and_b64 vcc, exec, s[14:15]
	s_cbranch_vccz .LBB0_1336
	s_barrier

.LBB0_1357:
	s_add_u32 s3, s14, s34
	s_addc_u32 s6, s15, s35
	s_add_u32 s3, s3, 0x100
	s_addc_u32 s6, s6, 0
	s_add_u32 s42, s57, s34
	s_addc_u32 s43, s58, s35
	s_add_i32 s59, 0, 0x10000
	s_cmpk_eq_i32 s34, 0x2b00
	s_cselect_b32 s45, s23, s6
	s_cselect_b32 s44, s22, s3
	v_add_u32_e32 v146, s59, v144
	s_cselect_b32 s43, s25, s43
	s_cselect_b32 s42, s24, s42
	s_add_i32 s3, 0, 0x14000
	ds_read_b128 v[154:157], v146
	ds_read_b128 v[158:161], v146 offset:1024
	ds_read_b128 v[162:165], v146 offset:2048
	ds_read_b128 v[166:169], v146 offset:3072
	v_add_u32_e32 v146, s3, v144
	ds_read_b128 v[174:177], v146
	ds_read_b128 v[178:181], v146 offset:1024
	ds_read_b128 v[182:185], v146 offset:2048
	ds_read_b128 v[186:189], v146 offset:3072
	v_lshl_add_u64 v[146:147], v[140:141], 0, s[34:35]
	s_add_i32 m0, s17, 0xc000
	ds_read_b128 v[190:193], v145
	ds_read_b128 v[202:205], v145 offset:1024
	ds_read_b128 v[206:209], v145 offset:2048
	ds_read_b128 v[214:217], v145 offset:3072
	ds_read_b128 v[218:221], v145 offset:4096
	ds_read_b128 v[222:225], v145 offset:5120
	ds_read_b128 v[226:229], v145 offset:6144
	ds_read_b128 v[230:233], v145 offset:7168
	global_load_lds_dwordx4 v[146:147], off
	v_lshl_add_u64 v[146:147], v[142:143], 0, s[34:35]
	s_add_i32 m0, s17, 0xe000
	s_nop 0
	global_load_lds_dwordx4 v[146:147], off
	s_waitcnt vmcnt(8)
	s_waitcnt lgkmcnt(0)
	v_mfma_f32_16x16x32_bf16 v[110:113], v[154:157], v[190:193], v[110:113]
	v_mfma_f32_16x16x32_bf16 v[106:109], v[162:165], v[190:193], v[106:109]
	v_mfma_f32_16x16x32_bf16 v[118:121], v[154:157], v[206:209], v[118:121]
	v_mfma_f32_16x16x32_bf16 v[114:117], v[162:165], v[206:209], v[114:117]
	s_barrier
	s_setprio 1
	s_waitcnt lgkmcnt(0)
	v_mfma_f32_16x16x32_bf16 v[126:129], v[154:157], v[218:221], v[126:129]
	v_mfma_f32_16x16x32_bf16 v[122:125], v[162:165], v[218:221], v[122:125]
	v_mfma_f32_16x16x32_bf16 v[92:95], v[154:157], v[226:229], v[92:95]
	v_mfma_f32_16x16x32_bf16 v[88:91], v[162:165], v[226:229], v[88:91]
	v_mfma_f32_16x16x32_bf16 v[110:113], v[158:161], v[202:205], v[110:113]
	v_mfma_f32_16x16x32_bf16 v[106:109], v[166:169], v[202:205], v[106:109]
	v_mfma_f32_16x16x32_bf16 v[118:121], v[158:161], v[214:217], v[118:121]
	v_mfma_f32_16x16x32_bf16 v[114:117], v[166:169], v[214:217], v[114:117]
	v_mfma_f32_16x16x32_bf16 v[126:129], v[158:161], v[222:225], v[126:129]
	v_mfma_f32_16x16x32_bf16 v[122:125], v[166:169], v[222:225], v[122:125]
	v_mfma_f32_16x16x32_bf16 v[92:95], v[158:161], v[230:233], v[92:95]
	v_mfma_f32_16x16x32_bf16 v[88:91], v[166:169], v[230:233], v[88:91]
	s_setprio 0
	s_setprio 1
	v_mfma_f32_16x16x32_bf16 v[4:7], v[174:177], v[190:193], v[4:7]
	v_mfma_f32_16x16x32_bf16 v[0:3], v[182:185], v[190:193], v[0:3]
	v_mfma_f32_16x16x32_bf16 v[12:15], v[174:177], v[206:209], v[12:15]
	v_mfma_f32_16x16x32_bf16 v[8:11], v[182:185], v[206:209], v[8:11]
	v_mfma_f32_16x16x32_bf16 v[24:27], v[174:177], v[218:221], v[24:27]
	v_mfma_f32_16x16x32_bf16 v[20:23], v[182:185], v[218:221], v[20:23]
	v_mfma_f32_16x16x32_bf16 v[40:43], v[174:177], v[226:229], v[40:43]
	v_mfma_f32_16x16x32_bf16 v[36:39], v[182:185], v[226:229], v[36:39]
	v_mfma_f32_16x16x32_bf16 v[4:7], v[178:181], v[202:205], v[4:7]
	v_mfma_f32_16x16x32_bf16 v[0:3], v[186:189], v[202:205], v[0:3]
	v_mfma_f32_16x16x32_bf16 v[12:15], v[178:181], v[214:217], v[12:15]
	v_mfma_f32_16x16x32_bf16 v[8:11], v[186:189], v[214:217], v[8:11]
	v_mfma_f32_16x16x32_bf16 v[24:27], v[178:181], v[222:225], v[24:27]
	v_mfma_f32_16x16x32_bf16 v[20:23], v[186:189], v[222:225], v[20:23]
	v_mfma_f32_16x16x32_bf16 v[40:43], v[178:181], v[230:233], v[40:43]
	v_mfma_f32_16x16x32_bf16 v[36:39], v[186:189], v[230:233], v[36:39]
	s_setprio 0
	s_barrier
	s_add_i32 s6, s59, s5
	v_lshl_add_u64 v[146:147], s[42:43], 0, v[96:97]
	s_mov_b32 m0, s6
	ds_read_b128 v[190:193], v145 offset:16384
	ds_read_b128 v[202:205], v145 offset:17408
	ds_read_b128 v[206:209], v145 offset:18432
	ds_read_b128 v[214:217], v145 offset:19456
	ds_read_b128 v[218:221], v145 offset:20480
	ds_read_b128 v[222:225], v145 offset:21504
	ds_read_b128 v[226:229], v145 offset:22528
	ds_read_b128 v[230:233], v145 offset:23552
	global_load_lds_dwordx4 v[146:147], off
	s_add_i32 m0, s6, 0x2000
	s_add_u32 s60, s42, 0x160000
	v_lshl_add_u64 v[150:151], s[42:43], 0, v[130:131]
	s_addc_u32 s61, s43, 0
	s_add_i32 s3, s3, s5
	global_load_lds_dwordx4 v[150:151], off
	v_lshl_add_u64 v[170:171], s[60:61], 0, v[96:97]
	s_mov_b32 m0, s3
	v_lshl_add_u64 v[194:195], s[44:45], 0, v[132:133]
	global_load_lds_dwordx4 v[170:171], off
	v_lshl_add_u64 v[170:171], s[60:61], 0, v[130:131]
	s_add_i32 m0, s3, 0x2000
	s_nop 0
	global_load_lds_dwordx4 v[170:171], off
	v_lshl_add_u64 v[170:171], s[44:45], 0, v[134:135]
	s_mov_b32 m0, s17
	s_nop 0
	global_load_lds_dwordx4 v[170:171], off
	s_mov_b32 m0, s18
	s_nop 0
	global_load_lds_dwordx4 v[194:195], off
	s_waitcnt vmcnt(8)
	s_waitcnt lgkmcnt(0)
	v_mfma_f32_16x16x32_bf16 v[102:105], v[154:157], v[190:193], v[102:105]
	v_mfma_f32_16x16x32_bf16 v[98:101], v[162:165], v[190:193], v[98:101]
	v_mfma_f32_16x16x32_bf16 v[84:87], v[154:157], v[206:209], v[84:87]
	v_mfma_f32_16x16x32_bf16 v[80:83], v[162:165], v[206:209], v[80:83]
	s_barrier
	s_setprio 1
	s_waitcnt lgkmcnt(0)
	v_mfma_f32_16x16x32_bf16 v[68:71], v[154:157], v[218:221], v[68:71]
	v_mfma_f32_16x16x32_bf16 v[64:67], v[162:165], v[218:221], v[64:67]
	v_mfma_f32_16x16x32_bf16 v[44:47], v[154:157], v[226:229], v[44:47]
	v_mfma_f32_16x16x32_bf16 v[32:35], v[162:165], v[226:229], v[32:35]
	v_mfma_f32_16x16x32_bf16 v[102:105], v[158:161], v[202:205], v[102:105]
	v_mfma_f32_16x16x32_bf16 v[98:101], v[166:169], v[202:205], v[98:101]
	v_mfma_f32_16x16x32_bf16 v[84:87], v[158:161], v[214:217], v[84:87]
	v_mfma_f32_16x16x32_bf16 v[80:83], v[166:169], v[214:217], v[80:83]
	v_mfma_f32_16x16x32_bf16 v[68:71], v[158:161], v[222:225], v[68:71]
	v_mfma_f32_16x16x32_bf16 v[64:67], v[166:169], v[222:225], v[64:67]
	v_mfma_f32_16x16x32_bf16 v[44:47], v[158:161], v[230:233], v[44:47]
	v_mfma_f32_16x16x32_bf16 v[32:35], v[166:169], v[230:233], v[32:35]
	s_setprio 0
	s_setprio 1
	v_mfma_f32_16x16x32_bf16 v[60:63], v[174:177], v[190:193], v[60:63]
	v_mfma_f32_16x16x32_bf16 v[56:59], v[182:185], v[190:193], v[56:59]
	v_mfma_f32_16x16x32_bf16 v[76:79], v[174:177], v[206:209], v[76:79]
	v_mfma_f32_16x16x32_bf16 v[72:75], v[182:185], v[206:209], v[72:75]
	v_mfma_f32_16x16x32_bf16 v[52:55], v[174:177], v[218:221], v[52:55]
	v_mfma_f32_16x16x32_bf16 v[48:51], v[182:185], v[218:221], v[48:51]
	v_mfma_f32_16x16x32_bf16 v[28:31], v[174:177], v[226:229], v[28:31]
	v_mfma_f32_16x16x32_bf16 v[16:19], v[182:185], v[226:229], v[16:19]
	v_mfma_f32_16x16x32_bf16 v[60:63], v[178:181], v[202:205], v[60:63]
	v_mfma_f32_16x16x32_bf16 v[56:59], v[186:189], v[202:205], v[56:59]
	v_mfma_f32_16x16x32_bf16 v[76:79], v[178:181], v[214:217], v[76:79]
	v_mfma_f32_16x16x32_bf16 v[72:75], v[186:189], v[214:217], v[72:75]
	v_mfma_f32_16x16x32_bf16 v[52:55], v[178:181], v[222:225], v[52:55]
	v_mfma_f32_16x16x32_bf16 v[48:51], v[186:189], v[222:225], v[48:51]
	v_mfma_f32_16x16x32_bf16 v[28:31], v[178:181], v[230:233], v[28:31]
	v_mfma_f32_16x16x32_bf16 v[16:19], v[186:189], v[230:233], v[16:19]
	s_setprio 0
	s_barrier
	s_add_i32 s3, 0, 0x18000
	v_add_u32_e32 v149, s3, v144
	s_add_i32 s6, 0, 0x1c000
	ds_read_b128 v[154:157], v149
	ds_read_b128 v[158:161], v149 offset:1024
	ds_read_b128 v[162:165], v149 offset:2048
	ds_read_b128 v[166:169], v149 offset:3072
	v_add_u32_e32 v149, s6, v144
	ds_read_b128 v[174:177], v149
	ds_read_b128 v[178:181], v149 offset:1024
	ds_read_b128 v[182:185], v149 offset:2048
	ds_read_b128 v[186:189], v149 offset:3072
	s_add_u32 s44, s44, 0x160000
	s_addc_u32 s45, s45, 0
	s_mov_b32 m0, s19
	v_lshl_add_u64 v[198:199], s[44:45], 0, v[134:135]
	ds_read_b128 v[190:193], v145 offset:32768
	ds_read_b128 v[202:205], v145 offset:33792
	ds_read_b128 v[206:209], v145 offset:34816
	ds_read_b128 v[214:217], v145 offset:35840
	ds_read_b128 v[218:221], v145 offset:36864
	ds_read_b128 v[222:225], v145 offset:37888
	ds_read_b128 v[226:229], v145 offset:38912
	ds_read_b128 v[230:233], v145 offset:39936
	global_load_lds_dwordx4 v[198:199], off
	v_lshl_add_u64 v[198:199], s[44:45], 0, v[132:133]
	s_mov_b32 m0, s20
	s_nop 0
	global_load_lds_dwordx4 v[198:199], off
	s_waitcnt vmcnt(8)
	s_waitcnt lgkmcnt(0)
	v_mfma_f32_16x16x32_bf16 v[110:113], v[154:157], v[190:193], v[110:113]
	v_mfma_f32_16x16x32_bf16 v[106:109], v[162:165], v[190:193], v[106:109]
	v_mfma_f32_16x16x32_bf16 v[118:121], v[154:157], v[206:209], v[118:121]
	v_mfma_f32_16x16x32_bf16 v[114:117], v[162:165], v[206:209], v[114:117]
	s_barrier
	s_setprio 1
	s_waitcnt lgkmcnt(0)
	v_mfma_f32_16x16x32_bf16 v[126:129], v[154:157], v[218:221], v[126:129]
	v_mfma_f32_16x16x32_bf16 v[122:125], v[162:165], v[218:221], v[122:125]
	v_mfma_f32_16x16x32_bf16 v[92:95], v[154:157], v[226:229], v[92:95]
	v_mfma_f32_16x16x32_bf16 v[88:91], v[162:165], v[226:229], v[88:91]
	v_mfma_f32_16x16x32_bf16 v[110:113], v[158:161], v[202:205], v[110:113]
	v_mfma_f32_16x16x32_bf16 v[106:109], v[166:169], v[202:205], v[106:109]
	v_mfma_f32_16x16x32_bf16 v[118:121], v[158:161], v[214:217], v[118:121]
	v_mfma_f32_16x16x32_bf16 v[114:117], v[166:169], v[214:217], v[114:117]
	v_mfma_f32_16x16x32_bf16 v[126:129], v[158:161], v[222:225], v[126:129]
	v_mfma_f32_16x16x32_bf16 v[122:125], v[166:169], v[222:225], v[122:125]
	v_mfma_f32_16x16x32_bf16 v[92:95], v[158:161], v[230:233], v[92:95]
	v_mfma_f32_16x16x32_bf16 v[88:91], v[166:169], v[230:233], v[88:91]
	s_setprio 0
	s_setprio 1
	v_mfma_f32_16x16x32_bf16 v[4:7], v[174:177], v[190:193], v[4:7]
	v_mfma_f32_16x16x32_bf16 v[0:3], v[182:185], v[190:193], v[0:3]
	v_mfma_f32_16x16x32_bf16 v[12:15], v[174:177], v[206:209], v[12:15]
	v_mfma_f32_16x16x32_bf16 v[8:11], v[182:185], v[206:209], v[8:11]
	v_mfma_f32_16x16x32_bf16 v[24:27], v[174:177], v[218:221], v[24:27]
	v_mfma_f32_16x16x32_bf16 v[20:23], v[182:185], v[218:221], v[20:23]
	v_mfma_f32_16x16x32_bf16 v[40:43], v[174:177], v[226:229], v[40:43]
	v_mfma_f32_16x16x32_bf16 v[36:39], v[182:185], v[226:229], v[36:39]
	v_mfma_f32_16x16x32_bf16 v[4:7], v[178:181], v[202:205], v[4:7]
	v_mfma_f32_16x16x32_bf16 v[0:3], v[186:189], v[202:205], v[0:3]
	v_mfma_f32_16x16x32_bf16 v[12:15], v[178:181], v[214:217], v[12:15]
	v_mfma_f32_16x16x32_bf16 v[8:11], v[186:189], v[214:217], v[8:11]
	v_mfma_f32_16x16x32_bf16 v[24:27], v[178:181], v[222:225], v[24:27]
	v_mfma_f32_16x16x32_bf16 v[20:23], v[186:189], v[222:225], v[20:23]
	v_mfma_f32_16x16x32_bf16 v[40:43], v[178:181], v[230:233], v[40:43]
	v_mfma_f32_16x16x32_bf16 v[36:39], v[186:189], v[230:233], v[36:39]
	s_setprio 0
	s_barrier
	s_add_i32 s3, s3, s5
	v_lshl_add_u64 v[146:147], v[146:147], 0, s[30:31]
	s_mov_b32 m0, s3
	ds_read_b128 v[190:193], v145 offset:49152
	ds_read_b128 v[202:205], v145 offset:50176
	ds_read_b128 v[206:209], v145 offset:51200
	ds_read_b128 v[214:217], v145 offset:52224
	ds_read_b128 v[218:221], v145 offset:53248
	ds_read_b128 v[222:225], v145 offset:54272
	ds_read_b128 v[226:229], v145 offset:55296
	ds_read_b128 v[230:233], v145 offset:56320
	global_load_lds_dwordx4 v[146:147], off
	s_add_i32 m0, s3, 0x2000
	s_add_u32 s42, s42, 0x160080
	v_lshl_add_u64 v[146:147], v[150:151], 0, s[30:31]
	s_addc_u32 s43, s43, 0
	s_add_i32 s3, s6, s5
	global_load_lds_dwordx4 v[146:147], off
	v_lshl_add_u64 v[146:147], s[42:43], 0, v[96:97]
	s_mov_b32 m0, s3
	s_nop 0
	global_load_lds_dwordx4 v[146:147], off
	v_lshl_add_u64 v[146:147], s[42:43], 0, v[130:131]
	s_add_i32 m0, s3, 0x2000
	s_nop 0
	global_load_lds_dwordx4 v[146:147], off
	v_lshl_add_u64 v[146:147], v[170:171], 0, s[30:31]
	s_mov_b32 m0, s37
	s_nop 0
	global_load_lds_dwordx4 v[146:147], off
	v_lshl_add_u64 v[146:147], v[194:195], 0, s[30:31]
	s_mov_b32 m0, s52
	s_nop 0
	global_load_lds_dwordx4 v[146:147], off
	s_waitcnt vmcnt(8)
	s_waitcnt lgkmcnt(0)
	v_mfma_f32_16x16x32_bf16 v[102:105], v[154:157], v[190:193], v[102:105]
	v_mfma_f32_16x16x32_bf16 v[98:101], v[162:165], v[190:193], v[98:101]
	v_mfma_f32_16x16x32_bf16 v[84:87], v[154:157], v[206:209], v[84:87]
	v_mfma_f32_16x16x32_bf16 v[80:83], v[162:165], v[206:209], v[80:83]
	s_barrier
	s_setprio 1
	s_waitcnt lgkmcnt(0)
	v_mfma_f32_16x16x32_bf16 v[68:71], v[154:157], v[218:221], v[68:71]
	v_mfma_f32_16x16x32_bf16 v[64:67], v[162:165], v[218:221], v[64:67]
	v_mfma_f32_16x16x32_bf16 v[44:47], v[154:157], v[226:229], v[44:47]
	v_mfma_f32_16x16x32_bf16 v[32:35], v[162:165], v[226:229], v[32:35]
	v_mfma_f32_16x16x32_bf16 v[102:105], v[158:161], v[202:205], v[102:105]
	v_mfma_f32_16x16x32_bf16 v[98:101], v[166:169], v[202:205], v[98:101]
	v_mfma_f32_16x16x32_bf16 v[84:87], v[158:161], v[214:217], v[84:87]
	v_mfma_f32_16x16x32_bf16 v[80:83], v[166:169], v[214:217], v[80:83]
	v_mfma_f32_16x16x32_bf16 v[68:71], v[158:161], v[222:225], v[68:71]
	v_mfma_f32_16x16x32_bf16 v[64:67], v[166:169], v[222:225], v[64:67]
	v_mfma_f32_16x16x32_bf16 v[44:47], v[158:161], v[230:233], v[44:47]
	v_mfma_f32_16x16x32_bf16 v[32:35], v[166:169], v[230:233], v[32:35]
	s_setprio 0
	s_setprio 1
	v_mfma_f32_16x16x32_bf16 v[60:63], v[174:177], v[190:193], v[60:63]
	v_mfma_f32_16x16x32_bf16 v[56:59], v[182:185], v[190:193], v[56:59]
	v_mfma_f32_16x16x32_bf16 v[76:79], v[174:177], v[206:209], v[76:79]
	v_mfma_f32_16x16x32_bf16 v[72:75], v[182:185], v[206:209], v[72:75]
	v_mfma_f32_16x16x32_bf16 v[52:55], v[174:177], v[218:221], v[52:55]
	v_mfma_f32_16x16x32_bf16 v[48:51], v[182:185], v[218:221], v[48:51]
	v_mfma_f32_16x16x32_bf16 v[28:31], v[174:177], v[226:229], v[28:31]
	v_mfma_f32_16x16x32_bf16 v[16:19], v[182:185], v[226:229], v[16:19]
	v_mfma_f32_16x16x32_bf16 v[60:63], v[178:181], v[202:205], v[60:63]
	v_mfma_f32_16x16x32_bf16 v[56:59], v[186:189], v[202:205], v[56:59]
	v_mfma_f32_16x16x32_bf16 v[76:79], v[178:181], v[214:217], v[76:79]
	v_mfma_f32_16x16x32_bf16 v[72:75], v[186:189], v[214:217], v[72:75]
	v_mfma_f32_16x16x32_bf16 v[52:55], v[178:181], v[222:225], v[52:55]
	v_mfma_f32_16x16x32_bf16 v[48:51], v[186:189], v[222:225], v[48:51]
	v_mfma_f32_16x16x32_bf16 v[28:31], v[178:181], v[230:233], v[28:31]
	v_mfma_f32_16x16x32_bf16 v[16:19], v[186:189], v[230:233], v[16:19]
	s_setprio 0
	s_barrier
	s_add_i32 s2, s2, 2
	s_add_u32 s34, s34, 0x100
	s_addc_u32 s35, s35, 0
	s_cmpk_gt_u32 s2, 0x55
	s_cbranch_scc0 .LBB0_1357
	s_and_b64 vcc, exec, s[12:13]
	s_cbranch_vccz .LBB0_1360
	s_barrier

.LBB0_1413:
	s_add_u32 s24, s22, 0x100
	s_addc_u32 s25, s23, 0
	s_add_i32 s45, 0, 0x10000
	s_cmpk_eq_i32 s6, 0x54
	s_cselect_b32 s39, s13, s25
	s_cselect_b32 s38, s12, s24
	s_cselect_b32 s35, s15, s3
	s_cselect_b32 s34, s14, s2
	s_add_i32 s46, 0, 0x14000
	v_add_u32_e32 v142, s45, v155
	v_add_u32_e32 v152, s46, v155
	ds_read_b128 v[130:133], v142
	ds_read_b128 v[134:137], v142 offset:1024
	ds_read_b128 v[138:141], v142 offset:2048
	ds_read_b128 v[142:145], v142 offset:3072
	ds_read_b128 v[158:161], v152
	ds_read_b128 v[162:165], v152 offset:1024
	ds_read_b128 v[166:169], v152 offset:2048
	ds_read_b128 v[170:173], v152 offset:3072
	v_lshl_add_u64 v[152:153], s[22:23], 0, v[148:149]
	s_add_i32 m0, s5, 0xc000
	ds_read_b128 v[174:177], v157
	ds_read_b128 v[178:181], v157 offset:1024
	ds_read_b128 v[182:185], v157 offset:2048
	ds_read_b128 v[186:189], v157 offset:3072
	ds_read_b128 v[190:193], v157 offset:4096
	ds_read_b128 v[202:205], v157 offset:5120
	ds_read_b128 v[206:209], v157 offset:6144
	ds_read_b128 v[214:217], v157 offset:7168
	global_load_lds_dwordx4 v[152:153], off
	v_lshl_add_u64 v[152:153], s[22:23], 0, v[150:151]
	s_add_i32 m0, s5, 0xe000
	s_nop 0
	global_load_lds_dwordx4 v[152:153], off
	s_waitcnt vmcnt(8)
	s_waitcnt lgkmcnt(0)
	v_mfma_f32_16x16x32_bf16 v[126:129], v[130:133], v[174:177], v[126:129]
	v_mfma_f32_16x16x32_bf16 v[122:125], v[138:141], v[174:177], v[122:125]
	v_mfma_f32_16x16x32_bf16 v[114:117], v[130:133], v[182:185], v[114:117]
	v_mfma_f32_16x16x32_bf16 v[110:113], v[138:141], v[182:185], v[110:113]
	s_barrier
	s_setprio 1
	s_waitcnt lgkmcnt(0)
	v_mfma_f32_16x16x32_bf16 v[98:101], v[130:133], v[190:193], v[98:101]
	v_mfma_f32_16x16x32_bf16 v[92:95], v[138:141], v[190:193], v[92:95]
	v_mfma_f32_16x16x32_bf16 v[80:83], v[130:133], v[206:209], v[80:83]
	v_mfma_f32_16x16x32_bf16 v[76:79], v[138:141], v[206:209], v[76:79]
	v_mfma_f32_16x16x32_bf16 v[126:129], v[134:137], v[178:181], v[126:129]
	v_mfma_f32_16x16x32_bf16 v[122:125], v[142:145], v[178:181], v[122:125]
	v_mfma_f32_16x16x32_bf16 v[114:117], v[134:137], v[186:189], v[114:117]
	v_mfma_f32_16x16x32_bf16 v[110:113], v[142:145], v[186:189], v[110:113]
	v_mfma_f32_16x16x32_bf16 v[98:101], v[134:137], v[202:205], v[98:101]
	v_mfma_f32_16x16x32_bf16 v[92:95], v[142:145], v[202:205], v[92:95]
	v_mfma_f32_16x16x32_bf16 v[80:83], v[134:137], v[214:217], v[80:83]
	v_mfma_f32_16x16x32_bf16 v[76:79], v[142:145], v[214:217], v[76:79]
	s_setprio 0
	s_setprio 1
	v_mfma_f32_16x16x32_bf16 v[118:121], v[158:161], v[174:177], v[118:121]
	v_mfma_f32_16x16x32_bf16 v[106:109], v[166:169], v[174:177], v[106:109]
	v_mfma_f32_16x16x32_bf16 v[102:105], v[158:161], v[182:185], v[102:105]
	v_mfma_f32_16x16x32_bf16 v[88:91], v[166:169], v[182:185], v[88:91]
	v_mfma_f32_16x16x32_bf16 v[84:87], v[158:161], v[190:193], v[84:87]
	v_mfma_f32_16x16x32_bf16 v[72:75], v[166:169], v[190:193], v[72:75]
	v_mfma_f32_16x16x32_bf16 v[68:71], v[158:161], v[206:209], v[68:71]
	v_mfma_f32_16x16x32_bf16 v[64:67], v[166:169], v[206:209], v[64:67]
	v_mfma_f32_16x16x32_bf16 v[118:121], v[162:165], v[178:181], v[118:121]
	v_mfma_f32_16x16x32_bf16 v[106:109], v[170:173], v[178:181], v[106:109]
	v_mfma_f32_16x16x32_bf16 v[102:105], v[162:165], v[186:189], v[102:105]
	v_mfma_f32_16x16x32_bf16 v[88:91], v[170:173], v[186:189], v[88:91]
	v_mfma_f32_16x16x32_bf16 v[84:87], v[162:165], v[202:205], v[84:87]
	v_mfma_f32_16x16x32_bf16 v[72:75], v[170:173], v[202:205], v[72:75]
	v_mfma_f32_16x16x32_bf16 v[68:71], v[162:165], v[214:217], v[68:71]
	v_mfma_f32_16x16x32_bf16 v[64:67], v[170:173], v[214:217], v[64:67]
	s_setprio 0
	s_barrier
	s_add_i32 s22, s45, s4
	v_lshl_add_u64 v[152:153], s[34:35], 0, v[96:97]
	s_mov_b32 m0, s22
	ds_read_b128 v[174:177], v157 offset:16384
	ds_read_b128 v[178:181], v157 offset:17408
	ds_read_b128 v[182:185], v157 offset:18432
	ds_read_b128 v[186:189], v157 offset:19456
	ds_read_b128 v[190:193], v157 offset:20480
	ds_read_b128 v[202:205], v157 offset:21504
	ds_read_b128 v[206:209], v157 offset:22528
	ds_read_b128 v[214:217], v157 offset:23552
	global_load_lds_dwordx4 v[152:153], off
	s_add_i32 m0, s22, 0x2000
	s_add_u32 s22, s34, 0x160000
	v_lshl_add_u64 v[194:195], s[34:35], 0, v[146:147]
	s_addc_u32 s23, s35, 0
	s_add_i32 s45, s46, s4
	global_load_lds_dwordx4 v[194:195], off
	v_lshl_add_u64 v[198:199], s[22:23], 0, v[96:97]
	s_mov_b32 m0, s45
	v_lshl_add_u64 v[200:201], s[38:39], 0, v[146:147]
	global_load_lds_dwordx4 v[198:199], off
	v_lshl_add_u64 v[198:199], s[22:23], 0, v[146:147]
	s_add_i32 m0, s45, 0x2000
	s_nop 0
	global_load_lds_dwordx4 v[198:199], off
	v_lshl_add_u64 v[198:199], s[38:39], 0, v[96:97]
	s_mov_b32 m0, s5
	s_nop 0
	global_load_lds_dwordx4 v[198:199], off
	s_mov_b32 m0, s17
	s_nop 0
	global_load_lds_dwordx4 v[200:201], off
	s_waitcnt vmcnt(8)
	s_waitcnt lgkmcnt(0)
	v_mfma_f32_16x16x32_bf16 v[60:63], v[130:133], v[174:177], v[60:63]
	v_mfma_f32_16x16x32_bf16 v[56:59], v[138:141], v[174:177], v[56:59]
	v_mfma_f32_16x16x32_bf16 v[48:51], v[130:133], v[182:185], v[48:51]
	v_mfma_f32_16x16x32_bf16 v[44:47], v[138:141], v[182:185], v[44:47]
	s_barrier
	s_setprio 1
	s_waitcnt lgkmcnt(0)
	v_mfma_f32_16x16x32_bf16 v[32:35], v[130:133], v[190:193], v[32:35]
	v_mfma_f32_16x16x32_bf16 v[28:31], v[138:141], v[190:193], v[28:31]
	v_mfma_f32_16x16x32_bf16 v[16:19], v[130:133], v[206:209], v[16:19]
	v_mfma_f32_16x16x32_bf16 v[12:15], v[138:141], v[206:209], v[12:15]
	v_mfma_f32_16x16x32_bf16 v[60:63], v[134:137], v[178:181], v[60:63]
	v_mfma_f32_16x16x32_bf16 v[56:59], v[142:145], v[178:181], v[56:59]
	v_mfma_f32_16x16x32_bf16 v[48:51], v[134:137], v[186:189], v[48:51]
	v_mfma_f32_16x16x32_bf16 v[44:47], v[142:145], v[186:189], v[44:47]
	v_mfma_f32_16x16x32_bf16 v[32:35], v[134:137], v[202:205], v[32:35]
	v_mfma_f32_16x16x32_bf16 v[28:31], v[142:145], v[202:205], v[28:31]
	v_mfma_f32_16x16x32_bf16 v[16:19], v[134:137], v[214:217], v[16:19]
	v_mfma_f32_16x16x32_bf16 v[12:15], v[142:145], v[214:217], v[12:15]
	s_setprio 0
	s_setprio 1
	v_mfma_f32_16x16x32_bf16 v[52:55], v[158:161], v[174:177], v[52:55]
	v_mfma_f32_16x16x32_bf16 v[40:43], v[166:169], v[174:177], v[40:43]
	v_mfma_f32_16x16x32_bf16 v[36:39], v[158:161], v[182:185], v[36:39]
	v_mfma_f32_16x16x32_bf16 v[24:27], v[166:169], v[182:185], v[24:27]
	v_mfma_f32_16x16x32_bf16 v[20:23], v[158:161], v[190:193], v[20:23]
	v_mfma_f32_16x16x32_bf16 v[8:11], v[166:169], v[190:193], v[8:11]
	v_mfma_f32_16x16x32_bf16 v[4:7], v[158:161], v[206:209], v[4:7]
	v_mfma_f32_16x16x32_bf16 v[0:3], v[166:169], v[206:209], v[0:3]
	v_mfma_f32_16x16x32_bf16 v[52:55], v[162:165], v[178:181], v[52:55]
	v_mfma_f32_16x16x32_bf16 v[40:43], v[170:173], v[178:181], v[40:43]
	v_mfma_f32_16x16x32_bf16 v[36:39], v[162:165], v[186:189], v[36:39]
	v_mfma_f32_16x16x32_bf16 v[24:27], v[170:173], v[186:189], v[24:27]
	v_mfma_f32_16x16x32_bf16 v[20:23], v[162:165], v[202:205], v[20:23]
	v_mfma_f32_16x16x32_bf16 v[8:11], v[170:173], v[202:205], v[8:11]
	v_mfma_f32_16x16x32_bf16 v[4:7], v[162:165], v[214:217], v[4:7]
	v_mfma_f32_16x16x32_bf16 v[0:3], v[170:173], v[214:217], v[0:3]
	s_setprio 0
	s_barrier
	s_add_i32 s45, 0, 0x18000
	s_add_i32 s46, 0, 0x1c000
	v_add_u32_e32 v142, s45, v155
	v_add_u32_e32 v170, s46, v155
	ds_read_b128 v[130:133], v142
	ds_read_b128 v[134:137], v142 offset:1024
	ds_read_b128 v[138:141], v142 offset:2048
	ds_read_b128 v[142:145], v142 offset:3072
	ds_read_b128 v[158:161], v170
	ds_read_b128 v[162:165], v170 offset:1024
	ds_read_b128 v[166:169], v170 offset:2048
	ds_read_b128 v[170:173], v170 offset:3072
	s_add_u32 s22, s38, 0x160000
	s_addc_u32 s23, s39, 0
	s_mov_b32 m0, s18
	v_lshl_add_u64 v[218:219], s[22:23], 0, v[96:97]
	ds_read_b128 v[174:177], v157 offset:32768
	ds_read_b128 v[178:181], v157 offset:33792
	ds_read_b128 v[182:185], v157 offset:34816
	ds_read_b128 v[186:189], v157 offset:35840
	ds_read_b128 v[190:193], v157 offset:36864
	ds_read_b128 v[202:205], v157 offset:37888
	ds_read_b128 v[206:209], v157 offset:38912
	ds_read_b128 v[214:217], v157 offset:39936
	global_load_lds_dwordx4 v[218:219], off
	v_lshl_add_u64 v[218:219], s[22:23], 0, v[146:147]
	s_mov_b32 m0, s19
	s_nop 0
	global_load_lds_dwordx4 v[218:219], off
	s_waitcnt vmcnt(8)
	s_waitcnt lgkmcnt(0)
	v_mfma_f32_16x16x32_bf16 v[126:129], v[130:133], v[174:177], v[126:129]
	v_mfma_f32_16x16x32_bf16 v[122:125], v[138:141], v[174:177], v[122:125]
	v_mfma_f32_16x16x32_bf16 v[114:117], v[130:133], v[182:185], v[114:117]
	v_mfma_f32_16x16x32_bf16 v[110:113], v[138:141], v[182:185], v[110:113]
	s_barrier
	s_setprio 1
	s_waitcnt lgkmcnt(0)
	v_mfma_f32_16x16x32_bf16 v[98:101], v[130:133], v[190:193], v[98:101]
	v_mfma_f32_16x16x32_bf16 v[92:95], v[138:141], v[190:193], v[92:95]
	v_mfma_f32_16x16x32_bf16 v[80:83], v[130:133], v[206:209], v[80:83]
	v_mfma_f32_16x16x32_bf16 v[76:79], v[138:141], v[206:209], v[76:79]
	v_mfma_f32_16x16x32_bf16 v[126:129], v[134:137], v[178:181], v[126:129]
	v_mfma_f32_16x16x32_bf16 v[122:125], v[142:145], v[178:181], v[122:125]
	v_mfma_f32_16x16x32_bf16 v[114:117], v[134:137], v[186:189], v[114:117]
	v_mfma_f32_16x16x32_bf16 v[110:113], v[142:145], v[186:189], v[110:113]
	v_mfma_f32_16x16x32_bf16 v[98:101], v[134:137], v[202:205], v[98:101]
	v_mfma_f32_16x16x32_bf16 v[92:95], v[142:145], v[202:205], v[92:95]
	v_mfma_f32_16x16x32_bf16 v[80:83], v[134:137], v[214:217], v[80:83]
	v_mfma_f32_16x16x32_bf16 v[76:79], v[142:145], v[214:217], v[76:79]
	s_setprio 0
	s_setprio 1
	v_mfma_f32_16x16x32_bf16 v[118:121], v[158:161], v[174:177], v[118:121]
	v_mfma_f32_16x16x32_bf16 v[106:109], v[166:169], v[174:177], v[106:109]
	v_mfma_f32_16x16x32_bf16 v[102:105], v[158:161], v[182:185], v[102:105]
	v_mfma_f32_16x16x32_bf16 v[88:91], v[166:169], v[182:185], v[88:91]
	v_mfma_f32_16x16x32_bf16 v[84:87], v[158:161], v[190:193], v[84:87]
	v_mfma_f32_16x16x32_bf16 v[72:75], v[166:169], v[190:193], v[72:75]
	v_mfma_f32_16x16x32_bf16 v[68:71], v[158:161], v[206:209], v[68:71]
	v_mfma_f32_16x16x32_bf16 v[64:67], v[166:169], v[206:209], v[64:67]
	v_mfma_f32_16x16x32_bf16 v[118:121], v[162:165], v[178:181], v[118:121]
	v_mfma_f32_16x16x32_bf16 v[106:109], v[170:173], v[178:181], v[106:109]
	v_mfma_f32_16x16x32_bf16 v[102:105], v[162:165], v[186:189], v[102:105]
	v_mfma_f32_16x16x32_bf16 v[88:91], v[170:173], v[186:189], v[88:91]
	v_mfma_f32_16x16x32_bf16 v[84:87], v[162:165], v[202:205], v[84:87]
	v_mfma_f32_16x16x32_bf16 v[72:75], v[170:173], v[202:205], v[72:75]
	v_mfma_f32_16x16x32_bf16 v[68:71], v[162:165], v[214:217], v[68:71]
	v_mfma_f32_16x16x32_bf16 v[64:67], v[170:173], v[214:217], v[64:67]
	s_setprio 0
	s_barrier
	s_add_i32 s22, s45, s4
	v_lshl_add_u64 v[152:153], v[152:153], 0, s[30:31]
	s_mov_b32 m0, s22
	ds_read_b128 v[174:177], v157 offset:49152
	ds_read_b128 v[178:181], v157 offset:50176
	ds_read_b128 v[182:185], v157 offset:51200
	ds_read_b128 v[186:189], v157 offset:52224
	ds_read_b128 v[190:193], v157 offset:53248
	ds_read_b128 v[202:205], v157 offset:54272
	ds_read_b128 v[206:209], v157 offset:55296
	ds_read_b128 v[214:217], v157 offset:56320
	global_load_lds_dwordx4 v[152:153], off
	s_add_i32 m0, s22, 0x2000
	s_add_u32 s22, s34, 0x160080
	v_lshl_add_u64 v[152:153], v[194:195], 0, s[30:31]
	s_addc_u32 s23, s35, 0
	s_add_i32 s34, s46, s4
	global_load_lds_dwordx4 v[152:153], off
	v_lshl_add_u64 v[152:153], s[22:23], 0, v[96:97]
	s_mov_b32 m0, s34
	s_nop 0
	global_load_lds_dwordx4 v[152:153], off
	v_lshl_add_u64 v[152:153], s[22:23], 0, v[146:147]
	s_add_i32 m0, s34, 0x2000
	s_nop 0
	global_load_lds_dwordx4 v[152:153], off
	v_lshl_add_u64 v[152:153], v[198:199], 0, s[30:31]
	s_mov_b32 m0, s20
	s_nop 0
	global_load_lds_dwordx4 v[152:153], off
	v_lshl_add_u64 v[152:153], v[200:201], 0, s[30:31]
	s_mov_b32 m0, s36
	s_nop 0
	global_load_lds_dwordx4 v[152:153], off
	s_waitcnt vmcnt(8)
	s_waitcnt lgkmcnt(0)
	v_mfma_f32_16x16x32_bf16 v[60:63], v[130:133], v[174:177], v[60:63]
	v_mfma_f32_16x16x32_bf16 v[56:59], v[138:141], v[174:177], v[56:59]
	v_mfma_f32_16x16x32_bf16 v[48:51], v[130:133], v[182:185], v[48:51]
	v_mfma_f32_16x16x32_bf16 v[44:47], v[138:141], v[182:185], v[44:47]
	s_barrier
	s_setprio 1
	s_waitcnt lgkmcnt(0)
	v_mfma_f32_16x16x32_bf16 v[32:35], v[130:133], v[190:193], v[32:35]
	v_mfma_f32_16x16x32_bf16 v[28:31], v[138:141], v[190:193], v[28:31]
	v_mfma_f32_16x16x32_bf16 v[16:19], v[130:133], v[206:209], v[16:19]
	v_mfma_f32_16x16x32_bf16 v[12:15], v[138:141], v[206:209], v[12:15]
	v_mfma_f32_16x16x32_bf16 v[60:63], v[134:137], v[178:181], v[60:63]
	v_mfma_f32_16x16x32_bf16 v[56:59], v[142:145], v[178:181], v[56:59]
	v_mfma_f32_16x16x32_bf16 v[48:51], v[134:137], v[186:189], v[48:51]
	v_mfma_f32_16x16x32_bf16 v[44:47], v[142:145], v[186:189], v[44:47]
	v_mfma_f32_16x16x32_bf16 v[32:35], v[134:137], v[202:205], v[32:35]
	v_mfma_f32_16x16x32_bf16 v[28:31], v[142:145], v[202:205], v[28:31]
	v_mfma_f32_16x16x32_bf16 v[16:19], v[134:137], v[214:217], v[16:19]
	v_mfma_f32_16x16x32_bf16 v[12:15], v[142:145], v[214:217], v[12:15]
	s_setprio 0
	s_setprio 1
	v_mfma_f32_16x16x32_bf16 v[52:55], v[158:161], v[174:177], v[52:55]
	v_mfma_f32_16x16x32_bf16 v[40:43], v[166:169], v[174:177], v[40:43]
	v_mfma_f32_16x16x32_bf16 v[36:39], v[158:161], v[182:185], v[36:39]
	v_mfma_f32_16x16x32_bf16 v[24:27], v[166:169], v[182:185], v[24:27]
	v_mfma_f32_16x16x32_bf16 v[20:23], v[158:161], v[190:193], v[20:23]
	v_mfma_f32_16x16x32_bf16 v[8:11], v[166:169], v[190:193], v[8:11]
	v_mfma_f32_16x16x32_bf16 v[4:7], v[158:161], v[206:209], v[4:7]
	v_mfma_f32_16x16x32_bf16 v[0:3], v[166:169], v[206:209], v[0:3]
	v_mfma_f32_16x16x32_bf16 v[52:55], v[162:165], v[178:181], v[52:55]
	v_mfma_f32_16x16x32_bf16 v[40:43], v[170:173], v[178:181], v[40:43]
	v_mfma_f32_16x16x32_bf16 v[36:39], v[162:165], v[186:189], v[36:39]
	v_mfma_f32_16x16x32_bf16 v[24:27], v[170:173], v[186:189], v[24:27]
	v_mfma_f32_16x16x32_bf16 v[20:23], v[162:165], v[202:205], v[20:23]
	v_mfma_f32_16x16x32_bf16 v[8:11], v[170:173], v[202:205], v[8:11]
	v_mfma_f32_16x16x32_bf16 v[4:7], v[162:165], v[214:217], v[4:7]
	v_mfma_f32_16x16x32_bf16 v[0:3], v[170:173], v[214:217], v[0:3]
	s_setprio 0
	s_barrier
	s_add_i32 s6, s6, 2
	s_add_u32 s2, s2, 0x100
	s_addc_u32 s3, s3, 0
	s_cmpk_gt_u32 s6, 0x55
	s_mov_b64 s[22:23], s[24:25]
	s_cbranch_scc0 .LBB0_1413
	s_and_b64 vcc, exec, s[10:11]
	s_cbranch_vccz .LBB0_1416
	s_barrier
